# SSD output unit v2: B rows, states, x and z staged cooperatively in LDS per head group (76 instead of 300 vector-memory instructions per wave), outputs transposed through LDS into 16-byte stores; atte
# speedup vs baseline: 1.0576x; 1.0576x over previous
.LBB0_118:
	v_readfirstlane_b32 s56, v203
	v_readlane_b32 s40, v251, 43
	v_readlane_b32 s41, v251, 44
	v_readlane_b32 s42, v251, 49
	v_readlane_b32 s43, v251, 50
	v_readlane_b32 s46, v251, 59
	v_readlane_b32 s47, v251, 60
	v_readlane_b32 s54, v251, 45
	v_readlane_b32 s55, v251, 46
	v_readlane_b32 s58, v251, 47
	v_readlane_b32 s59, v251, 48
	v_readlane_b32 s48, v254, 44
	v_readlane_b32 s49, v254, 45
	v_readlane_b32 s50, v254, 46
	v_readlane_b32 s51, v254, 47
	s_lshr_b32 s56, s56, 6
	s_mul_i32 s0, s24, 0x600
	s_add_u32 s40, s40, s0
	s_addc_u32 s41, s41, 0
	s_mul_i32 s0, s2, 34
	s_add_i32 s0, s0, s3
	s_lshl_b32 s0, s0, 17
	s_add_u32 s42, s42, s0
	s_addc_u32 s43, s43, 0
	s_mul_i32 s0, s24, 0x1c00
	s_add_u32 s44, s70, s0
	s_addc_u32 s45, s71, 0
	s_add_u32 s44, s44, 0x1a00
	s_addc_u32 s45, s45, 0
	s_lshl_b32 s0, s24, 11
	s_add_u32 s46, s46, s0
	s_addc_u32 s47, s47, 0
	s_add_u32 s46, s46, 0x600
	s_addc_u32 s47, s47, 0
	s_lshl_b32 s0, s24, 5
	s_add_u32 s54, s54, s0
	s_addc_u32 s55, s55, 0
	s_add_u32 s58, s58, s0
	s_addc_u32 s59, s59, 0
	s_load_dword s60, s[48:49], 0x0
	s_load_dword s61, s[48:49], 0x4
	s_load_dword s62, s[48:49], 0x8
	s_load_dword s63, s[48:49], 0xc
	s_mov_b32 s25, 0x3b800000
	v_lshrrev_b32_e32 v6, 4, v203
	v_and_b32_e32 v7, 15, v203
	v_lshlrev_b32_e32 v7, 4, v7
	v_mul_u32_u24_e32 v0, 0x600, v6
	v_add_u32_e32 v0, v0, v7
	v_mul_u32_u24_e32 v1, 0x1c00, v6
	v_add_u32_e32 v1, v1, v7
	v_lshl_add_u32 v2, v6, 8, v7
	v_mul_u32_u24_e32 v3, 288, v6
	v_add_u32_e32 v3, v3, v7
	v_mul_u32_u24_e32 v4, 272, v6
	v_add_u32_e32 v4, v4, v7
	v_add_u32_e32 v5, 0x1c800, v4
	v_add_u32_e32 v4, 0x12000, v4
	v_lshlrev_b32_e32 v8, 2, v203
	v_and_b32_e32 v10, 7, v203
	v_lshlrev_b32_e32 v10, 9, v10
	v_lshrrev_b32_e32 v11, 3, v203
	v_lshl_add_u32 v10, v11, 2, v10
	v_add_u32_e32 v10, 0x1a800, v10
	global_load_dword v128, v8, s[54:55]
	global_load_dword v129, v8, s[54:55] offset:2048
	global_load_dword v130, v8, s[58:59]
	global_load_dword v131, v8, s[58:59] offset:2048
	s_mov_b32 s52, s40
	s_mov_b32 s53, s41
	global_load_dwordx4 v[64:67], v0, s[52:53] offset:0
	global_load_dwordx4 v[96:99], v0, s[52:53] offset:512
	s_add_u32 s52, s40, 0xc000
	s_addc_u32 s53, s41, 0
	global_load_dwordx4 v[68:71], v0, s[52:53] offset:0
	global_load_dwordx4 v[100:103], v0, s[52:53] offset:512
	s_add_u32 s52, s40, 0x18000
	s_addc_u32 s53, s41, 0
	global_load_dwordx4 v[72:75], v0, s[52:53] offset:0
	global_load_dwordx4 v[104:107], v0, s[52:53] offset:512
	s_add_u32 s52, s40, 0x24000
	s_addc_u32 s53, s41, 0
	global_load_dwordx4 v[76:79], v0, s[52:53] offset:0
	global_load_dwordx4 v[108:111], v0, s[52:53] offset:512
	s_mov_b32 s52, s44
	s_mov_b32 s53, s45
	global_load_dwordx4 v[80:83], v1, s[52:53] offset:0
	s_add_u32 s52, s44, 0x38000
	s_addc_u32 s53, s45, 0
	global_load_dwordx4 v[84:87], v1, s[52:53] offset:0
	s_add_u32 s52, s44, 0x70000
	s_addc_u32 s53, s45, 0
	global_load_dwordx4 v[88:91], v1, s[52:53] offset:0
	s_add_u32 s52, s44, 0xa8000
	s_addc_u32 s53, s45, 0
	global_load_dwordx4 v[92:95], v1, s[52:53] offset:0
	s_mov_b32 s52, s42
	s_mov_b32 s53, s43
	global_load_dwordx4 v[112:115], v2, s[52:53]
	s_add_u32 s52, s42, 0x2000
	s_addc_u32 s53, s43, 0
	global_load_dwordx4 v[116:119], v2, s[52:53]
	s_add_u32 s52, s42, 0x4000
	s_addc_u32 s53, s43, 0
	global_load_dwordx4 v[120:123], v2, s[52:53]
	s_add_u32 s52, s42, 0x6000
	s_addc_u32 s53, s43, 0
	global_load_dwordx4 v[124:127], v2, s[52:53]
	v_and_b32_e32 v11, 15, v220
	v_lshrrev_b32_e32 v12, 4, v220
	v_lshlrev_b32_e32 v165, 4, v12
	v_lshrrev_b32_e32 v13, 2, v11
	v_lshl_add_u32 v13, v12, 2, v13
	v_mul_u32_u24_e32 v166, 288, v13
	v_and_b32_e32 v14, 3, v11
	v_lshl_add_u32 v166, v14, 3, v166
	s_lshl_b32 s0, s56, 4
	v_add_u32_e32 v15, s0, v11
	v_lshlrev_b32_e32 v167, 2, v15
	v_add_u32_e32 v167, 0x1a800, v167
	v_add_u32_e32 v168, 0x1a800, v165
	v_mul_u32_u24_e32 v169, 272, v11
	v_add_u32_e32 v169, v169, v165
	v_add_u32_e32 v170, 0x1c800, v169
	v_add_u32_e32 v169, 0x12000, v169
	s_mul_i32 s1, s56, 4608
	v_add_u32_e32 v174, s1, v166
	v_add_u32_e32 v227, 0x9000, v174
	v_lshlrev_b32_e32 v13, 2, v12
	v_sub_u32_e32 v175, v15, v13
	v_mul_u32_u24_e32 v177, 0x600, v15
	v_add_u32_e32 v177, v177, v165
	v_add_u32_e32 v177, 0x400, v177
	v_add_u32_e32 v13, s0, v13
	v_mul_u32_u24_e32 v171, 288, v13
	v_lshl_add_u32 v171, v11, 1, v171
	v_add_u32_e32 v171, 0x9000, v171
	v_add_u32_e32 v13, s0, v12
	v_mul_u32_u24_e32 v172, 288, v13
	v_lshl_add_u32 v172, v11, 4, v172
	v_add_u32_e32 v172, 0x9000, v172
	v_lshlrev_b32_e32 v173, 11, v13
	v_lshl_add_u32 v173, v11, 4, v173
	v_lshlrev_b32_e32 v234, 2, v11
	v_mov_b32_e32 v228, 0
	v_mov_b32_e32 v229, 0
	v_mov_b32_e32 v230, 0
	v_mov_b32_e32 v231, 0
	global_load_dwordx4 v[48:51], v177, s[40:41] offset:0
	global_load_dwordx4 v[52:55], v177, s[40:41] offset:64
	global_load_dwordx4 v[56:59], v177, s[40:41] offset:128
	global_load_dwordx4 v[60:63], v177, s[40:41] offset:192
	s_waitcnt vmcnt(4)
	ds_write_b32 v10, v128
	ds_write_b32 v10, v129 offset:256
	ds_write_b32 v10, v130 offset:4096
	ds_write_b32 v10, v131 offset:4352
	ds_write_b128 v3, v[64:67]
	ds_write_b128 v3, v[68:71] offset:9216
	ds_write_b128 v3, v[72:75] offset:18432
	ds_write_b128 v3, v[76:79] offset:27648
	ds_write_b128 v3, v[80:83] offset:36864
	ds_write_b128 v3, v[84:87] offset:46080
	ds_write_b128 v3, v[88:91] offset:55296
	ds_write_b128 v3, v[92:95] offset:64512
	ds_write_b128 v4, v[96:99]
	ds_write_b128 v4, v[100:103] offset:8704
	ds_write_b128 v4, v[104:107] offset:17408
	ds_write_b128 v4, v[108:111] offset:26112
	ds_write_b128 v5, v[112:115]
	ds_write_b128 v5, v[116:119] offset:8704
	ds_write_b128 v5, v[120:123] offset:17408
	ds_write_b128 v5, v[124:127] offset:26112
	s_waitcnt lgkmcnt(0)
	s_barrier
	s_add_u32 s52, s42, 0x8000
	s_addc_u32 s53, s43, 0
	global_load_dwordx4 v[124:127], v2, s[52:53]
	s_add_u32 s52, s42, 0xa000
	s_addc_u32 s53, s43, 0
	global_load_dwordx4 v[128:131], v2, s[52:53]
	s_add_u32 s52, s42, 0xc000
	s_addc_u32 s53, s43, 0
	global_load_dwordx4 v[132:135], v2, s[52:53]
	s_add_u32 s52, s42, 0xe000
	s_addc_u32 s53, s43, 0
	global_load_dwordx4 v[136:139], v2, s[52:53]
	ds_read_b32 v156, v167 offset:4096
	ds_read_b32 v157, v167 offset:6144
	ds_read_b32 v158, v167 offset:4608
	ds_read_b32 v159, v167 offset:6656
	ds_read_b128 v[64:67], v169 offset:0
	ds_read_b128 v[68:71], v169 offset:64
	ds_read_b128 v[72:75], v169 offset:128
	ds_read_b128 v[76:79], v169 offset:192
	ds_read_b128 v[80:83], v169 offset:4352
	ds_read_b128 v[84:87], v169 offset:4416
	ds_read_b128 v[88:91], v169 offset:4480
	ds_read_b128 v[92:95], v169 offset:4544
	s_waitcnt vmcnt(4)
	s_waitcnt lgkmcnt(0)
	v_mfma_f32_16x16x32_bf16 v[96:99], v[64:67], v[48:51], 0
	v_mfma_f32_16x16x32_bf16 v[96:99], v[68:71], v[52:55], v[96:99]
	v_mfma_f32_16x16x32_bf16 v[96:99], v[72:75], v[56:59], v[96:99]
	v_mfma_f32_16x16x32_bf16 v[96:99], v[76:79], v[60:63], v[96:99]
	v_mfma_f32_16x16x32_bf16 v[100:103], v[80:83], v[48:51], 0
	v_mfma_f32_16x16x32_bf16 v[100:103], v[84:87], v[52:55], v[100:103]
	v_mfma_f32_16x16x32_bf16 v[100:103], v[88:91], v[56:59], v[100:103]
	v_mfma_f32_16x16x32_bf16 v[100:103], v[92:95], v[60:63], v[100:103]
	ds_read_b128 v[64:67], v168 offset:0
	ds_read_b128 v[68:71], v168 offset:2048
	ds_read_b128 v[72:75], v168 offset:4096
	ds_read_b128 v[76:79], v168 offset:6144
	ds_read_b128 v[80:83], v168 offset:64
	ds_read_b128 v[84:87], v168 offset:2112
	ds_read_b128 v[88:91], v168 offset:4160
	ds_read_b128 v[92:95], v168 offset:6208
	ds_read_b64_tr_b16 v[108:109], v166 offset:0
	ds_read_b64_tr_b16 v[110:111], v166 offset:4608
	ds_read_b64_tr_b16 v[112:113], v166 offset:32
	ds_read_b64_tr_b16 v[114:115], v166 offset:4640
	s_waitcnt lgkmcnt(4)
	v_subrev_u32_e32 v236, 0, v175
	v_cmp_gt_i32_e64 s[78:79], v236, 0
	v_cmp_gt_i32_e64 s[80:81], v236, 1
	v_cmp_gt_i32_e64 s[82:83], v236, 2
	v_cmp_gt_i32_e64 s[84:85], v236, 3
	v_cmp_eq_u32_e64 s[86:87], v236, 0
	v_cmp_eq_u32_e64 s[88:89], v236, 1
	v_cmp_eq_u32_e64 s[90:91], v236, 2
	v_cmp_eq_u32_e64 s[92:93], v236, 3
	v_cndmask_b32_e64 v237, v76, v72, s[78:79]
	v_cndmask_b32_e64 v238, v157, v156, s[78:79]
	v_sub_f32_e32 v237, v238, v237
	v_min_f32_e32 v237, 0, v237
	v_mul_f32_e32 v237, 0x3fb8aa3b, v237
	v_exp_f32_e32 v237, v237
	v_cndmask_b32_e64 v239, v68, v64, s[78:79]
	v_add_f32_e32 v240, v64, v68
	v_mul_f32_e32 v237, v239, v237
	v_cndmask_b32_e64 v237, v237, v240, s[86:87]
	v_mul_f32_e32 v241, v96, v237
	v_cndmask_b32_e64 v237, v77, v73, s[80:81]
	v_cndmask_b32_e64 v238, v157, v156, s[80:81]
	v_sub_f32_e32 v237, v238, v237
	v_min_f32_e32 v237, 0, v237
	v_mul_f32_e32 v237, 0x3fb8aa3b, v237
	v_exp_f32_e32 v237, v237
	v_cndmask_b32_e64 v239, v69, v65, s[80:81]
	v_add_f32_e32 v240, v65, v69
	v_mul_f32_e32 v237, v239, v237
	v_cndmask_b32_e64 v237, v237, v240, s[88:89]
	v_mul_f32_e32 v242, v97, v237
	v_cndmask_b32_e64 v237, v78, v74, s[82:83]
	v_cndmask_b32_e64 v238, v157, v156, s[82:83]
	v_sub_f32_e32 v237, v238, v237
	v_min_f32_e32 v237, 0, v237
	v_mul_f32_e32 v237, 0x3fb8aa3b, v237
	v_exp_f32_e32 v237, v237
	v_cndmask_b32_e64 v239, v70, v66, s[82:83]
	v_add_f32_e32 v240, v66, v70
	v_mul_f32_e32 v237, v239, v237
	v_cndmask_b32_e64 v237, v237, v240, s[90:91]
	v_mul_f32_e32 v243, v98, v237
	v_cndmask_b32_e64 v237, v79, v75, s[84:85]
	v_cndmask_b32_e64 v238, v157, v156, s[84:85]
	v_sub_f32_e32 v237, v238, v237
	v_min_f32_e32 v237, 0, v237
	v_mul_f32_e32 v237, 0x3fb8aa3b, v237
	v_exp_f32_e32 v237, v237
	v_cndmask_b32_e64 v239, v71, v67, s[84:85]
	v_add_f32_e32 v240, v67, v71
	v_mul_f32_e32 v237, v239, v237
	v_cndmask_b32_e64 v237, v237, v240, s[92:93]
	v_mul_f32_e32 v244, v99, v237
	ds_read_b64_tr_b16 v[116:117], v166 offset:64
	ds_read_b64_tr_b16 v[118:119], v166 offset:4672
	ds_read_b64_tr_b16 v[120:121], v166 offset:96
	ds_read_b64_tr_b16 v[122:123], v166 offset:4704
	v_subrev_u32_e32 v236, 16, v175
	v_cmp_gt_i32_e64 s[78:79], v236, 0
	v_cmp_gt_i32_e64 s[80:81], v236, 1
	v_cmp_gt_i32_e64 s[82:83], v236, 2
	v_cmp_gt_i32_e64 s[84:85], v236, 3
	v_cmp_eq_u32_e64 s[86:87], v236, 0
	v_cmp_eq_u32_e64 s[88:89], v236, 1
	v_cmp_eq_u32_e64 s[90:91], v236, 2
	v_cmp_eq_u32_e64 s[92:93], v236, 3
	v_cndmask_b32_e64 v237, v92, v88, s[78:79]
	v_cndmask_b32_e64 v238, v157, v156, s[78:79]
	v_sub_f32_e32 v237, v238, v237
	v_min_f32_e32 v237, 0, v237
	v_mul_f32_e32 v237, 0x3fb8aa3b, v237
	v_exp_f32_e32 v237, v237
	v_cndmask_b32_e64 v239, v84, v80, s[78:79]
	v_add_f32_e32 v240, v80, v84
	v_mul_f32_e32 v237, v239, v237
	v_cndmask_b32_e64 v237, v237, v240, s[86:87]
	v_mul_f32_e32 v245, v100, v237
	v_cndmask_b32_e64 v237, v93, v89, s[80:81]
	v_cndmask_b32_e64 v238, v157, v156, s[80:81]
	v_sub_f32_e32 v237, v238, v237
	v_min_f32_e32 v237, 0, v237
	v_mul_f32_e32 v237, 0x3fb8aa3b, v237
	v_exp_f32_e32 v237, v237
	v_cndmask_b32_e64 v239, v85, v81, s[80:81]
	v_add_f32_e32 v240, v81, v85
	v_mul_f32_e32 v237, v239, v237
	v_cndmask_b32_e64 v237, v237, v240, s[88:89]
	v_mul_f32_e32 v246, v101, v237
	v_cndmask_b32_e64 v237, v94, v90, s[82:83]
	v_cndmask_b32_e64 v238, v157, v156, s[82:83]
	v_sub_f32_e32 v237, v238, v237
	v_min_f32_e32 v237, 0, v237
	v_mul_f32_e32 v237, 0x3fb8aa3b, v237
	v_exp_f32_e32 v237, v237
	v_cndmask_b32_e64 v239, v86, v82, s[82:83]
	v_add_f32_e32 v240, v82, v86
	v_mul_f32_e32 v237, v239, v237
	v_cndmask_b32_e64 v237, v237, v240, s[90:91]
	v_mul_f32_e32 v247, v102, v237
	v_cndmask_b32_e64 v237, v95, v91, s[84:85]
	v_cndmask_b32_e64 v238, v157, v156, s[84:85]
	v_sub_f32_e32 v237, v238, v237
	v_min_f32_e32 v237, 0, v237
	v_mul_f32_e32 v237, 0x3fb8aa3b, v237
	v_exp_f32_e32 v237, v237
	v_cndmask_b32_e64 v239, v87, v83, s[84:85]
	v_add_f32_e32 v240, v83, v87
	v_mul_f32_e32 v237, v239, v237
	v_cndmask_b32_e64 v237, v237, v240, s[92:93]
	v_mul_f32_e32 v248, v103, v237
	v_cvt_pk_bf16_f32 v104, v241, v242
	v_cvt_pk_bf16_f32 v105, v243, v244
	v_cvt_pk_bf16_f32 v106, v245, v246
	v_cvt_pk_bf16_f32 v107, v247, v248
	s_waitcnt lgkmcnt(0)
	s_nop 1
	v_mfma_f32_16x16x32_bf16 v[16:19], v[104:107], v[108:111], 0
	v_mfma_f32_16x16x32_bf16 v[20:23], v[104:107], v[112:115], 0
	v_mfma_f32_16x16x32_bf16 v[24:27], v[104:107], v[116:119], 0
	v_mfma_f32_16x16x32_bf16 v[28:31], v[104:107], v[120:123], 0
	ds_read_b128 v[64:67], v168 offset:512
	ds_read_b128 v[68:71], v168 offset:2560
	ds_read_b128 v[72:75], v168 offset:4608
	ds_read_b128 v[76:79], v168 offset:6656
	ds_read_b128 v[80:83], v168 offset:576
	ds_read_b128 v[84:87], v168 offset:2624
	ds_read_b128 v[88:91], v168 offset:4672
	ds_read_b128 v[92:95], v168 offset:6720
	ds_read_b64_tr_b16 v[108:109], v166 offset:128
	ds_read_b64_tr_b16 v[110:111], v166 offset:4736
	ds_read_b64_tr_b16 v[112:113], v166 offset:160
	ds_read_b64_tr_b16 v[114:115], v166 offset:4768
	s_waitcnt lgkmcnt(4)
	v_subrev_u32_e32 v236, 0, v175
	v_cmp_gt_i32_e64 s[78:79], v236, 0
	v_cmp_gt_i32_e64 s[80:81], v236, 1
	v_cmp_gt_i32_e64 s[82:83], v236, 2
	v_cmp_gt_i32_e64 s[84:85], v236, 3
	v_cmp_eq_u32_e64 s[86:87], v236, 0
	v_cmp_eq_u32_e64 s[88:89], v236, 1
	v_cmp_eq_u32_e64 s[90:91], v236, 2
	v_cmp_eq_u32_e64 s[92:93], v236, 3
	v_cndmask_b32_e64 v237, v76, v72, s[78:79]
	v_cndmask_b32_e64 v238, v159, v158, s[78:79]
	v_sub_f32_e32 v237, v238, v237
	v_min_f32_e32 v237, 0, v237
	v_mul_f32_e32 v237, 0x3fb8aa3b, v237
	v_exp_f32_e32 v237, v237
	v_cndmask_b32_e64 v239, v68, v64, s[78:79]
	v_add_f32_e32 v240, v64, v68
	v_mul_f32_e32 v237, v239, v237
	v_cndmask_b32_e64 v237, v237, v240, s[86:87]
	v_mul_f32_e32 v241, v96, v237
	v_cndmask_b32_e64 v237, v77, v73, s[80:81]
	v_cndmask_b32_e64 v238, v159, v158, s[80:81]
	v_sub_f32_e32 v237, v238, v237
	v_min_f32_e32 v237, 0, v237
	v_mul_f32_e32 v237, 0x3fb8aa3b, v237
	v_exp_f32_e32 v237, v237
	v_cndmask_b32_e64 v239, v69, v65, s[80:81]
	v_add_f32_e32 v240, v65, v69
	v_mul_f32_e32 v237, v239, v237
	v_cndmask_b32_e64 v237, v237, v240, s[88:89]
	v_mul_f32_e32 v242, v97, v237
	v_cndmask_b32_e64 v237, v78, v74, s[82:83]
	v_cndmask_b32_e64 v238, v159, v158, s[82:83]
	v_sub_f32_e32 v237, v238, v237
	v_min_f32_e32 v237, 0, v237
	v_mul_f32_e32 v237, 0x3fb8aa3b, v237
	v_exp_f32_e32 v237, v237
	v_cndmask_b32_e64 v239, v70, v66, s[82:83]
	v_add_f32_e32 v240, v66, v70
	v_mul_f32_e32 v237, v239, v237
	v_cndmask_b32_e64 v237, v237, v240, s[90:91]
	v_mul_f32_e32 v243, v98, v237
	v_cndmask_b32_e64 v237, v79, v75, s[84:85]
	v_cndmask_b32_e64 v238, v159, v158, s[84:85]
	v_sub_f32_e32 v237, v238, v237
	v_min_f32_e32 v237, 0, v237
	v_mul_f32_e32 v237, 0x3fb8aa3b, v237
	v_exp_f32_e32 v237, v237
	v_cndmask_b32_e64 v239, v71, v67, s[84:85]
	v_add_f32_e32 v240, v67, v71
	v_mul_f32_e32 v237, v239, v237
	v_cndmask_b32_e64 v237, v237, v240, s[92:93]
	v_mul_f32_e32 v244, v99, v237
	ds_read_b64_tr_b16 v[116:117], v166 offset:192
	ds_read_b64_tr_b16 v[118:119], v166 offset:4800
	ds_read_b64_tr_b16 v[120:121], v166 offset:224
	ds_read_b64_tr_b16 v[122:123], v166 offset:4832
	v_subrev_u32_e32 v236, 16, v175
	v_cmp_gt_i32_e64 s[78:79], v236, 0
	v_cmp_gt_i32_e64 s[80:81], v236, 1
	v_cmp_gt_i32_e64 s[82:83], v236, 2
	v_cmp_gt_i32_e64 s[84:85], v236, 3
	v_cmp_eq_u32_e64 s[86:87], v236, 0
	v_cmp_eq_u32_e64 s[88:89], v236, 1
	v_cmp_eq_u32_e64 s[90:91], v236, 2
	v_cmp_eq_u32_e64 s[92:93], v236, 3
	v_cndmask_b32_e64 v237, v92, v88, s[78:79]
	v_cndmask_b32_e64 v238, v159, v158, s[78:79]
	v_sub_f32_e32 v237, v238, v237
	v_min_f32_e32 v237, 0, v237
	v_mul_f32_e32 v237, 0x3fb8aa3b, v237
	v_exp_f32_e32 v237, v237
	v_cndmask_b32_e64 v239, v84, v80, s[78:79]
	v_add_f32_e32 v240, v80, v84
	v_mul_f32_e32 v237, v239, v237
	v_cndmask_b32_e64 v237, v237, v240, s[86:87]
	v_mul_f32_e32 v245, v100, v237
	v_cndmask_b32_e64 v237, v93, v89, s[80:81]
	v_cndmask_b32_e64 v238, v159, v158, s[80:81]
	v_sub_f32_e32 v237, v238, v237
	v_min_f32_e32 v237, 0, v237
	v_mul_f32_e32 v237, 0x3fb8aa3b, v237
	v_exp_f32_e32 v237, v237
	v_cndmask_b32_e64 v239, v85, v81, s[80:81]
	v_add_f32_e32 v240, v81, v85
	v_mul_f32_e32 v237, v239, v237
	v_cndmask_b32_e64 v237, v237, v240, s[88:89]
	v_mul_f32_e32 v246, v101, v237
	v_cndmask_b32_e64 v237, v94, v90, s[82:83]
	v_cndmask_b32_e64 v238, v159, v158, s[82:83]
	v_sub_f32_e32 v237, v238, v237
	v_min_f32_e32 v237, 0, v237
	v_mul_f32_e32 v237, 0x3fb8aa3b, v237
	v_exp_f32_e32 v237, v237
	v_cndmask_b32_e64 v239, v86, v82, s[82:83]
	v_add_f32_e32 v240, v82, v86
	v_mul_f32_e32 v237, v239, v237
	v_cndmask_b32_e64 v237, v237, v240, s[90:91]
	v_mul_f32_e32 v247, v102, v237
	v_cndmask_b32_e64 v237, v95, v91, s[84:85]
	v_cndmask_b32_e64 v238, v159, v158, s[84:85]
	v_sub_f32_e32 v237, v238, v237
	v_min_f32_e32 v237, 0, v237
	v_mul_f32_e32 v237, 0x3fb8aa3b, v237
	v_exp_f32_e32 v237, v237
	v_cndmask_b32_e64 v239, v87, v83, s[84:85]
	v_add_f32_e32 v240, v83, v87
	v_mul_f32_e32 v237, v239, v237
	v_cndmask_b32_e64 v237, v237, v240, s[92:93]
	v_mul_f32_e32 v248, v103, v237
	v_cvt_pk_bf16_f32 v104, v241, v242
	v_cvt_pk_bf16_f32 v105, v243, v244
	v_cvt_pk_bf16_f32 v106, v245, v246
	v_cvt_pk_bf16_f32 v107, v247, v248
	s_waitcnt lgkmcnt(0)
	s_nop 1
	v_mfma_f32_16x16x32_bf16 v[32:35], v[104:107], v[108:111], 0
	v_mfma_f32_16x16x32_bf16 v[36:39], v[104:107], v[112:115], 0
	v_mfma_f32_16x16x32_bf16 v[40:43], v[104:107], v[116:119], 0
	v_mfma_f32_16x16x32_bf16 v[44:47], v[104:107], v[120:123], 0
	ds_read_b128 v[64:67], v169 offset:8704
	ds_read_b128 v[68:71], v169 offset:8768
	ds_read_b128 v[72:75], v169 offset:8832
	ds_read_b128 v[76:79], v169 offset:8896
	ds_read_b128 v[80:83], v169 offset:13056
	ds_read_b128 v[84:87], v169 offset:13120
	ds_read_b128 v[88:91], v169 offset:13184
	ds_read_b128 v[92:95], v169 offset:13248
	s_waitcnt lgkmcnt(0)
	v_mfma_f32_16x16x32_bf16 v[96:99], v[64:67], v[48:51], 0
	v_mfma_f32_16x16x32_bf16 v[96:99], v[68:71], v[52:55], v[96:99]
	v_mfma_f32_16x16x32_bf16 v[96:99], v[72:75], v[56:59], v[96:99]
	v_mfma_f32_16x16x32_bf16 v[96:99], v[76:79], v[60:63], v[96:99]
	v_mfma_f32_16x16x32_bf16 v[100:103], v[80:83], v[48:51], 0
	v_mfma_f32_16x16x32_bf16 v[100:103], v[84:87], v[52:55], v[100:103]
	v_mfma_f32_16x16x32_bf16 v[100:103], v[88:91], v[56:59], v[100:103]
	v_mfma_f32_16x16x32_bf16 v[100:103], v[92:95], v[60:63], v[100:103]
	ds_read_b128 v[64:67], v168 offset:128
	ds_read_b128 v[68:71], v168 offset:2176
	ds_read_b128 v[72:75], v168 offset:4224
	ds_read_b128 v[76:79], v168 offset:6272
	ds_read_b128 v[80:83], v168 offset:192
	ds_read_b128 v[84:87], v168 offset:2240
	ds_read_b128 v[88:91], v168 offset:4288
	ds_read_b128 v[92:95], v168 offset:6336
	ds_read_b64_tr_b16 v[108:109], v166 offset:9216
	ds_read_b64_tr_b16 v[110:111], v166 offset:13824
	ds_read_b64_tr_b16 v[112:113], v166 offset:9248
	ds_read_b64_tr_b16 v[114:115], v166 offset:13856
	s_waitcnt lgkmcnt(4)
	v_subrev_u32_e32 v236, 32, v175
	v_cmp_gt_i32_e64 s[78:79], v236, 0
	v_cmp_gt_i32_e64 s[80:81], v236, 1
	v_cmp_gt_i32_e64 s[82:83], v236, 2
	v_cmp_gt_i32_e64 s[84:85], v236, 3
	v_cmp_eq_u32_e64 s[86:87], v236, 0
	v_cmp_eq_u32_e64 s[88:89], v236, 1
	v_cmp_eq_u32_e64 s[90:91], v236, 2
	v_cmp_eq_u32_e64 s[92:93], v236, 3
	v_cndmask_b32_e64 v237, v76, v72, s[78:79]
	v_cndmask_b32_e64 v238, v157, v156, s[78:79]
	v_sub_f32_e32 v237, v238, v237
	v_min_f32_e32 v237, 0, v237
	v_mul_f32_e32 v237, 0x3fb8aa3b, v237
	v_exp_f32_e32 v237, v237
	v_cndmask_b32_e64 v239, v68, v64, s[78:79]
	v_add_f32_e32 v240, v64, v68
	v_mul_f32_e32 v237, v239, v237
	v_cndmask_b32_e64 v237, v237, v240, s[86:87]
	v_mul_f32_e32 v241, v96, v237
	v_cndmask_b32_e64 v237, v77, v73, s[80:81]
	v_cndmask_b32_e64 v238, v157, v156, s[80:81]
	v_sub_f32_e32 v237, v238, v237
	v_min_f32_e32 v237, 0, v237
	v_mul_f32_e32 v237, 0x3fb8aa3b, v237
	v_exp_f32_e32 v237, v237
	v_cndmask_b32_e64 v239, v69, v65, s[80:81]
	v_add_f32_e32 v240, v65, v69
	v_mul_f32_e32 v237, v239, v237
	v_cndmask_b32_e64 v237, v237, v240, s[88:89]
	v_mul_f32_e32 v242, v97, v237
	v_cndmask_b32_e64 v237, v78, v74, s[82:83]
	v_cndmask_b32_e64 v238, v157, v156, s[82:83]
	v_sub_f32_e32 v237, v238, v237
	v_min_f32_e32 v237, 0, v237
	v_mul_f32_e32 v237, 0x3fb8aa3b, v237
	v_exp_f32_e32 v237, v237
	v_cndmask_b32_e64 v239, v70, v66, s[82:83]
	v_add_f32_e32 v240, v66, v70
	v_mul_f32_e32 v237, v239, v237
	v_cndmask_b32_e64 v237, v237, v240, s[90:91]
	v_mul_f32_e32 v243, v98, v237
	v_cndmask_b32_e64 v237, v79, v75, s[84:85]
	v_cndmask_b32_e64 v238, v157, v156, s[84:85]
	v_sub_f32_e32 v237, v238, v237
	v_min_f32_e32 v237, 0, v237
	v_mul_f32_e32 v237, 0x3fb8aa3b, v237
	v_exp_f32_e32 v237, v237
	v_cndmask_b32_e64 v239, v71, v67, s[84:85]
	v_add_f32_e32 v240, v67, v71
	v_mul_f32_e32 v237, v239, v237
	v_cndmask_b32_e64 v237, v237, v240, s[92:93]
	v_mul_f32_e32 v244, v99, v237
	ds_read_b64_tr_b16 v[116:117], v166 offset:9280
	ds_read_b64_tr_b16 v[118:119], v166 offset:13888
	ds_read_b64_tr_b16 v[120:121], v166 offset:9312
	ds_read_b64_tr_b16 v[122:123], v166 offset:13920
	v_subrev_u32_e32 v236, 48, v175
	v_cmp_gt_i32_e64 s[78:79], v236, 0
	v_cmp_gt_i32_e64 s[80:81], v236, 1
	v_cmp_gt_i32_e64 s[82:83], v236, 2
	v_cmp_gt_i32_e64 s[84:85], v236, 3
	v_cmp_eq_u32_e64 s[86:87], v236, 0
	v_cmp_eq_u32_e64 s[88:89], v236, 1
	v_cmp_eq_u32_e64 s[90:91], v236, 2
	v_cmp_eq_u32_e64 s[92:93], v236, 3
	v_cndmask_b32_e64 v237, v92, v88, s[78:79]
	v_cndmask_b32_e64 v238, v157, v156, s[78:79]
	v_sub_f32_e32 v237, v238, v237
	v_min_f32_e32 v237, 0, v237
	v_mul_f32_e32 v237, 0x3fb8aa3b, v237
	v_exp_f32_e32 v237, v237
	v_cndmask_b32_e64 v239, v84, v80, s[78:79]
	v_add_f32_e32 v240, v80, v84
	v_mul_f32_e32 v237, v239, v237
	v_cndmask_b32_e64 v237, v237, v240, s[86:87]
	v_mul_f32_e32 v245, v100, v237
	v_cndmask_b32_e64 v237, v93, v89, s[80:81]
	v_cndmask_b32_e64 v238, v157, v156, s[80:81]
	v_sub_f32_e32 v237, v238, v237
	v_min_f32_e32 v237, 0, v237
	v_mul_f32_e32 v237, 0x3fb8aa3b, v237
	v_exp_f32_e32 v237, v237
	v_cndmask_b32_e64 v239, v85, v81, s[80:81]
	v_add_f32_e32 v240, v81, v85
	v_mul_f32_e32 v237, v239, v237
	v_cndmask_b32_e64 v237, v237, v240, s[88:89]
	v_mul_f32_e32 v246, v101, v237
	v_cndmask_b32_e64 v237, v94, v90, s[82:83]
	v_cndmask_b32_e64 v238, v157, v156, s[82:83]
	v_sub_f32_e32 v237, v238, v237
	v_min_f32_e32 v237, 0, v237
	v_mul_f32_e32 v237, 0x3fb8aa3b, v237
	v_exp_f32_e32 v237, v237
	v_cndmask_b32_e64 v239, v86, v82, s[82:83]
	v_add_f32_e32 v240, v82, v86
	v_mul_f32_e32 v237, v239, v237
	v_cndmask_b32_e64 v237, v237, v240, s[90:91]
	v_mul_f32_e32 v247, v102, v237
	v_cndmask_b32_e64 v237, v95, v91, s[84:85]
	v_cndmask_b32_e64 v238, v157, v156, s[84:85]
	v_sub_f32_e32 v237, v238, v237
	v_min_f32_e32 v237, 0, v237
	v_mul_f32_e32 v237, 0x3fb8aa3b, v237
	v_exp_f32_e32 v237, v237
	v_cndmask_b32_e64 v239, v87, v83, s[84:85]
	v_add_f32_e32 v240, v83, v87
	v_mul_f32_e32 v237, v239, v237
	v_cndmask_b32_e64 v237, v237, v240, s[92:93]
	v_mul_f32_e32 v248, v103, v237
	v_cvt_pk_bf16_f32 v104, v241, v242
	v_cvt_pk_bf16_f32 v105, v243, v244
	v_cvt_pk_bf16_f32 v106, v245, v246
	v_cvt_pk_bf16_f32 v107, v247, v248
	s_waitcnt lgkmcnt(0)
	s_nop 1
	v_mfma_f32_16x16x32_bf16 v[16:19], v[104:107], v[108:111], v[16:19]
	v_mfma_f32_16x16x32_bf16 v[20:23], v[104:107], v[112:115], v[20:23]
	v_mfma_f32_16x16x32_bf16 v[24:27], v[104:107], v[116:119], v[24:27]
	v_mfma_f32_16x16x32_bf16 v[28:31], v[104:107], v[120:123], v[28:31]
	ds_read_b128 v[64:67], v168 offset:640
	ds_read_b128 v[68:71], v168 offset:2688
	ds_read_b128 v[72:75], v168 offset:4736
	ds_read_b128 v[76:79], v168 offset:6784
	ds_read_b128 v[80:83], v168 offset:704
	ds_read_b128 v[84:87], v168 offset:2752
	ds_read_b128 v[88:91], v168 offset:4800
	ds_read_b128 v[92:95], v168 offset:6848
	ds_read_b64_tr_b16 v[108:109], v166 offset:9344
	ds_read_b64_tr_b16 v[110:111], v166 offset:13952
	ds_read_b64_tr_b16 v[112:113], v166 offset:9376
	ds_read_b64_tr_b16 v[114:115], v166 offset:13984
	s_waitcnt lgkmcnt(4)
	v_subrev_u32_e32 v236, 32, v175
	v_cmp_gt_i32_e64 s[78:79], v236, 0
	v_cmp_gt_i32_e64 s[80:81], v236, 1
	v_cmp_gt_i32_e64 s[82:83], v236, 2
	v_cmp_gt_i32_e64 s[84:85], v236, 3
	v_cmp_eq_u32_e64 s[86:87], v236, 0
	v_cmp_eq_u32_e64 s[88:89], v236, 1
	v_cmp_eq_u32_e64 s[90:91], v236, 2
	v_cmp_eq_u32_e64 s[92:93], v236, 3
	v_cndmask_b32_e64 v237, v76, v72, s[78:79]
	v_cndmask_b32_e64 v238, v159, v158, s[78:79]
	v_sub_f32_e32 v237, v238, v237
	v_min_f32_e32 v237, 0, v237
	v_mul_f32_e32 v237, 0x3fb8aa3b, v237
	v_exp_f32_e32 v237, v237
	v_cndmask_b32_e64 v239, v68, v64, s[78:79]
	v_add_f32_e32 v240, v64, v68
	v_mul_f32_e32 v237, v239, v237
	v_cndmask_b32_e64 v237, v237, v240, s[86:87]
	v_mul_f32_e32 v241, v96, v237
	v_cndmask_b32_e64 v237, v77, v73, s[80:81]
	v_cndmask_b32_e64 v238, v159, v158, s[80:81]
	v_sub_f32_e32 v237, v238, v237
	v_min_f32_e32 v237, 0, v237
	v_mul_f32_e32 v237, 0x3fb8aa3b, v237
	v_exp_f32_e32 v237, v237
	v_cndmask_b32_e64 v239, v69, v65, s[80:81]
	v_add_f32_e32 v240, v65, v69
	v_mul_f32_e32 v237, v239, v237
	v_cndmask_b32_e64 v237, v237, v240, s[88:89]
	v_mul_f32_e32 v242, v97, v237
	v_cndmask_b32_e64 v237, v78, v74, s[82:83]
	v_cndmask_b32_e64 v238, v159, v158, s[82:83]
	v_sub_f32_e32 v237, v238, v237
	v_min_f32_e32 v237, 0, v237
	v_mul_f32_e32 v237, 0x3fb8aa3b, v237
	v_exp_f32_e32 v237, v237
	v_cndmask_b32_e64 v239, v70, v66, s[82:83]
	v_add_f32_e32 v240, v66, v70
	v_mul_f32_e32 v237, v239, v237
	v_cndmask_b32_e64 v237, v237, v240, s[90:91]
	v_mul_f32_e32 v243, v98, v237
	v_cndmask_b32_e64 v237, v79, v75, s[84:85]
	v_cndmask_b32_e64 v238, v159, v158, s[84:85]
	v_sub_f32_e32 v237, v238, v237
	v_min_f32_e32 v237, 0, v237
	v_mul_f32_e32 v237, 0x3fb8aa3b, v237
	v_exp_f32_e32 v237, v237
	v_cndmask_b32_e64 v239, v71, v67, s[84:85]
	v_add_f32_e32 v240, v67, v71
	v_mul_f32_e32 v237, v239, v237
	v_cndmask_b32_e64 v237, v237, v240, s[92:93]
	v_mul_f32_e32 v244, v99, v237
	ds_read_b64_tr_b16 v[116:117], v166 offset:9408
	ds_read_b64_tr_b16 v[118:119], v166 offset:14016
	ds_read_b64_tr_b16 v[120:121], v166 offset:9440
	ds_read_b64_tr_b16 v[122:123], v166 offset:14048
	v_subrev_u32_e32 v236, 48, v175
	v_cmp_gt_i32_e64 s[78:79], v236, 0
	v_cmp_gt_i32_e64 s[80:81], v236, 1
	v_cmp_gt_i32_e64 s[82:83], v236, 2
	v_cmp_gt_i32_e64 s[84:85], v236, 3
	v_cmp_eq_u32_e64 s[86:87], v236, 0
	v_cmp_eq_u32_e64 s[88:89], v236, 1
	v_cmp_eq_u32_e64 s[90:91], v236, 2
	v_cmp_eq_u32_e64 s[92:93], v236, 3
	v_cndmask_b32_e64 v237, v92, v88, s[78:79]
	v_cndmask_b32_e64 v238, v159, v158, s[78:79]
	v_sub_f32_e32 v237, v238, v237
	v_min_f32_e32 v237, 0, v237
	v_mul_f32_e32 v237, 0x3fb8aa3b, v237
	v_exp_f32_e32 v237, v237
	v_cndmask_b32_e64 v239, v84, v80, s[78:79]
	v_add_f32_e32 v240, v80, v84
	v_mul_f32_e32 v237, v239, v237
	v_cndmask_b32_e64 v237, v237, v240, s[86:87]
	v_mul_f32_e32 v245, v100, v237
	v_cndmask_b32_e64 v237, v93, v89, s[80:81]
	v_cndmask_b32_e64 v238, v159, v158, s[80:81]
	v_sub_f32_e32 v237, v238, v237
	v_min_f32_e32 v237, 0, v237
	v_mul_f32_e32 v237, 0x3fb8aa3b, v237
	v_exp_f32_e32 v237, v237
	v_cndmask_b32_e64 v239, v85, v81, s[80:81]
	v_add_f32_e32 v240, v81, v85
	v_mul_f32_e32 v237, v239, v237
	v_cndmask_b32_e64 v237, v237, v240, s[88:89]
	v_mul_f32_e32 v246, v101, v237
	v_cndmask_b32_e64 v237, v94, v90, s[82:83]
	v_cndmask_b32_e64 v238, v159, v158, s[82:83]
	v_sub_f32_e32 v237, v238, v237
	v_min_f32_e32 v237, 0, v237
	v_mul_f32_e32 v237, 0x3fb8aa3b, v237
	v_exp_f32_e32 v237, v237
	v_cndmask_b32_e64 v239, v86, v82, s[82:83]
	v_add_f32_e32 v240, v82, v86
	v_mul_f32_e32 v237, v239, v237
	v_cndmask_b32_e64 v237, v237, v240, s[90:91]
	v_mul_f32_e32 v247, v102, v237
	v_cndmask_b32_e64 v237, v95, v91, s[84:85]
	v_cndmask_b32_e64 v238, v159, v158, s[84:85]
	v_sub_f32_e32 v237, v238, v237
	v_min_f32_e32 v237, 0, v237
	v_mul_f32_e32 v237, 0x3fb8aa3b, v237
	v_exp_f32_e32 v237, v237
	v_cndmask_b32_e64 v239, v87, v83, s[84:85]
	v_add_f32_e32 v240, v83, v87
	v_mul_f32_e32 v237, v239, v237
	v_cndmask_b32_e64 v237, v237, v240, s[92:93]
	v_mul_f32_e32 v248, v103, v237
	v_cvt_pk_bf16_f32 v104, v241, v242
	v_cvt_pk_bf16_f32 v105, v243, v244
	v_cvt_pk_bf16_f32 v106, v245, v246
	v_cvt_pk_bf16_f32 v107, v247, v248
	s_waitcnt lgkmcnt(0)
	s_nop 1
	v_mfma_f32_16x16x32_bf16 v[32:35], v[104:107], v[108:111], v[32:35]
	v_mfma_f32_16x16x32_bf16 v[36:39], v[104:107], v[112:115], v[36:39]
	v_mfma_f32_16x16x32_bf16 v[40:43], v[104:107], v[116:119], v[40:43]
	v_mfma_f32_16x16x32_bf16 v[44:47], v[104:107], v[120:123], v[44:47]
	ds_read_b128 v[64:67], v169 offset:17408
	ds_read_b128 v[68:71], v169 offset:17472
	ds_read_b128 v[72:75], v169 offset:17536
	ds_read_b128 v[76:79], v169 offset:17600
	ds_read_b128 v[80:83], v169 offset:21760
	ds_read_b128 v[84:87], v169 offset:21824
	ds_read_b128 v[88:91], v169 offset:21888
	ds_read_b128 v[92:95], v169 offset:21952
	s_waitcnt lgkmcnt(0)
	v_mfma_f32_16x16x32_bf16 v[96:99], v[64:67], v[48:51], 0
	v_mfma_f32_16x16x32_bf16 v[96:99], v[68:71], v[52:55], v[96:99]
	v_mfma_f32_16x16x32_bf16 v[96:99], v[72:75], v[56:59], v[96:99]
	v_mfma_f32_16x16x32_bf16 v[96:99], v[76:79], v[60:63], v[96:99]
	v_mfma_f32_16x16x32_bf16 v[100:103], v[80:83], v[48:51], 0
	v_mfma_f32_16x16x32_bf16 v[100:103], v[84:87], v[52:55], v[100:103]
	v_mfma_f32_16x16x32_bf16 v[100:103], v[88:91], v[56:59], v[100:103]
	v_mfma_f32_16x16x32_bf16 v[100:103], v[92:95], v[60:63], v[100:103]
	ds_read_b128 v[64:67], v168 offset:256
	ds_read_b128 v[68:71], v168 offset:2304
	ds_read_b128 v[72:75], v168 offset:4352
	ds_read_b128 v[76:79], v168 offset:6400
	ds_read_b128 v[80:83], v168 offset:320
	ds_read_b128 v[84:87], v168 offset:2368
	ds_read_b128 v[88:91], v168 offset:4416
	ds_read_b128 v[92:95], v168 offset:6464
	ds_read_b64_tr_b16 v[108:109], v166 offset:18432
	ds_read_b64_tr_b16 v[110:111], v166 offset:23040
	ds_read_b64_tr_b16 v[112:113], v166 offset:18464
	ds_read_b64_tr_b16 v[114:115], v166 offset:23072
	s_waitcnt lgkmcnt(4)
	v_subrev_u32_e32 v236, 64, v175
	v_cmp_gt_i32_e64 s[78:79], v236, 0
	v_cmp_gt_i32_e64 s[80:81], v236, 1
	v_cmp_gt_i32_e64 s[82:83], v236, 2
	v_cmp_gt_i32_e64 s[84:85], v236, 3
	v_cmp_eq_u32_e64 s[86:87], v236, 0
	v_cmp_eq_u32_e64 s[88:89], v236, 1
	v_cmp_eq_u32_e64 s[90:91], v236, 2
	v_cmp_eq_u32_e64 s[92:93], v236, 3
	v_cndmask_b32_e64 v237, v76, v72, s[78:79]
	v_cndmask_b32_e64 v238, v157, v156, s[78:79]
	v_sub_f32_e32 v237, v238, v237
	v_min_f32_e32 v237, 0, v237
	v_mul_f32_e32 v237, 0x3fb8aa3b, v237
	v_exp_f32_e32 v237, v237
	v_cndmask_b32_e64 v239, v68, v64, s[78:79]
	v_add_f32_e32 v240, v64, v68
	v_mul_f32_e32 v237, v239, v237
	v_cndmask_b32_e64 v237, v237, v240, s[86:87]
	v_mul_f32_e32 v241, v96, v237
	v_cndmask_b32_e64 v237, v77, v73, s[80:81]
	v_cndmask_b32_e64 v238, v157, v156, s[80:81]
	v_sub_f32_e32 v237, v238, v237
	v_min_f32_e32 v237, 0, v237
	v_mul_f32_e32 v237, 0x3fb8aa3b, v237
	v_exp_f32_e32 v237, v237
	v_cndmask_b32_e64 v239, v69, v65, s[80:81]
	v_add_f32_e32 v240, v65, v69
	v_mul_f32_e32 v237, v239, v237
	v_cndmask_b32_e64 v237, v237, v240, s[88:89]
	v_mul_f32_e32 v242, v97, v237
	v_cndmask_b32_e64 v237, v78, v74, s[82:83]
	v_cndmask_b32_e64 v238, v157, v156, s[82:83]
	v_sub_f32_e32 v237, v238, v237
	v_min_f32_e32 v237, 0, v237
	v_mul_f32_e32 v237, 0x3fb8aa3b, v237
	v_exp_f32_e32 v237, v237
	v_cndmask_b32_e64 v239, v70, v66, s[82:83]
	v_add_f32_e32 v240, v66, v70
	v_mul_f32_e32 v237, v239, v237
	v_cndmask_b32_e64 v237, v237, v240, s[90:91]
	v_mul_f32_e32 v243, v98, v237
	v_cndmask_b32_e64 v237, v79, v75, s[84:85]
	v_cndmask_b32_e64 v238, v157, v156, s[84:85]
	v_sub_f32_e32 v237, v238, v237
	v_min_f32_e32 v237, 0, v237
	v_mul_f32_e32 v237, 0x3fb8aa3b, v237
	v_exp_f32_e32 v237, v237
	v_cndmask_b32_e64 v239, v71, v67, s[84:85]
	v_add_f32_e32 v240, v67, v71
	v_mul_f32_e32 v237, v239, v237
	v_cndmask_b32_e64 v237, v237, v240, s[92:93]
	v_mul_f32_e32 v244, v99, v237
	ds_read_b64_tr_b16 v[116:117], v166 offset:18496
	ds_read_b64_tr_b16 v[118:119], v166 offset:23104
	ds_read_b64_tr_b16 v[120:121], v166 offset:18528
	ds_read_b64_tr_b16 v[122:123], v166 offset:23136
	v_subrev_u32_e32 v236, 80, v175
	v_cmp_gt_i32_e64 s[78:79], v236, 0
	v_cmp_gt_i32_e64 s[80:81], v236, 1
	v_cmp_gt_i32_e64 s[82:83], v236, 2
	v_cmp_gt_i32_e64 s[84:85], v236, 3
	v_cmp_eq_u32_e64 s[86:87], v236, 0
	v_cmp_eq_u32_e64 s[88:89], v236, 1
	v_cmp_eq_u32_e64 s[90:91], v236, 2
	v_cmp_eq_u32_e64 s[92:93], v236, 3
	v_cndmask_b32_e64 v237, v92, v88, s[78:79]
	v_cndmask_b32_e64 v238, v157, v156, s[78:79]
	v_sub_f32_e32 v237, v238, v237
	v_min_f32_e32 v237, 0, v237
	v_mul_f32_e32 v237, 0x3fb8aa3b, v237
	v_exp_f32_e32 v237, v237
	v_cndmask_b32_e64 v239, v84, v80, s[78:79]
	v_add_f32_e32 v240, v80, v84
	v_mul_f32_e32 v237, v239, v237
	v_cndmask_b32_e64 v237, v237, v240, s[86:87]
	v_mul_f32_e32 v245, v100, v237
	v_cndmask_b32_e64 v237, v93, v89, s[80:81]
	v_cndmask_b32_e64 v238, v157, v156, s[80:81]
	v_sub_f32_e32 v237, v238, v237
	v_min_f32_e32 v237, 0, v237
	v_mul_f32_e32 v237, 0x3fb8aa3b, v237
	v_exp_f32_e32 v237, v237
	v_cndmask_b32_e64 v239, v85, v81, s[80:81]
	v_add_f32_e32 v240, v81, v85
	v_mul_f32_e32 v237, v239, v237
	v_cndmask_b32_e64 v237, v237, v240, s[88:89]
	v_mul_f32_e32 v246, v101, v237
	v_cndmask_b32_e64 v237, v94, v90, s[82:83]
	v_cndmask_b32_e64 v238, v157, v156, s[82:83]
	v_sub_f32_e32 v237, v238, v237
	v_min_f32_e32 v237, 0, v237
	v_mul_f32_e32 v237, 0x3fb8aa3b, v237
	v_exp_f32_e32 v237, v237
	v_cndmask_b32_e64 v239, v86, v82, s[82:83]
	v_add_f32_e32 v240, v82, v86
	v_mul_f32_e32 v237, v239, v237
	v_cndmask_b32_e64 v237, v237, v240, s[90:91]
	v_mul_f32_e32 v247, v102, v237
	v_cndmask_b32_e64 v237, v95, v91, s[84:85]
	v_cndmask_b32_e64 v238, v157, v156, s[84:85]
	v_sub_f32_e32 v237, v238, v237
	v_min_f32_e32 v237, 0, v237
	v_mul_f32_e32 v237, 0x3fb8aa3b, v237
	v_exp_f32_e32 v237, v237
	v_cndmask_b32_e64 v239, v87, v83, s[84:85]
	v_add_f32_e32 v240, v83, v87
	v_mul_f32_e32 v237, v239, v237
	v_cndmask_b32_e64 v237, v237, v240, s[92:93]
	v_mul_f32_e32 v248, v103, v237
	v_cvt_pk_bf16_f32 v104, v241, v242
	v_cvt_pk_bf16_f32 v105, v243, v244
	v_cvt_pk_bf16_f32 v106, v245, v246
	v_cvt_pk_bf16_f32 v107, v247, v248
	s_waitcnt lgkmcnt(0)
	s_nop 1
	v_mfma_f32_16x16x32_bf16 v[16:19], v[104:107], v[108:111], v[16:19]
	v_mfma_f32_16x16x32_bf16 v[20:23], v[104:107], v[112:115], v[20:23]
	v_mfma_f32_16x16x32_bf16 v[24:27], v[104:107], v[116:119], v[24:27]
	v_mfma_f32_16x16x32_bf16 v[28:31], v[104:107], v[120:123], v[28:31]
	ds_read_b128 v[64:67], v168 offset:768
	ds_read_b128 v[68:71], v168 offset:2816
	ds_read_b128 v[72:75], v168 offset:4864
	ds_read_b128 v[76:79], v168 offset:6912
	ds_read_b128 v[80:83], v168 offset:832
	ds_read_b128 v[84:87], v168 offset:2880
	ds_read_b128 v[88:91], v168 offset:4928
	ds_read_b128 v[92:95], v168 offset:6976
	ds_read_b64_tr_b16 v[108:109], v166 offset:18560
	ds_read_b64_tr_b16 v[110:111], v166 offset:23168
	ds_read_b64_tr_b16 v[112:113], v166 offset:18592
	ds_read_b64_tr_b16 v[114:115], v166 offset:23200
	s_waitcnt lgkmcnt(4)
	v_subrev_u32_e32 v236, 64, v175
	v_cmp_gt_i32_e64 s[78:79], v236, 0
	v_cmp_gt_i32_e64 s[80:81], v236, 1
	v_cmp_gt_i32_e64 s[82:83], v236, 2
	v_cmp_gt_i32_e64 s[84:85], v236, 3
	v_cmp_eq_u32_e64 s[86:87], v236, 0
	v_cmp_eq_u32_e64 s[88:89], v236, 1
	v_cmp_eq_u32_e64 s[90:91], v236, 2
	v_cmp_eq_u32_e64 s[92:93], v236, 3
	v_cndmask_b32_e64 v237, v76, v72, s[78:79]
	v_cndmask_b32_e64 v238, v159, v158, s[78:79]
	v_sub_f32_e32 v237, v238, v237
	v_min_f32_e32 v237, 0, v237
	v_mul_f32_e32 v237, 0x3fb8aa3b, v237
	v_exp_f32_e32 v237, v237
	v_cndmask_b32_e64 v239, v68, v64, s[78:79]
	v_add_f32_e32 v240, v64, v68
	v_mul_f32_e32 v237, v239, v237
	v_cndmask_b32_e64 v237, v237, v240, s[86:87]
	v_mul_f32_e32 v241, v96, v237
	v_cndmask_b32_e64 v237, v77, v73, s[80:81]
	v_cndmask_b32_e64 v238, v159, v158, s[80:81]
	v_sub_f32_e32 v237, v238, v237
	v_min_f32_e32 v237, 0, v237
	v_mul_f32_e32 v237, 0x3fb8aa3b, v237
	v_exp_f32_e32 v237, v237
	v_cndmask_b32_e64 v239, v69, v65, s[80:81]
	v_add_f32_e32 v240, v65, v69
	v_mul_f32_e32 v237, v239, v237
	v_cndmask_b32_e64 v237, v237, v240, s[88:89]
	v_mul_f32_e32 v242, v97, v237
	v_cndmask_b32_e64 v237, v78, v74, s[82:83]
	v_cndmask_b32_e64 v238, v159, v158, s[82:83]
	v_sub_f32_e32 v237, v238, v237
	v_min_f32_e32 v237, 0, v237
	v_mul_f32_e32 v237, 0x3fb8aa3b, v237
	v_exp_f32_e32 v237, v237
	v_cndmask_b32_e64 v239, v70, v66, s[82:83]
	v_add_f32_e32 v240, v66, v70
	v_mul_f32_e32 v237, v239, v237
	v_cndmask_b32_e64 v237, v237, v240, s[90:91]
	v_mul_f32_e32 v243, v98, v237
	v_cndmask_b32_e64 v237, v79, v75, s[84:85]
	v_cndmask_b32_e64 v238, v159, v158, s[84:85]
	v_sub_f32_e32 v237, v238, v237
	v_min_f32_e32 v237, 0, v237
	v_mul_f32_e32 v237, 0x3fb8aa3b, v237
	v_exp_f32_e32 v237, v237
	v_cndmask_b32_e64 v239, v71, v67, s[84:85]
	v_add_f32_e32 v240, v67, v71
	v_mul_f32_e32 v237, v239, v237
	v_cndmask_b32_e64 v237, v237, v240, s[92:93]
	v_mul_f32_e32 v244, v99, v237
	ds_read_b64_tr_b16 v[116:117], v166 offset:18624
	ds_read_b64_tr_b16 v[118:119], v166 offset:23232
	ds_read_b64_tr_b16 v[120:121], v166 offset:18656
	ds_read_b64_tr_b16 v[122:123], v166 offset:23264
	v_subrev_u32_e32 v236, 80, v175
	v_cmp_gt_i32_e64 s[78:79], v236, 0
	v_cmp_gt_i32_e64 s[80:81], v236, 1
	v_cmp_gt_i32_e64 s[82:83], v236, 2
	v_cmp_gt_i32_e64 s[84:85], v236, 3
	v_cmp_eq_u32_e64 s[86:87], v236, 0
	v_cmp_eq_u32_e64 s[88:89], v236, 1
	v_cmp_eq_u32_e64 s[90:91], v236, 2
	v_cmp_eq_u32_e64 s[92:93], v236, 3
	v_cndmask_b32_e64 v237, v92, v88, s[78:79]
	v_cndmask_b32_e64 v238, v159, v158, s[78:79]
	v_sub_f32_e32 v237, v238, v237
	v_min_f32_e32 v237, 0, v237
	v_mul_f32_e32 v237, 0x3fb8aa3b, v237
	v_exp_f32_e32 v237, v237
	v_cndmask_b32_e64 v239, v84, v80, s[78:79]
	v_add_f32_e32 v240, v80, v84
	v_mul_f32_e32 v237, v239, v237
	v_cndmask_b32_e64 v237, v237, v240, s[86:87]
	v_mul_f32_e32 v245, v100, v237
	v_cndmask_b32_e64 v237, v93, v89, s[80:81]
	v_cndmask_b32_e64 v238, v159, v158, s[80:81]
	v_sub_f32_e32 v237, v238, v237
	v_min_f32_e32 v237, 0, v237
	v_mul_f32_e32 v237, 0x3fb8aa3b, v237
	v_exp_f32_e32 v237, v237
	v_cndmask_b32_e64 v239, v85, v81, s[80:81]
	v_add_f32_e32 v240, v81, v85
	v_mul_f32_e32 v237, v239, v237
	v_cndmask_b32_e64 v237, v237, v240, s[88:89]
	v_mul_f32_e32 v246, v101, v237
	v_cndmask_b32_e64 v237, v94, v90, s[82:83]
	v_cndmask_b32_e64 v238, v159, v158, s[82:83]
	v_sub_f32_e32 v237, v238, v237
	v_min_f32_e32 v237, 0, v237
	v_mul_f32_e32 v237, 0x3fb8aa3b, v237
	v_exp_f32_e32 v237, v237
	v_cndmask_b32_e64 v239, v86, v82, s[82:83]
	v_add_f32_e32 v240, v82, v86
	v_mul_f32_e32 v237, v239, v237
	v_cndmask_b32_e64 v237, v237, v240, s[90:91]
	v_mul_f32_e32 v247, v102, v237
	v_cndmask_b32_e64 v237, v95, v91, s[84:85]
	v_cndmask_b32_e64 v238, v159, v158, s[84:85]
	v_sub_f32_e32 v237, v238, v237
	v_min_f32_e32 v237, 0, v237
	v_mul_f32_e32 v237, 0x3fb8aa3b, v237
	v_exp_f32_e32 v237, v237
	v_cndmask_b32_e64 v239, v87, v83, s[84:85]
	v_add_f32_e32 v240, v83, v87
	v_mul_f32_e32 v237, v239, v237
	v_cndmask_b32_e64 v237, v237, v240, s[92:93]
	v_mul_f32_e32 v248, v103, v237
	v_cvt_pk_bf16_f32 v104, v241, v242
	v_cvt_pk_bf16_f32 v105, v243, v244
	v_cvt_pk_bf16_f32 v106, v245, v246
	v_cvt_pk_bf16_f32 v107, v247, v248
	s_waitcnt lgkmcnt(0)
	s_nop 1
	v_mfma_f32_16x16x32_bf16 v[32:35], v[104:107], v[108:111], v[32:35]
	v_mfma_f32_16x16x32_bf16 v[36:39], v[104:107], v[112:115], v[36:39]
	v_mfma_f32_16x16x32_bf16 v[40:43], v[104:107], v[116:119], v[40:43]
	v_mfma_f32_16x16x32_bf16 v[44:47], v[104:107], v[120:123], v[44:47]
	ds_read_b128 v[64:67], v169 offset:26112
	ds_read_b128 v[68:71], v169 offset:26176
	ds_read_b128 v[72:75], v169 offset:26240
	ds_read_b128 v[76:79], v169 offset:26304
	ds_read_b128 v[80:83], v169 offset:30464
	ds_read_b128 v[84:87], v169 offset:30528
	ds_read_b128 v[88:91], v169 offset:30592
	ds_read_b128 v[92:95], v169 offset:30656
	s_waitcnt lgkmcnt(0)
	v_mfma_f32_16x16x32_bf16 v[96:99], v[64:67], v[48:51], 0
	v_mfma_f32_16x16x32_bf16 v[96:99], v[68:71], v[52:55], v[96:99]
	v_mfma_f32_16x16x32_bf16 v[96:99], v[72:75], v[56:59], v[96:99]
	v_mfma_f32_16x16x32_bf16 v[96:99], v[76:79], v[60:63], v[96:99]
	v_mfma_f32_16x16x32_bf16 v[100:103], v[80:83], v[48:51], 0
	v_mfma_f32_16x16x32_bf16 v[100:103], v[84:87], v[52:55], v[100:103]
	v_mfma_f32_16x16x32_bf16 v[100:103], v[88:91], v[56:59], v[100:103]
	v_mfma_f32_16x16x32_bf16 v[100:103], v[92:95], v[60:63], v[100:103]
	ds_read_b128 v[64:67], v168 offset:384
	ds_read_b128 v[68:71], v168 offset:2432
	ds_read_b128 v[72:75], v168 offset:4480
	ds_read_b128 v[76:79], v168 offset:6528
	ds_read_b128 v[80:83], v168 offset:448
	ds_read_b128 v[84:87], v168 offset:2496
	ds_read_b128 v[88:91], v168 offset:4544
	ds_read_b128 v[92:95], v168 offset:6592
	ds_read_b64_tr_b16 v[108:109], v166 offset:27648
	ds_read_b64_tr_b16 v[110:111], v166 offset:32256
	ds_read_b64_tr_b16 v[112:113], v166 offset:27680
	ds_read_b64_tr_b16 v[114:115], v166 offset:32288
	s_waitcnt lgkmcnt(4)
	v_subrev_u32_e32 v236, 96, v175
	v_cmp_gt_i32_e64 s[78:79], v236, 0
	v_cmp_gt_i32_e64 s[80:81], v236, 1
	v_cmp_gt_i32_e64 s[82:83], v236, 2
	v_cmp_gt_i32_e64 s[84:85], v236, 3
	v_cmp_eq_u32_e64 s[86:87], v236, 0
	v_cmp_eq_u32_e64 s[88:89], v236, 1
	v_cmp_eq_u32_e64 s[90:91], v236, 2
	v_cmp_eq_u32_e64 s[92:93], v236, 3
	v_cndmask_b32_e64 v237, v76, v72, s[78:79]
	v_cndmask_b32_e64 v238, v157, v156, s[78:79]
	v_sub_f32_e32 v237, v238, v237
	v_min_f32_e32 v237, 0, v237
	v_mul_f32_e32 v237, 0x3fb8aa3b, v237
	v_exp_f32_e32 v237, v237
	v_cndmask_b32_e64 v239, v68, v64, s[78:79]
	v_add_f32_e32 v240, v64, v68
	v_mul_f32_e32 v237, v239, v237
	v_cndmask_b32_e64 v237, v237, v240, s[86:87]
	v_mul_f32_e32 v241, v96, v237
	v_cndmask_b32_e64 v237, v77, v73, s[80:81]
	v_cndmask_b32_e64 v238, v157, v156, s[80:81]
	v_sub_f32_e32 v237, v238, v237
	v_min_f32_e32 v237, 0, v237
	v_mul_f32_e32 v237, 0x3fb8aa3b, v237
	v_exp_f32_e32 v237, v237
	v_cndmask_b32_e64 v239, v69, v65, s[80:81]
	v_add_f32_e32 v240, v65, v69
	v_mul_f32_e32 v237, v239, v237
	v_cndmask_b32_e64 v237, v237, v240, s[88:89]
	v_mul_f32_e32 v242, v97, v237
	v_cndmask_b32_e64 v237, v78, v74, s[82:83]
	v_cndmask_b32_e64 v238, v157, v156, s[82:83]
	v_sub_f32_e32 v237, v238, v237
	v_min_f32_e32 v237, 0, v237
	v_mul_f32_e32 v237, 0x3fb8aa3b, v237
	v_exp_f32_e32 v237, v237
	v_cndmask_b32_e64 v239, v70, v66, s[82:83]
	v_add_f32_e32 v240, v66, v70
	v_mul_f32_e32 v237, v239, v237
	v_cndmask_b32_e64 v237, v237, v240, s[90:91]
	v_mul_f32_e32 v243, v98, v237
	v_cndmask_b32_e64 v237, v79, v75, s[84:85]
	v_cndmask_b32_e64 v238, v157, v156, s[84:85]
	v_sub_f32_e32 v237, v238, v237
	v_min_f32_e32 v237, 0, v237
	v_mul_f32_e32 v237, 0x3fb8aa3b, v237
	v_exp_f32_e32 v237, v237
	v_cndmask_b32_e64 v239, v71, v67, s[84:85]
	v_add_f32_e32 v240, v67, v71
	v_mul_f32_e32 v237, v239, v237
	v_cndmask_b32_e64 v237, v237, v240, s[92:93]
	v_mul_f32_e32 v244, v99, v237
	ds_read_b64_tr_b16 v[116:117], v166 offset:27712
	ds_read_b64_tr_b16 v[118:119], v166 offset:32320
	ds_read_b64_tr_b16 v[120:121], v166 offset:27744
	ds_read_b64_tr_b16 v[122:123], v166 offset:32352
	v_subrev_u32_e32 v236, 112, v175
	v_cmp_gt_i32_e64 s[78:79], v236, 0
	v_cmp_gt_i32_e64 s[80:81], v236, 1
	v_cmp_gt_i32_e64 s[82:83], v236, 2
	v_cmp_gt_i32_e64 s[84:85], v236, 3
	v_cmp_eq_u32_e64 s[86:87], v236, 0
	v_cmp_eq_u32_e64 s[88:89], v236, 1
	v_cmp_eq_u32_e64 s[90:91], v236, 2
	v_cmp_eq_u32_e64 s[92:93], v236, 3
	v_cndmask_b32_e64 v237, v92, v88, s[78:79]
	v_cndmask_b32_e64 v238, v157, v156, s[78:79]
	v_sub_f32_e32 v237, v238, v237
	v_min_f32_e32 v237, 0, v237
	v_mul_f32_e32 v237, 0x3fb8aa3b, v237
	v_exp_f32_e32 v237, v237
	v_cndmask_b32_e64 v239, v84, v80, s[78:79]
	v_add_f32_e32 v240, v80, v84
	v_mul_f32_e32 v237, v239, v237
	v_cndmask_b32_e64 v237, v237, v240, s[86:87]
	v_mul_f32_e32 v245, v100, v237
	v_cndmask_b32_e64 v237, v93, v89, s[80:81]
	v_cndmask_b32_e64 v238, v157, v156, s[80:81]
	v_sub_f32_e32 v237, v238, v237
	v_min_f32_e32 v237, 0, v237
	v_mul_f32_e32 v237, 0x3fb8aa3b, v237
	v_exp_f32_e32 v237, v237
	v_cndmask_b32_e64 v239, v85, v81, s[80:81]
	v_add_f32_e32 v240, v81, v85
	v_mul_f32_e32 v237, v239, v237
	v_cndmask_b32_e64 v237, v237, v240, s[88:89]
	v_mul_f32_e32 v246, v101, v237
	v_cndmask_b32_e64 v237, v94, v90, s[82:83]
	v_cndmask_b32_e64 v238, v157, v156, s[82:83]
	v_sub_f32_e32 v237, v238, v237
	v_min_f32_e32 v237, 0, v237
	v_mul_f32_e32 v237, 0x3fb8aa3b, v237
	v_exp_f32_e32 v237, v237
	v_cndmask_b32_e64 v239, v86, v82, s[82:83]
	v_add_f32_e32 v240, v82, v86
	v_mul_f32_e32 v237, v239, v237
	v_cndmask_b32_e64 v237, v237, v240, s[90:91]
	v_mul_f32_e32 v247, v102, v237
	v_cndmask_b32_e64 v237, v95, v91, s[84:85]
	v_cndmask_b32_e64 v238, v157, v156, s[84:85]
	v_sub_f32_e32 v237, v238, v237
	v_min_f32_e32 v237, 0, v237
	v_mul_f32_e32 v237, 0x3fb8aa3b, v237
	v_exp_f32_e32 v237, v237
	v_cndmask_b32_e64 v239, v87, v83, s[84:85]
	v_add_f32_e32 v240, v83, v87
	v_mul_f32_e32 v237, v239, v237
	v_cndmask_b32_e64 v237, v237, v240, s[92:93]
	v_mul_f32_e32 v248, v103, v237
	v_cvt_pk_bf16_f32 v104, v241, v242
	v_cvt_pk_bf16_f32 v105, v243, v244
	v_cvt_pk_bf16_f32 v106, v245, v246
	v_cvt_pk_bf16_f32 v107, v247, v248
	s_waitcnt lgkmcnt(0)
	s_nop 1
	v_mfma_f32_16x16x32_bf16 v[16:19], v[104:107], v[108:111], v[16:19]
	v_mfma_f32_16x16x32_bf16 v[20:23], v[104:107], v[112:115], v[20:23]
	v_mfma_f32_16x16x32_bf16 v[24:27], v[104:107], v[116:119], v[24:27]
	v_mfma_f32_16x16x32_bf16 v[28:31], v[104:107], v[120:123], v[28:31]
	ds_read_b128 v[64:67], v168 offset:896
	ds_read_b128 v[68:71], v168 offset:2944
	ds_read_b128 v[72:75], v168 offset:4992
	ds_read_b128 v[76:79], v168 offset:7040
	ds_read_b128 v[80:83], v168 offset:960
	ds_read_b128 v[84:87], v168 offset:3008
	ds_read_b128 v[88:91], v168 offset:5056
	ds_read_b128 v[92:95], v168 offset:7104
	ds_read_b64_tr_b16 v[108:109], v166 offset:27776
	ds_read_b64_tr_b16 v[110:111], v166 offset:32384
	ds_read_b64_tr_b16 v[112:113], v166 offset:27808
	ds_read_b64_tr_b16 v[114:115], v166 offset:32416
	s_waitcnt lgkmcnt(4)
	v_subrev_u32_e32 v236, 96, v175
	v_cmp_gt_i32_e64 s[78:79], v236, 0
	v_cmp_gt_i32_e64 s[80:81], v236, 1
	v_cmp_gt_i32_e64 s[82:83], v236, 2
	v_cmp_gt_i32_e64 s[84:85], v236, 3
	v_cmp_eq_u32_e64 s[86:87], v236, 0
	v_cmp_eq_u32_e64 s[88:89], v236, 1
	v_cmp_eq_u32_e64 s[90:91], v236, 2
	v_cmp_eq_u32_e64 s[92:93], v236, 3
	v_cndmask_b32_e64 v237, v76, v72, s[78:79]
	v_cndmask_b32_e64 v238, v159, v158, s[78:79]
	v_sub_f32_e32 v237, v238, v237
	v_min_f32_e32 v237, 0, v237
	v_mul_f32_e32 v237, 0x3fb8aa3b, v237
	v_exp_f32_e32 v237, v237
	v_cndmask_b32_e64 v239, v68, v64, s[78:79]
	v_add_f32_e32 v240, v64, v68
	v_mul_f32_e32 v237, v239, v237
	v_cndmask_b32_e64 v237, v237, v240, s[86:87]
	v_mul_f32_e32 v241, v96, v237
	v_cndmask_b32_e64 v237, v77, v73, s[80:81]
	v_cndmask_b32_e64 v238, v159, v158, s[80:81]
	v_sub_f32_e32 v237, v238, v237
	v_min_f32_e32 v237, 0, v237
	v_mul_f32_e32 v237, 0x3fb8aa3b, v237
	v_exp_f32_e32 v237, v237
	v_cndmask_b32_e64 v239, v69, v65, s[80:81]
	v_add_f32_e32 v240, v65, v69
	v_mul_f32_e32 v237, v239, v237
	v_cndmask_b32_e64 v237, v237, v240, s[88:89]
	v_mul_f32_e32 v242, v97, v237
	v_cndmask_b32_e64 v237, v78, v74, s[82:83]
	v_cndmask_b32_e64 v238, v159, v158, s[82:83]
	v_sub_f32_e32 v237, v238, v237
	v_min_f32_e32 v237, 0, v237
	v_mul_f32_e32 v237, 0x3fb8aa3b, v237
	v_exp_f32_e32 v237, v237
	v_cndmask_b32_e64 v239, v70, v66, s[82:83]
	v_add_f32_e32 v240, v66, v70
	v_mul_f32_e32 v237, v239, v237
	v_cndmask_b32_e64 v237, v237, v240, s[90:91]
	v_mul_f32_e32 v243, v98, v237
	v_cndmask_b32_e64 v237, v79, v75, s[84:85]
	v_cndmask_b32_e64 v238, v159, v158, s[84:85]
	v_sub_f32_e32 v237, v238, v237
	v_min_f32_e32 v237, 0, v237
	v_mul_f32_e32 v237, 0x3fb8aa3b, v237
	v_exp_f32_e32 v237, v237
	v_cndmask_b32_e64 v239, v71, v67, s[84:85]
	v_add_f32_e32 v240, v67, v71
	v_mul_f32_e32 v237, v239, v237
	v_cndmask_b32_e64 v237, v237, v240, s[92:93]
	v_mul_f32_e32 v244, v99, v237
	ds_read_b64_tr_b16 v[116:117], v166 offset:27840
	ds_read_b64_tr_b16 v[118:119], v166 offset:32448
	ds_read_b64_tr_b16 v[120:121], v166 offset:27872
	ds_read_b64_tr_b16 v[122:123], v166 offset:32480
	v_subrev_u32_e32 v236, 112, v175
	v_cmp_gt_i32_e64 s[78:79], v236, 0
	v_cmp_gt_i32_e64 s[80:81], v236, 1
	v_cmp_gt_i32_e64 s[82:83], v236, 2
	v_cmp_gt_i32_e64 s[84:85], v236, 3
	v_cmp_eq_u32_e64 s[86:87], v236, 0
	v_cmp_eq_u32_e64 s[88:89], v236, 1
	v_cmp_eq_u32_e64 s[90:91], v236, 2
	v_cmp_eq_u32_e64 s[92:93], v236, 3
	v_cndmask_b32_e64 v237, v92, v88, s[78:79]
	v_cndmask_b32_e64 v238, v159, v158, s[78:79]
	v_sub_f32_e32 v237, v238, v237
	v_min_f32_e32 v237, 0, v237
	v_mul_f32_e32 v237, 0x3fb8aa3b, v237
	v_exp_f32_e32 v237, v237
	v_cndmask_b32_e64 v239, v84, v80, s[78:79]
	v_add_f32_e32 v240, v80, v84
	v_mul_f32_e32 v237, v239, v237
	v_cndmask_b32_e64 v237, v237, v240, s[86:87]
	v_mul_f32_e32 v245, v100, v237
	v_cndmask_b32_e64 v237, v93, v89, s[80:81]
	v_cndmask_b32_e64 v238, v159, v158, s[80:81]
	v_sub_f32_e32 v237, v238, v237
	v_min_f32_e32 v237, 0, v237
	v_mul_f32_e32 v237, 0x3fb8aa3b, v237
	v_exp_f32_e32 v237, v237
	v_cndmask_b32_e64 v239, v85, v81, s[80:81]
	v_add_f32_e32 v240, v81, v85
	v_mul_f32_e32 v237, v239, v237
	v_cndmask_b32_e64 v237, v237, v240, s[88:89]
	v_mul_f32_e32 v246, v101, v237
	v_cndmask_b32_e64 v237, v94, v90, s[82:83]
	v_cndmask_b32_e64 v238, v159, v158, s[82:83]
	v_sub_f32_e32 v237, v238, v237
	v_min_f32_e32 v237, 0, v237
	v_mul_f32_e32 v237, 0x3fb8aa3b, v237
	v_exp_f32_e32 v237, v237
	v_cndmask_b32_e64 v239, v86, v82, s[82:83]
	v_add_f32_e32 v240, v82, v86
	v_mul_f32_e32 v237, v239, v237
	v_cndmask_b32_e64 v237, v237, v240, s[90:91]
	v_mul_f32_e32 v247, v102, v237
	v_cndmask_b32_e64 v237, v95, v91, s[84:85]
	v_cndmask_b32_e64 v238, v159, v158, s[84:85]
	v_sub_f32_e32 v237, v238, v237
	v_min_f32_e32 v237, 0, v237
	v_mul_f32_e32 v237, 0x3fb8aa3b, v237
	v_exp_f32_e32 v237, v237
	v_cndmask_b32_e64 v239, v87, v83, s[84:85]
	v_add_f32_e32 v240, v83, v87
	v_mul_f32_e32 v237, v239, v237
	v_cndmask_b32_e64 v237, v237, v240, s[92:93]
	v_mul_f32_e32 v248, v103, v237
	v_cvt_pk_bf16_f32 v104, v241, v242
	v_cvt_pk_bf16_f32 v105, v243, v244
	v_cvt_pk_bf16_f32 v106, v245, v246
	v_cvt_pk_bf16_f32 v107, v247, v248
	s_waitcnt lgkmcnt(0)
	s_nop 1
	v_mfma_f32_16x16x32_bf16 v[32:35], v[104:107], v[108:111], v[32:35]
	v_mfma_f32_16x16x32_bf16 v[36:39], v[104:107], v[112:115], v[36:39]
	v_mfma_f32_16x16x32_bf16 v[40:43], v[104:107], v[116:119], v[40:43]
	v_mfma_f32_16x16x32_bf16 v[44:47], v[104:107], v[120:123], v[44:47]
	ds_read_b128 v[108:111], v170 offset:0
	ds_read_b128 v[112:115], v170 offset:4352
	ds_read_b128 v[116:119], v170 offset:8704
	ds_read_b128 v[120:123], v170 offset:13056
	ds_read_b128 v[64:67], v170 offset:64
	ds_read_b128 v[68:71], v170 offset:4416
	ds_read_b128 v[72:75], v170 offset:8768
	ds_read_b128 v[76:79], v170 offset:13120
	v_mul_f32_e32 v236, 0x3fb8aa3b, v156
	v_exp_f32_e32 v236, v236
	s_nop 0
	v_lshlrev_b32_e32 v237, 16, v48
	v_and_b32_e32 v238, 0xffff0000, v48
	v_mul_f32_e32 v237, v236, v237
	v_mul_f32_e32 v238, v236, v238
	v_cvt_pk_bf16_f32 v104, v237, v238
	v_lshlrev_b32_e32 v237, 16, v49
	v_and_b32_e32 v238, 0xffff0000, v49
	v_mul_f32_e32 v237, v236, v237
	v_mul_f32_e32 v238, v236, v238
	v_cvt_pk_bf16_f32 v105, v237, v238
	v_lshlrev_b32_e32 v237, 16, v50
	v_and_b32_e32 v238, 0xffff0000, v50
	v_mul_f32_e32 v237, v236, v237
	v_mul_f32_e32 v238, v236, v238
	v_cvt_pk_bf16_f32 v106, v237, v238
	v_lshlrev_b32_e32 v237, 16, v51
	v_and_b32_e32 v238, 0xffff0000, v51
	v_mul_f32_e32 v237, v236, v237
	v_mul_f32_e32 v238, v236, v238
	v_cvt_pk_bf16_f32 v107, v237, v238
	s_waitcnt lgkmcnt(4)
	s_nop 0
	v_mfma_f32_16x16x32_bf16 v[16:19], v[104:107], v[108:111], v[16:19]
	v_mfma_f32_16x16x32_bf16 v[20:23], v[104:107], v[112:115], v[20:23]
	v_mfma_f32_16x16x32_bf16 v[24:27], v[104:107], v[116:119], v[24:27]
	v_mfma_f32_16x16x32_bf16 v[28:31], v[104:107], v[120:123], v[28:31]
	ds_read_b128 v[108:111], v170 offset:128
	ds_read_b128 v[112:115], v170 offset:4480
	ds_read_b128 v[116:119], v170 offset:8832
	ds_read_b128 v[120:123], v170 offset:13184
	v_lshlrev_b32_e32 v237, 16, v52
	v_and_b32_e32 v238, 0xffff0000, v52
	v_mul_f32_e32 v237, v236, v237
	v_mul_f32_e32 v238, v236, v238
	v_cvt_pk_bf16_f32 v104, v237, v238
	v_lshlrev_b32_e32 v237, 16, v53
	v_and_b32_e32 v238, 0xffff0000, v53
	v_mul_f32_e32 v237, v236, v237
	v_mul_f32_e32 v238, v236, v238
	v_cvt_pk_bf16_f32 v105, v237, v238
	v_lshlrev_b32_e32 v237, 16, v54
	v_and_b32_e32 v238, 0xffff0000, v54
	v_mul_f32_e32 v237, v236, v237
	v_mul_f32_e32 v238, v236, v238
	v_cvt_pk_bf16_f32 v106, v237, v238
	v_lshlrev_b32_e32 v237, 16, v55
	v_and_b32_e32 v238, 0xffff0000, v55
	v_mul_f32_e32 v237, v236, v237
	v_mul_f32_e32 v238, v236, v238
	v_cvt_pk_bf16_f32 v107, v237, v238
	s_waitcnt lgkmcnt(4)
	s_nop 0
	v_mfma_f32_16x16x32_bf16 v[16:19], v[104:107], v[64:67], v[16:19]
	v_mfma_f32_16x16x32_bf16 v[20:23], v[104:107], v[68:71], v[20:23]
	v_mfma_f32_16x16x32_bf16 v[24:27], v[104:107], v[72:75], v[24:27]
	v_mfma_f32_16x16x32_bf16 v[28:31], v[104:107], v[76:79], v[28:31]
	ds_read_b128 v[64:67], v170 offset:192
	ds_read_b128 v[68:71], v170 offset:4544
	ds_read_b128 v[72:75], v170 offset:8896
	ds_read_b128 v[76:79], v170 offset:13248
	v_lshlrev_b32_e32 v237, 16, v56
	v_and_b32_e32 v238, 0xffff0000, v56
	v_mul_f32_e32 v237, v236, v237
	v_mul_f32_e32 v238, v236, v238
	v_cvt_pk_bf16_f32 v104, v237, v238
	v_lshlrev_b32_e32 v237, 16, v57
	v_and_b32_e32 v238, 0xffff0000, v57
	v_mul_f32_e32 v237, v236, v237
	v_mul_f32_e32 v238, v236, v238
	v_cvt_pk_bf16_f32 v105, v237, v238
	v_lshlrev_b32_e32 v237, 16, v58
	v_and_b32_e32 v238, 0xffff0000, v58
	v_mul_f32_e32 v237, v236, v237
	v_mul_f32_e32 v238, v236, v238
	v_cvt_pk_bf16_f32 v106, v237, v238
	v_lshlrev_b32_e32 v237, 16, v59
	v_and_b32_e32 v238, 0xffff0000, v59
	v_mul_f32_e32 v237, v236, v237
	v_mul_f32_e32 v238, v236, v238
	v_cvt_pk_bf16_f32 v107, v237, v238
	s_waitcnt lgkmcnt(4)
	s_nop 0
	v_mfma_f32_16x16x32_bf16 v[16:19], v[104:107], v[108:111], v[16:19]
	v_mfma_f32_16x16x32_bf16 v[20:23], v[104:107], v[112:115], v[20:23]
	v_mfma_f32_16x16x32_bf16 v[24:27], v[104:107], v[116:119], v[24:27]
	v_mfma_f32_16x16x32_bf16 v[28:31], v[104:107], v[120:123], v[28:31]
	ds_read_b128 v[108:111], v170 offset:17408
	ds_read_b128 v[112:115], v170 offset:21760
	ds_read_b128 v[116:119], v170 offset:26112
	ds_read_b128 v[120:123], v170 offset:30464
	v_lshlrev_b32_e32 v237, 16, v60
	v_and_b32_e32 v238, 0xffff0000, v60
	v_mul_f32_e32 v237, v236, v237
	v_mul_f32_e32 v238, v236, v238
	v_cvt_pk_bf16_f32 v104, v237, v238
	v_lshlrev_b32_e32 v237, 16, v61
	v_and_b32_e32 v238, 0xffff0000, v61
	v_mul_f32_e32 v237, v236, v237
	v_mul_f32_e32 v238, v236, v238
	v_cvt_pk_bf16_f32 v105, v237, v238
	v_lshlrev_b32_e32 v237, 16, v62
	v_and_b32_e32 v238, 0xffff0000, v62
	v_mul_f32_e32 v237, v236, v237
	v_mul_f32_e32 v238, v236, v238
	v_cvt_pk_bf16_f32 v106, v237, v238
	v_lshlrev_b32_e32 v237, 16, v63
	v_and_b32_e32 v238, 0xffff0000, v63
	v_mul_f32_e32 v237, v236, v237
	v_mul_f32_e32 v238, v236, v238
	v_cvt_pk_bf16_f32 v107, v237, v238
	s_waitcnt lgkmcnt(4)
	s_nop 0
	v_mfma_f32_16x16x32_bf16 v[16:19], v[104:107], v[64:67], v[16:19]
	v_mfma_f32_16x16x32_bf16 v[20:23], v[104:107], v[68:71], v[20:23]
	v_mfma_f32_16x16x32_bf16 v[24:27], v[104:107], v[72:75], v[24:27]
	v_mfma_f32_16x16x32_bf16 v[28:31], v[104:107], v[76:79], v[28:31]
	ds_read_b128 v[64:67], v170 offset:17472
	ds_read_b128 v[68:71], v170 offset:21824
	ds_read_b128 v[72:75], v170 offset:26176
	ds_read_b128 v[76:79], v170 offset:30528
	v_mul_f32_e32 v236, 0x3fb8aa3b, v157
	v_exp_f32_e32 v236, v236
	s_nop 0
	v_lshlrev_b32_e32 v237, 16, v48
	v_and_b32_e32 v238, 0xffff0000, v48
	v_mul_f32_e32 v237, v236, v237
	v_mul_f32_e32 v238, v236, v238
	v_cvt_pk_bf16_f32 v104, v237, v238
	v_lshlrev_b32_e32 v237, 16, v49
	v_and_b32_e32 v238, 0xffff0000, v49
	v_mul_f32_e32 v237, v236, v237
	v_mul_f32_e32 v238, v236, v238
	v_cvt_pk_bf16_f32 v105, v237, v238
	v_lshlrev_b32_e32 v237, 16, v50
	v_and_b32_e32 v238, 0xffff0000, v50
	v_mul_f32_e32 v237, v236, v237
	v_mul_f32_e32 v238, v236, v238
	v_cvt_pk_bf16_f32 v106, v237, v238
	v_lshlrev_b32_e32 v237, 16, v51
	v_and_b32_e32 v238, 0xffff0000, v51
	v_mul_f32_e32 v237, v236, v237
	v_mul_f32_e32 v238, v236, v238
	v_cvt_pk_bf16_f32 v107, v237, v238
	s_waitcnt lgkmcnt(4)
	s_nop 0
	v_mfma_f32_16x16x32_bf16 v[16:19], v[104:107], v[108:111], v[16:19]
	v_mfma_f32_16x16x32_bf16 v[20:23], v[104:107], v[112:115], v[20:23]
	v_mfma_f32_16x16x32_bf16 v[24:27], v[104:107], v[116:119], v[24:27]
	v_mfma_f32_16x16x32_bf16 v[28:31], v[104:107], v[120:123], v[28:31]
	ds_read_b128 v[108:111], v170 offset:17536
	ds_read_b128 v[112:115], v170 offset:21888
	ds_read_b128 v[116:119], v170 offset:26240
	ds_read_b128 v[120:123], v170 offset:30592
	v_lshlrev_b32_e32 v237, 16, v52
	v_and_b32_e32 v238, 0xffff0000, v52
	v_mul_f32_e32 v237, v236, v237
	v_mul_f32_e32 v238, v236, v238
	v_cvt_pk_bf16_f32 v104, v237, v238
	v_lshlrev_b32_e32 v237, 16, v53
	v_and_b32_e32 v238, 0xffff0000, v53
	v_mul_f32_e32 v237, v236, v237
	v_mul_f32_e32 v238, v236, v238
	v_cvt_pk_bf16_f32 v105, v237, v238
	v_lshlrev_b32_e32 v237, 16, v54
	v_and_b32_e32 v238, 0xffff0000, v54
	v_mul_f32_e32 v237, v236, v237
	v_mul_f32_e32 v238, v236, v238
	v_cvt_pk_bf16_f32 v106, v237, v238
	v_lshlrev_b32_e32 v237, 16, v55
	v_and_b32_e32 v238, 0xffff0000, v55
	v_mul_f32_e32 v237, v236, v237
	v_mul_f32_e32 v238, v236, v238
	v_cvt_pk_bf16_f32 v107, v237, v238
	s_waitcnt lgkmcnt(4)
	s_nop 0
	v_mfma_f32_16x16x32_bf16 v[16:19], v[104:107], v[64:67], v[16:19]
	v_mfma_f32_16x16x32_bf16 v[20:23], v[104:107], v[68:71], v[20:23]
	v_mfma_f32_16x16x32_bf16 v[24:27], v[104:107], v[72:75], v[24:27]
	v_mfma_f32_16x16x32_bf16 v[28:31], v[104:107], v[76:79], v[28:31]
	ds_read_b128 v[64:67], v170 offset:17600
	ds_read_b128 v[68:71], v170 offset:21952
	ds_read_b128 v[72:75], v170 offset:26304
	ds_read_b128 v[76:79], v170 offset:30656
	v_lshlrev_b32_e32 v237, 16, v56
	v_and_b32_e32 v238, 0xffff0000, v56
	v_mul_f32_e32 v237, v236, v237
	v_mul_f32_e32 v238, v236, v238
	v_cvt_pk_bf16_f32 v104, v237, v238
	v_lshlrev_b32_e32 v237, 16, v57
	v_and_b32_e32 v238, 0xffff0000, v57
	v_mul_f32_e32 v237, v236, v237
	v_mul_f32_e32 v238, v236, v238
	v_cvt_pk_bf16_f32 v105, v237, v238
	v_lshlrev_b32_e32 v237, 16, v58
	v_and_b32_e32 v238, 0xffff0000, v58
	v_mul_f32_e32 v237, v236, v237
	v_mul_f32_e32 v238, v236, v238
	v_cvt_pk_bf16_f32 v106, v237, v238
	v_lshlrev_b32_e32 v237, 16, v59
	v_and_b32_e32 v238, 0xffff0000, v59
	v_mul_f32_e32 v237, v236, v237
	v_mul_f32_e32 v238, v236, v238
	v_cvt_pk_bf16_f32 v107, v237, v238
	s_waitcnt lgkmcnt(4)
	s_nop 0
	v_mfma_f32_16x16x32_bf16 v[16:19], v[104:107], v[108:111], v[16:19]
	v_mfma_f32_16x16x32_bf16 v[20:23], v[104:107], v[112:115], v[20:23]
	v_mfma_f32_16x16x32_bf16 v[24:27], v[104:107], v[116:119], v[24:27]
	v_mfma_f32_16x16x32_bf16 v[28:31], v[104:107], v[120:123], v[28:31]
	v_lshlrev_b32_e32 v237, 16, v60
	v_and_b32_e32 v238, 0xffff0000, v60
	v_mul_f32_e32 v237, v236, v237
	v_mul_f32_e32 v238, v236, v238
	v_cvt_pk_bf16_f32 v104, v237, v238
	v_lshlrev_b32_e32 v237, 16, v61
	v_and_b32_e32 v238, 0xffff0000, v61
	v_mul_f32_e32 v237, v236, v237
	v_mul_f32_e32 v238, v236, v238
	v_cvt_pk_bf16_f32 v105, v237, v238
	v_lshlrev_b32_e32 v237, 16, v62
	v_and_b32_e32 v238, 0xffff0000, v62
	v_mul_f32_e32 v237, v236, v237
	v_mul_f32_e32 v238, v236, v238
	v_cvt_pk_bf16_f32 v106, v237, v238
	v_lshlrev_b32_e32 v237, 16, v63
	v_and_b32_e32 v238, 0xffff0000, v63
	v_mul_f32_e32 v237, v236, v237
	v_mul_f32_e32 v238, v236, v238
	v_cvt_pk_bf16_f32 v107, v237, v238
	s_waitcnt lgkmcnt(0)
	s_nop 0
	v_mfma_f32_16x16x32_bf16 v[16:19], v[104:107], v[64:67], v[16:19]
	v_mfma_f32_16x16x32_bf16 v[20:23], v[104:107], v[68:71], v[20:23]
	v_mfma_f32_16x16x32_bf16 v[24:27], v[104:107], v[72:75], v[24:27]
	v_mfma_f32_16x16x32_bf16 v[28:31], v[104:107], v[76:79], v[28:31]
	s_waitcnt lgkmcnt(0)
	s_barrier
	s_waitcnt vmcnt(0)
	ds_write_b128 v5, v[124:127]
	ds_write_b128 v5, v[128:131] offset:8704
	ds_write_b128 v5, v[132:135] offset:17408
	ds_write_b128 v5, v[136:139] offset:26112
	s_waitcnt lgkmcnt(0)
	s_barrier
	ds_read_b128 v[108:111], v170 offset:0
	ds_read_b128 v[112:115], v170 offset:4352
	ds_read_b128 v[116:119], v170 offset:8704
	ds_read_b128 v[120:123], v170 offset:13056
	ds_read_b128 v[64:67], v170 offset:64
	ds_read_b128 v[68:71], v170 offset:4416
	ds_read_b128 v[72:75], v170 offset:8768
	ds_read_b128 v[76:79], v170 offset:13120
	v_mul_f32_e32 v236, 0x3fb8aa3b, v158
	v_exp_f32_e32 v236, v236
	s_nop 0
	v_lshlrev_b32_e32 v237, 16, v48
	v_and_b32_e32 v238, 0xffff0000, v48
	v_mul_f32_e32 v237, v236, v237
	v_mul_f32_e32 v238, v236, v238
	v_cvt_pk_bf16_f32 v104, v237, v238
	v_lshlrev_b32_e32 v237, 16, v49
	v_and_b32_e32 v238, 0xffff0000, v49
	v_mul_f32_e32 v237, v236, v237
	v_mul_f32_e32 v238, v236, v238
	v_cvt_pk_bf16_f32 v105, v237, v238
	v_lshlrev_b32_e32 v237, 16, v50
	v_and_b32_e32 v238, 0xffff0000, v50
	v_mul_f32_e32 v237, v236, v237
	v_mul_f32_e32 v238, v236, v238
	v_cvt_pk_bf16_f32 v106, v237, v238
	v_lshlrev_b32_e32 v237, 16, v51
	v_and_b32_e32 v238, 0xffff0000, v51
	v_mul_f32_e32 v237, v236, v237
	v_mul_f32_e32 v238, v236, v238
	v_cvt_pk_bf16_f32 v107, v237, v238
	s_waitcnt lgkmcnt(4)
	s_nop 0
	v_mfma_f32_16x16x32_bf16 v[32:35], v[104:107], v[108:111], v[32:35]
	v_mfma_f32_16x16x32_bf16 v[36:39], v[104:107], v[112:115], v[36:39]
	v_mfma_f32_16x16x32_bf16 v[40:43], v[104:107], v[116:119], v[40:43]
	v_mfma_f32_16x16x32_bf16 v[44:47], v[104:107], v[120:123], v[44:47]
	ds_read_b128 v[108:111], v170 offset:128
	ds_read_b128 v[112:115], v170 offset:4480
	ds_read_b128 v[116:119], v170 offset:8832
	ds_read_b128 v[120:123], v170 offset:13184
	v_lshlrev_b32_e32 v237, 16, v52
	v_and_b32_e32 v238, 0xffff0000, v52
	v_mul_f32_e32 v237, v236, v237
	v_mul_f32_e32 v238, v236, v238
	v_cvt_pk_bf16_f32 v104, v237, v238
	v_lshlrev_b32_e32 v237, 16, v53
	v_and_b32_e32 v238, 0xffff0000, v53
	v_mul_f32_e32 v237, v236, v237
	v_mul_f32_e32 v238, v236, v238
	v_cvt_pk_bf16_f32 v105, v237, v238
	v_lshlrev_b32_e32 v237, 16, v54
	v_and_b32_e32 v238, 0xffff0000, v54
	v_mul_f32_e32 v237, v236, v237
	v_mul_f32_e32 v238, v236, v238
	v_cvt_pk_bf16_f32 v106, v237, v238
	v_lshlrev_b32_e32 v237, 16, v55
	v_and_b32_e32 v238, 0xffff0000, v55
	v_mul_f32_e32 v237, v236, v237
	v_mul_f32_e32 v238, v236, v238
	v_cvt_pk_bf16_f32 v107, v237, v238
	s_waitcnt lgkmcnt(4)
	s_nop 0
	v_mfma_f32_16x16x32_bf16 v[32:35], v[104:107], v[64:67], v[32:35]
	v_mfma_f32_16x16x32_bf16 v[36:39], v[104:107], v[68:71], v[36:39]
	v_mfma_f32_16x16x32_bf16 v[40:43], v[104:107], v[72:75], v[40:43]
	v_mfma_f32_16x16x32_bf16 v[44:47], v[104:107], v[76:79], v[44:47]
	ds_read_b128 v[64:67], v170 offset:192
	ds_read_b128 v[68:71], v170 offset:4544
	ds_read_b128 v[72:75], v170 offset:8896
	ds_read_b128 v[76:79], v170 offset:13248
	v_lshlrev_b32_e32 v237, 16, v56
	v_and_b32_e32 v238, 0xffff0000, v56
	v_mul_f32_e32 v237, v236, v237
	v_mul_f32_e32 v238, v236, v238
	v_cvt_pk_bf16_f32 v104, v237, v238
	v_lshlrev_b32_e32 v237, 16, v57
	v_and_b32_e32 v238, 0xffff0000, v57
	v_mul_f32_e32 v237, v236, v237
	v_mul_f32_e32 v238, v236, v238
	v_cvt_pk_bf16_f32 v105, v237, v238
	v_lshlrev_b32_e32 v237, 16, v58
	v_and_b32_e32 v238, 0xffff0000, v58
	v_mul_f32_e32 v237, v236, v237
	v_mul_f32_e32 v238, v236, v238
	v_cvt_pk_bf16_f32 v106, v237, v238
	v_lshlrev_b32_e32 v237, 16, v59
	v_and_b32_e32 v238, 0xffff0000, v59
	v_mul_f32_e32 v237, v236, v237
	v_mul_f32_e32 v238, v236, v238
	v_cvt_pk_bf16_f32 v107, v237, v238
	s_waitcnt lgkmcnt(4)
	s_nop 0
	v_mfma_f32_16x16x32_bf16 v[32:35], v[104:107], v[108:111], v[32:35]
	v_mfma_f32_16x16x32_bf16 v[36:39], v[104:107], v[112:115], v[36:39]
	v_mfma_f32_16x16x32_bf16 v[40:43], v[104:107], v[116:119], v[40:43]
	v_mfma_f32_16x16x32_bf16 v[44:47], v[104:107], v[120:123], v[44:47]
	ds_read_b128 v[108:111], v170 offset:17408
	ds_read_b128 v[112:115], v170 offset:21760
	ds_read_b128 v[116:119], v170 offset:26112
	ds_read_b128 v[120:123], v170 offset:30464
	v_lshlrev_b32_e32 v237, 16, v60
	v_and_b32_e32 v238, 0xffff0000, v60
	v_mul_f32_e32 v237, v236, v237
	v_mul_f32_e32 v238, v236, v238
	v_cvt_pk_bf16_f32 v104, v237, v238
	v_lshlrev_b32_e32 v237, 16, v61
	v_and_b32_e32 v238, 0xffff0000, v61
	v_mul_f32_e32 v237, v236, v237
	v_mul_f32_e32 v238, v236, v238
	v_cvt_pk_bf16_f32 v105, v237, v238
	v_lshlrev_b32_e32 v237, 16, v62
	v_and_b32_e32 v238, 0xffff0000, v62
	v_mul_f32_e32 v237, v236, v237
	v_mul_f32_e32 v238, v236, v238
	v_cvt_pk_bf16_f32 v106, v237, v238
	v_lshlrev_b32_e32 v237, 16, v63
	v_and_b32_e32 v238, 0xffff0000, v63
	v_mul_f32_e32 v237, v236, v237
	v_mul_f32_e32 v238, v236, v238
	v_cvt_pk_bf16_f32 v107, v237, v238
	s_waitcnt lgkmcnt(4)
	s_nop 0
	v_mfma_f32_16x16x32_bf16 v[32:35], v[104:107], v[64:67], v[32:35]
	v_mfma_f32_16x16x32_bf16 v[36:39], v[104:107], v[68:71], v[36:39]
	v_mfma_f32_16x16x32_bf16 v[40:43], v[104:107], v[72:75], v[40:43]
	v_mfma_f32_16x16x32_bf16 v[44:47], v[104:107], v[76:79], v[44:47]
	ds_read_b128 v[64:67], v170 offset:17472
	ds_read_b128 v[68:71], v170 offset:21824
	ds_read_b128 v[72:75], v170 offset:26176
	ds_read_b128 v[76:79], v170 offset:30528
	v_mul_f32_e32 v236, 0x3fb8aa3b, v159
	v_exp_f32_e32 v236, v236
	s_nop 0
	v_lshlrev_b32_e32 v237, 16, v48
	v_and_b32_e32 v238, 0xffff0000, v48
	v_mul_f32_e32 v237, v236, v237
	v_mul_f32_e32 v238, v236, v238
	v_cvt_pk_bf16_f32 v104, v237, v238
	v_lshlrev_b32_e32 v237, 16, v49
	v_and_b32_e32 v238, 0xffff0000, v49
	v_mul_f32_e32 v237, v236, v237
	v_mul_f32_e32 v238, v236, v238
	v_cvt_pk_bf16_f32 v105, v237, v238
	v_lshlrev_b32_e32 v237, 16, v50
	v_and_b32_e32 v238, 0xffff0000, v50
	v_mul_f32_e32 v237, v236, v237
	v_mul_f32_e32 v238, v236, v238
	v_cvt_pk_bf16_f32 v106, v237, v238
	v_lshlrev_b32_e32 v237, 16, v51
	v_and_b32_e32 v238, 0xffff0000, v51
	v_mul_f32_e32 v237, v236, v237
	v_mul_f32_e32 v238, v236, v238
	v_cvt_pk_bf16_f32 v107, v237, v238
	s_waitcnt lgkmcnt(4)
	s_nop 0
	v_mfma_f32_16x16x32_bf16 v[32:35], v[104:107], v[108:111], v[32:35]
	v_mfma_f32_16x16x32_bf16 v[36:39], v[104:107], v[112:115], v[36:39]
	v_mfma_f32_16x16x32_bf16 v[40:43], v[104:107], v[116:119], v[40:43]
	v_mfma_f32_16x16x32_bf16 v[44:47], v[104:107], v[120:123], v[44:47]
	ds_read_b128 v[108:111], v170 offset:17536
	ds_read_b128 v[112:115], v170 offset:21888
	ds_read_b128 v[116:119], v170 offset:26240
	ds_read_b128 v[120:123], v170 offset:30592
	v_lshlrev_b32_e32 v237, 16, v52
	v_and_b32_e32 v238, 0xffff0000, v52
	v_mul_f32_e32 v237, v236, v237
	v_mul_f32_e32 v238, v236, v238
	v_cvt_pk_bf16_f32 v104, v237, v238
	v_lshlrev_b32_e32 v237, 16, v53
	v_and_b32_e32 v238, 0xffff0000, v53
	v_mul_f32_e32 v237, v236, v237
	v_mul_f32_e32 v238, v236, v238
	v_cvt_pk_bf16_f32 v105, v237, v238
	v_lshlrev_b32_e32 v237, 16, v54
	v_and_b32_e32 v238, 0xffff0000, v54
	v_mul_f32_e32 v237, v236, v237
	v_mul_f32_e32 v238, v236, v238
	v_cvt_pk_bf16_f32 v106, v237, v238
	v_lshlrev_b32_e32 v237, 16, v55
	v_and_b32_e32 v238, 0xffff0000, v55
	v_mul_f32_e32 v237, v236, v237
	v_mul_f32_e32 v238, v236, v238
	v_cvt_pk_bf16_f32 v107, v237, v238
	s_waitcnt lgkmcnt(4)
	s_nop 0
	v_mfma_f32_16x16x32_bf16 v[32:35], v[104:107], v[64:67], v[32:35]
	v_mfma_f32_16x16x32_bf16 v[36:39], v[104:107], v[68:71], v[36:39]
	v_mfma_f32_16x16x32_bf16 v[40:43], v[104:107], v[72:75], v[40:43]
	v_mfma_f32_16x16x32_bf16 v[44:47], v[104:107], v[76:79], v[44:47]
	ds_read_b128 v[64:67], v170 offset:17600
	ds_read_b128 v[68:71], v170 offset:21952
	ds_read_b128 v[72:75], v170 offset:26304
	ds_read_b128 v[76:79], v170 offset:30656
	v_lshlrev_b32_e32 v237, 16, v56
	v_and_b32_e32 v238, 0xffff0000, v56
	v_mul_f32_e32 v237, v236, v237
	v_mul_f32_e32 v238, v236, v238
	v_cvt_pk_bf16_f32 v104, v237, v238
	v_lshlrev_b32_e32 v237, 16, v57
	v_and_b32_e32 v238, 0xffff0000, v57
	v_mul_f32_e32 v237, v236, v237
	v_mul_f32_e32 v238, v236, v238
	v_cvt_pk_bf16_f32 v105, v237, v238
	v_lshlrev_b32_e32 v237, 16, v58
	v_and_b32_e32 v238, 0xffff0000, v58
	v_mul_f32_e32 v237, v236, v237
	v_mul_f32_e32 v238, v236, v238
	v_cvt_pk_bf16_f32 v106, v237, v238
	v_lshlrev_b32_e32 v237, 16, v59
	v_and_b32_e32 v238, 0xffff0000, v59
	v_mul_f32_e32 v237, v236, v237
	v_mul_f32_e32 v238, v236, v238
	v_cvt_pk_bf16_f32 v107, v237, v238
	s_waitcnt lgkmcnt(4)
	s_nop 0
	v_mfma_f32_16x16x32_bf16 v[32:35], v[104:107], v[108:111], v[32:35]
	v_mfma_f32_16x16x32_bf16 v[36:39], v[104:107], v[112:115], v[36:39]
	v_mfma_f32_16x16x32_bf16 v[40:43], v[104:107], v[116:119], v[40:43]
	v_mfma_f32_16x16x32_bf16 v[44:47], v[104:107], v[120:123], v[44:47]
	v_lshlrev_b32_e32 v237, 16, v60
	v_and_b32_e32 v238, 0xffff0000, v60
	v_mul_f32_e32 v237, v236, v237
	v_mul_f32_e32 v238, v236, v238
	v_cvt_pk_bf16_f32 v104, v237, v238
	v_lshlrev_b32_e32 v237, 16, v61
	v_and_b32_e32 v238, 0xffff0000, v61
	v_mul_f32_e32 v237, v236, v237
	v_mul_f32_e32 v238, v236, v238
	v_cvt_pk_bf16_f32 v105, v237, v238
	v_lshlrev_b32_e32 v237, 16, v62
	v_and_b32_e32 v238, 0xffff0000, v62
	v_mul_f32_e32 v237, v236, v237
	v_mul_f32_e32 v238, v236, v238
	v_cvt_pk_bf16_f32 v106, v237, v238
	v_lshlrev_b32_e32 v237, 16, v63
	v_and_b32_e32 v238, 0xffff0000, v63
	v_mul_f32_e32 v237, v236, v237
	v_mul_f32_e32 v238, v236, v238
	v_cvt_pk_bf16_f32 v107, v237, v238
	s_waitcnt lgkmcnt(0)
	s_nop 0
	v_mfma_f32_16x16x32_bf16 v[32:35], v[104:107], v[64:67], v[32:35]
	v_mfma_f32_16x16x32_bf16 v[36:39], v[104:107], v[68:71], v[36:39]
	v_mfma_f32_16x16x32_bf16 v[40:43], v[104:107], v[72:75], v[40:43]
	v_mfma_f32_16x16x32_bf16 v[44:47], v[104:107], v[76:79], v[44:47]
	s_mov_b32 s52, s40
	s_mov_b32 s53, s41
	global_load_dwordx4 v[64:67], v0, s[52:53] offset:256
	global_load_dwordx4 v[96:99], v0, s[52:53] offset:768
	s_add_u32 s52, s40, 0xc000
	s_addc_u32 s53, s41, 0
	global_load_dwordx4 v[68:71], v0, s[52:53] offset:256
	global_load_dwordx4 v[100:103], v0, s[52:53] offset:768
	s_add_u32 s52, s40, 0x18000
	s_addc_u32 s53, s41, 0
	global_load_dwordx4 v[72:75], v0, s[52:53] offset:256
	global_load_dwordx4 v[104:107], v0, s[52:53] offset:768
	s_add_u32 s52, s40, 0x24000
	s_addc_u32 s53, s41, 0
	global_load_dwordx4 v[76:79], v0, s[52:53] offset:256
	global_load_dwordx4 v[108:111], v0, s[52:53] offset:768
	s_mov_b32 s52, s44
	s_mov_b32 s53, s45
	global_load_dwordx4 v[80:83], v1, s[52:53] offset:256
	s_add_u32 s52, s44, 0x38000
	s_addc_u32 s53, s45, 0
	global_load_dwordx4 v[84:87], v1, s[52:53] offset:256
	s_add_u32 s52, s44, 0x70000
	s_addc_u32 s53, s45, 0
	global_load_dwordx4 v[88:91], v1, s[52:53] offset:256
	s_add_u32 s52, s44, 0xa8000
	s_addc_u32 s53, s45, 0
	global_load_dwordx4 v[92:95], v1, s[52:53] offset:256
	s_add_u32 s52, s42, 0x10000
	s_addc_u32 s53, s43, 0
	global_load_dwordx4 v[112:115], v2, s[52:53]
	s_add_u32 s52, s42, 0x12000
	s_addc_u32 s53, s43, 0
	global_load_dwordx4 v[116:119], v2, s[52:53]
	s_add_u32 s52, s42, 0x14000
	s_addc_u32 s53, s43, 0
	global_load_dwordx4 v[120:123], v2, s[52:53]
	s_add_u32 s52, s42, 0x16000
	s_addc_u32 s53, s43, 0
	global_load_dwordx4 v[124:127], v2, s[52:53]
	global_load_dwordx4 v[48:51], v177, s[40:41] offset:256
	global_load_dwordx4 v[52:55], v177, s[40:41] offset:320
	global_load_dwordx4 v[56:59], v177, s[40:41] offset:384
	global_load_dwordx4 v[60:63], v177, s[40:41] offset:448
	s_nop 7
	ds_read_b64_tr_b16 v[140:141], v174 offset:0
	ds_read_b64_tr_b16 v[148:149], v227 offset:0
	ds_read_b64_tr_b16 v[142:143], v174 offset:32
	ds_read_b64_tr_b16 v[150:151], v227 offset:32
	ds_read_b64_tr_b16 v[144:145], v174 offset:64
	ds_read_b64_tr_b16 v[152:153], v227 offset:64
	ds_read_b64_tr_b16 v[146:147], v174 offset:96
	ds_read_b64_tr_b16 v[154:155], v227 offset:96
	s_waitcnt lgkmcnt(6)
	v_lshlrev_b32_e32 v236, 16, v140
	v_lshlrev_b32_e32 v237, 16, v148
	v_fma_f32 v238, s60, v236, v16
	v_mul_f32_e32 v239, 0xbfb8aa3b, v237
	v_exp_f32_e32 v239, v239
	s_nop 0
	v_add_f32_e32 v239, 1.0, v239
	v_div_scale_f32 v240, s[0:1], v239, v239, v237
	v_rcp_f32_e32 v241, v240
	s_nop 0
	v_fma_f32 v242, -v240, v241, 1.0
	v_fmac_f32_e32 v241, v242, v241
	v_div_scale_f32 v242, vcc, v237, v239, v237
	v_mul_f32_e32 v243, v242, v241
	v_fma_f32 v244, -v240, v243, v242
	v_fmac_f32_e32 v243, v244, v241
	v_fma_f32 v240, -v240, v243, v242
	v_div_fmas_f32 v240, v240, v241, v243
	v_div_fixup_f32 v240, v240, v239, v237
	v_mul_f32_e32 v246, v238, v240
	v_fmac_f32_e32 v228, v246, v246
	v_and_b32_e32 v236, 0xffff0000, v140
	v_and_b32_e32 v237, 0xffff0000, v148
	v_fma_f32 v238, s60, v236, v17
	v_mul_f32_e32 v239, 0xbfb8aa3b, v237
	v_exp_f32_e32 v239, v239
	s_nop 0
	v_add_f32_e32 v239, 1.0, v239
	v_div_scale_f32 v240, s[0:1], v239, v239, v237
	v_rcp_f32_e32 v241, v240
	s_nop 0
	v_fma_f32 v242, -v240, v241, 1.0
	v_fmac_f32_e32 v241, v242, v241
	v_div_scale_f32 v242, vcc, v237, v239, v237
	v_mul_f32_e32 v243, v242, v241
	v_fma_f32 v244, -v240, v243, v242
	v_fmac_f32_e32 v243, v244, v241
	v_fma_f32 v240, -v240, v243, v242
	v_div_fmas_f32 v240, v240, v241, v243
	v_div_fixup_f32 v240, v240, v239, v237
	v_mul_f32_e32 v247, v238, v240
	v_fmac_f32_e32 v229, v247, v247
	v_lshlrev_b32_e32 v236, 16, v141
	v_lshlrev_b32_e32 v237, 16, v149
	v_fma_f32 v238, s60, v236, v18
	v_mul_f32_e32 v239, 0xbfb8aa3b, v237
	v_exp_f32_e32 v239, v239
	s_nop 0
	v_add_f32_e32 v239, 1.0, v239
	v_div_scale_f32 v240, s[0:1], v239, v239, v237
	v_rcp_f32_e32 v241, v240
	s_nop 0
	v_fma_f32 v242, -v240, v241, 1.0
	v_fmac_f32_e32 v241, v242, v241
	v_div_scale_f32 v242, vcc, v237, v239, v237
	v_mul_f32_e32 v243, v242, v241
	v_fma_f32 v244, -v240, v243, v242
	v_fmac_f32_e32 v243, v244, v241
	v_fma_f32 v240, -v240, v243, v242
	v_div_fmas_f32 v240, v240, v241, v243
	v_div_fixup_f32 v240, v240, v239, v237
	v_mul_f32_e32 v248, v238, v240
	v_fmac_f32_e32 v230, v248, v248
	v_and_b32_e32 v236, 0xffff0000, v141
	v_and_b32_e32 v237, 0xffff0000, v149
	v_fma_f32 v238, s60, v236, v19
	v_mul_f32_e32 v239, 0xbfb8aa3b, v237
	v_exp_f32_e32 v239, v239
	s_nop 0
	v_add_f32_e32 v239, 1.0, v239
	v_div_scale_f32 v240, s[0:1], v239, v239, v237
	v_rcp_f32_e32 v241, v240
	s_nop 0
	v_fma_f32 v242, -v240, v241, 1.0
	v_fmac_f32_e32 v241, v242, v241
	v_div_scale_f32 v242, vcc, v237, v239, v237
	v_mul_f32_e32 v243, v242, v241
	v_fma_f32 v244, -v240, v243, v242
	v_fmac_f32_e32 v243, v244, v241
	v_fma_f32 v240, -v240, v243, v242
	v_div_fmas_f32 v240, v240, v241, v243
	v_div_fixup_f32 v240, v240, v239, v237
	v_mul_f32_e32 v249, v238, v240
	v_fmac_f32_e32 v231, v249, v249
	v_cvt_pk_bf16_f32 v178, v246, v247
	v_cvt_pk_bf16_f32 v179, v248, v249
	s_waitcnt lgkmcnt(4)
	v_lshlrev_b32_e32 v236, 16, v142
	v_lshlrev_b32_e32 v237, 16, v150
	v_fma_f32 v238, s60, v236, v20
	v_mul_f32_e32 v239, 0xbfb8aa3b, v237
	v_exp_f32_e32 v239, v239
	s_nop 0
	v_add_f32_e32 v239, 1.0, v239
	v_div_scale_f32 v240, s[0:1], v239, v239, v237
	v_rcp_f32_e32 v241, v240
	s_nop 0
	v_fma_f32 v242, -v240, v241, 1.0
	v_fmac_f32_e32 v241, v242, v241
	v_div_scale_f32 v242, vcc, v237, v239, v237
	v_mul_f32_e32 v243, v242, v241
	v_fma_f32 v244, -v240, v243, v242
	v_fmac_f32_e32 v243, v244, v241
	v_fma_f32 v240, -v240, v243, v242
	v_div_fmas_f32 v240, v240, v241, v243
	v_div_fixup_f32 v240, v240, v239, v237
	v_mul_f32_e32 v246, v238, v240
	v_fmac_f32_e32 v228, v246, v246
	v_and_b32_e32 v236, 0xffff0000, v142
	v_and_b32_e32 v237, 0xffff0000, v150
	v_fma_f32 v238, s60, v236, v21
	v_mul_f32_e32 v239, 0xbfb8aa3b, v237
	v_exp_f32_e32 v239, v239
	s_nop 0
	v_add_f32_e32 v239, 1.0, v239
	v_div_scale_f32 v240, s[0:1], v239, v239, v237
	v_rcp_f32_e32 v241, v240
	s_nop 0
	v_fma_f32 v242, -v240, v241, 1.0
	v_fmac_f32_e32 v241, v242, v241
	v_div_scale_f32 v242, vcc, v237, v239, v237
	v_mul_f32_e32 v243, v242, v241
	v_fma_f32 v244, -v240, v243, v242
	v_fmac_f32_e32 v243, v244, v241
	v_fma_f32 v240, -v240, v243, v242
	v_div_fmas_f32 v240, v240, v241, v243
	v_div_fixup_f32 v240, v240, v239, v237
	v_mul_f32_e32 v247, v238, v240
	v_fmac_f32_e32 v229, v247, v247
	v_lshlrev_b32_e32 v236, 16, v143
	v_lshlrev_b32_e32 v237, 16, v151
	v_fma_f32 v238, s60, v236, v22
	v_mul_f32_e32 v239, 0xbfb8aa3b, v237
	v_exp_f32_e32 v239, v239
	s_nop 0
	v_add_f32_e32 v239, 1.0, v239
	v_div_scale_f32 v240, s[0:1], v239, v239, v237
	v_rcp_f32_e32 v241, v240
	s_nop 0
	v_fma_f32 v242, -v240, v241, 1.0
	v_fmac_f32_e32 v241, v242, v241
	v_div_scale_f32 v242, vcc, v237, v239, v237
	v_mul_f32_e32 v243, v242, v241
	v_fma_f32 v244, -v240, v243, v242
	v_fmac_f32_e32 v243, v244, v241
	v_fma_f32 v240, -v240, v243, v242
	v_div_fmas_f32 v240, v240, v241, v243
	v_div_fixup_f32 v240, v240, v239, v237
	v_mul_f32_e32 v248, v238, v240
	v_fmac_f32_e32 v230, v248, v248
	v_and_b32_e32 v236, 0xffff0000, v143
	v_and_b32_e32 v237, 0xffff0000, v151
	v_fma_f32 v238, s60, v236, v23
	v_mul_f32_e32 v239, 0xbfb8aa3b, v237
	v_exp_f32_e32 v239, v239
	s_nop 0
	v_add_f32_e32 v239, 1.0, v239
	v_div_scale_f32 v240, s[0:1], v239, v239, v237
	v_rcp_f32_e32 v241, v240
	s_nop 0
	v_fma_f32 v242, -v240, v241, 1.0
	v_fmac_f32_e32 v241, v242, v241
	v_div_scale_f32 v242, vcc, v237, v239, v237
	v_mul_f32_e32 v243, v242, v241
	v_fma_f32 v244, -v240, v243, v242
	v_fmac_f32_e32 v243, v244, v241
	v_fma_f32 v240, -v240, v243, v242
	v_div_fmas_f32 v240, v240, v241, v243
	v_div_fixup_f32 v240, v240, v239, v237
	v_mul_f32_e32 v249, v238, v240
	v_fmac_f32_e32 v231, v249, v249
	v_cvt_pk_bf16_f32 v180, v246, v247
	v_cvt_pk_bf16_f32 v181, v248, v249
	s_waitcnt lgkmcnt(2)
	v_lshlrev_b32_e32 v236, 16, v144
	v_lshlrev_b32_e32 v237, 16, v152
	v_fma_f32 v238, s60, v236, v24
	v_mul_f32_e32 v239, 0xbfb8aa3b, v237
	v_exp_f32_e32 v239, v239
	s_nop 0
	v_add_f32_e32 v239, 1.0, v239
	v_div_scale_f32 v240, s[0:1], v239, v239, v237
	v_rcp_f32_e32 v241, v240
	s_nop 0
	v_fma_f32 v242, -v240, v241, 1.0
	v_fmac_f32_e32 v241, v242, v241
	v_div_scale_f32 v242, vcc, v237, v239, v237
	v_mul_f32_e32 v243, v242, v241
	v_fma_f32 v244, -v240, v243, v242
	v_fmac_f32_e32 v243, v244, v241
	v_fma_f32 v240, -v240, v243, v242
	v_div_fmas_f32 v240, v240, v241, v243
	v_div_fixup_f32 v240, v240, v239, v237
	v_mul_f32_e32 v246, v238, v240
	v_fmac_f32_e32 v228, v246, v246
	v_and_b32_e32 v236, 0xffff0000, v144
	v_and_b32_e32 v237, 0xffff0000, v152
	v_fma_f32 v238, s60, v236, v25
	v_mul_f32_e32 v239, 0xbfb8aa3b, v237
	v_exp_f32_e32 v239, v239
	s_nop 0
	v_add_f32_e32 v239, 1.0, v239
	v_div_scale_f32 v240, s[0:1], v239, v239, v237
	v_rcp_f32_e32 v241, v240
	s_nop 0
	v_fma_f32 v242, -v240, v241, 1.0
	v_fmac_f32_e32 v241, v242, v241
	v_div_scale_f32 v242, vcc, v237, v239, v237
	v_mul_f32_e32 v243, v242, v241
	v_fma_f32 v244, -v240, v243, v242
	v_fmac_f32_e32 v243, v244, v241
	v_fma_f32 v240, -v240, v243, v242
	v_div_fmas_f32 v240, v240, v241, v243
	v_div_fixup_f32 v240, v240, v239, v237
	v_mul_f32_e32 v247, v238, v240
	v_fmac_f32_e32 v229, v247, v247
	v_lshlrev_b32_e32 v236, 16, v145
	v_lshlrev_b32_e32 v237, 16, v153
	v_fma_f32 v238, s60, v236, v26
	v_mul_f32_e32 v239, 0xbfb8aa3b, v237
	v_exp_f32_e32 v239, v239
	s_nop 0
	v_add_f32_e32 v239, 1.0, v239
	v_div_scale_f32 v240, s[0:1], v239, v239, v237
	v_rcp_f32_e32 v241, v240
	s_nop 0
	v_fma_f32 v242, -v240, v241, 1.0
	v_fmac_f32_e32 v241, v242, v241
	v_div_scale_f32 v242, vcc, v237, v239, v237
	v_mul_f32_e32 v243, v242, v241
	v_fma_f32 v244, -v240, v243, v242
	v_fmac_f32_e32 v243, v244, v241
	v_fma_f32 v240, -v240, v243, v242
	v_div_fmas_f32 v240, v240, v241, v243
	v_div_fixup_f32 v240, v240, v239, v237
	v_mul_f32_e32 v248, v238, v240
	v_fmac_f32_e32 v230, v248, v248
	v_and_b32_e32 v236, 0xffff0000, v145
	v_and_b32_e32 v237, 0xffff0000, v153
	v_fma_f32 v238, s60, v236, v27
	v_mul_f32_e32 v239, 0xbfb8aa3b, v237
	v_exp_f32_e32 v239, v239
	s_nop 0
	v_add_f32_e32 v239, 1.0, v239
	v_div_scale_f32 v240, s[0:1], v239, v239, v237
	v_rcp_f32_e32 v241, v240
	s_nop 0
	v_fma_f32 v242, -v240, v241, 1.0
	v_fmac_f32_e32 v241, v242, v241
	v_div_scale_f32 v242, vcc, v237, v239, v237
	v_mul_f32_e32 v243, v242, v241
	v_fma_f32 v244, -v240, v243, v242
	v_fmac_f32_e32 v243, v244, v241
	v_fma_f32 v240, -v240, v243, v242
	v_div_fmas_f32 v240, v240, v241, v243
	v_div_fixup_f32 v240, v240, v239, v237
	v_mul_f32_e32 v249, v238, v240
	v_fmac_f32_e32 v231, v249, v249
	v_cvt_pk_bf16_f32 v182, v246, v247
	v_cvt_pk_bf16_f32 v183, v248, v249
	s_waitcnt lgkmcnt(0)
	v_lshlrev_b32_e32 v236, 16, v146
	v_lshlrev_b32_e32 v237, 16, v154
	v_fma_f32 v238, s60, v236, v28
	v_mul_f32_e32 v239, 0xbfb8aa3b, v237
	v_exp_f32_e32 v239, v239
	s_nop 0
	v_add_f32_e32 v239, 1.0, v239
	v_div_scale_f32 v240, s[0:1], v239, v239, v237
	v_rcp_f32_e32 v241, v240
	s_nop 0
	v_fma_f32 v242, -v240, v241, 1.0
	v_fmac_f32_e32 v241, v242, v241
	v_div_scale_f32 v242, vcc, v237, v239, v237
	v_mul_f32_e32 v243, v242, v241
	v_fma_f32 v244, -v240, v243, v242
	v_fmac_f32_e32 v243, v244, v241
	v_fma_f32 v240, -v240, v243, v242
	v_div_fmas_f32 v240, v240, v241, v243
	v_div_fixup_f32 v240, v240, v239, v237
	v_mul_f32_e32 v246, v238, v240
	v_fmac_f32_e32 v228, v246, v246
	v_and_b32_e32 v236, 0xffff0000, v146
	v_and_b32_e32 v237, 0xffff0000, v154
	v_fma_f32 v238, s60, v236, v29
	v_mul_f32_e32 v239, 0xbfb8aa3b, v237
	v_exp_f32_e32 v239, v239
	s_nop 0
	v_add_f32_e32 v239, 1.0, v239
	v_div_scale_f32 v240, s[0:1], v239, v239, v237
	v_rcp_f32_e32 v241, v240
	s_nop 0
	v_fma_f32 v242, -v240, v241, 1.0
	v_fmac_f32_e32 v241, v242, v241
	v_div_scale_f32 v242, vcc, v237, v239, v237
	v_mul_f32_e32 v243, v242, v241
	v_fma_f32 v244, -v240, v243, v242
	v_fmac_f32_e32 v243, v244, v241
	v_fma_f32 v240, -v240, v243, v242
	v_div_fmas_f32 v240, v240, v241, v243
	v_div_fixup_f32 v240, v240, v239, v237
	v_mul_f32_e32 v247, v238, v240
	v_fmac_f32_e32 v229, v247, v247
	v_lshlrev_b32_e32 v236, 16, v147
	v_lshlrev_b32_e32 v237, 16, v155
	v_fma_f32 v238, s60, v236, v30
	v_mul_f32_e32 v239, 0xbfb8aa3b, v237
	v_exp_f32_e32 v239, v239
	s_nop 0
	v_add_f32_e32 v239, 1.0, v239
	v_div_scale_f32 v240, s[0:1], v239, v239, v237
	v_rcp_f32_e32 v241, v240
	s_nop 0
	v_fma_f32 v242, -v240, v241, 1.0
	v_fmac_f32_e32 v241, v242, v241
	v_div_scale_f32 v242, vcc, v237, v239, v237
	v_mul_f32_e32 v243, v242, v241
	v_fma_f32 v244, -v240, v243, v242
	v_fmac_f32_e32 v243, v244, v241
	v_fma_f32 v240, -v240, v243, v242
	v_div_fmas_f32 v240, v240, v241, v243
	v_div_fixup_f32 v240, v240, v239, v237
	v_mul_f32_e32 v248, v238, v240
	v_fmac_f32_e32 v230, v248, v248
	v_and_b32_e32 v236, 0xffff0000, v147
	v_and_b32_e32 v237, 0xffff0000, v155
	v_fma_f32 v238, s60, v236, v31
	v_mul_f32_e32 v239, 0xbfb8aa3b, v237
	v_exp_f32_e32 v239, v239
	s_nop 0
	v_add_f32_e32 v239, 1.0, v239
	v_div_scale_f32 v240, s[0:1], v239, v239, v237
	v_rcp_f32_e32 v241, v240
	s_nop 0
	v_fma_f32 v242, -v240, v241, 1.0
	v_fmac_f32_e32 v241, v242, v241
	v_div_scale_f32 v242, vcc, v237, v239, v237
	v_mul_f32_e32 v243, v242, v241
	v_fma_f32 v244, -v240, v243, v242
	v_fmac_f32_e32 v243, v244, v241
	v_fma_f32 v240, -v240, v243, v242
	v_div_fmas_f32 v240, v240, v241, v243
	v_div_fixup_f32 v240, v240, v239, v237
	v_mul_f32_e32 v249, v238, v240
	v_fmac_f32_e32 v231, v249, v249
	v_cvt_pk_bf16_f32 v184, v246, v247
	v_cvt_pk_bf16_f32 v185, v248, v249
	ds_read_b64_tr_b16 v[140:141], v174 offset:128
	ds_read_b64_tr_b16 v[148:149], v227 offset:128
	ds_read_b64_tr_b16 v[142:143], v174 offset:160
	ds_read_b64_tr_b16 v[150:151], v227 offset:160
	ds_read_b64_tr_b16 v[144:145], v174 offset:192
	ds_read_b64_tr_b16 v[152:153], v227 offset:192
	ds_read_b64_tr_b16 v[146:147], v174 offset:224
	ds_read_b64_tr_b16 v[154:155], v227 offset:224
	s_waitcnt lgkmcnt(6)
	v_lshlrev_b32_e32 v236, 16, v140
	v_lshlrev_b32_e32 v237, 16, v148
	v_fma_f32 v238, s61, v236, v32
	v_mul_f32_e32 v239, 0xbfb8aa3b, v237
	v_exp_f32_e32 v239, v239
	s_nop 0
	v_add_f32_e32 v239, 1.0, v239
	v_div_scale_f32 v240, s[0:1], v239, v239, v237
	v_rcp_f32_e32 v241, v240
	s_nop 0
	v_fma_f32 v242, -v240, v241, 1.0
	v_fmac_f32_e32 v241, v242, v241
	v_div_scale_f32 v242, vcc, v237, v239, v237
	v_mul_f32_e32 v243, v242, v241
	v_fma_f32 v244, -v240, v243, v242
	v_fmac_f32_e32 v243, v244, v241
	v_fma_f32 v240, -v240, v243, v242
	v_div_fmas_f32 v240, v240, v241, v243
	v_div_fixup_f32 v240, v240, v239, v237
	v_mul_f32_e32 v246, v238, v240
	v_fmac_f32_e32 v228, v246, v246
	v_and_b32_e32 v236, 0xffff0000, v140
	v_and_b32_e32 v237, 0xffff0000, v148
	v_fma_f32 v238, s61, v236, v33
	v_mul_f32_e32 v239, 0xbfb8aa3b, v237
	v_exp_f32_e32 v239, v239
	s_nop 0
	v_add_f32_e32 v239, 1.0, v239
	v_div_scale_f32 v240, s[0:1], v239, v239, v237
	v_rcp_f32_e32 v241, v240
	s_nop 0
	v_fma_f32 v242, -v240, v241, 1.0
	v_fmac_f32_e32 v241, v242, v241
	v_div_scale_f32 v242, vcc, v237, v239, v237
	v_mul_f32_e32 v243, v242, v241
	v_fma_f32 v244, -v240, v243, v242
	v_fmac_f32_e32 v243, v244, v241
	v_fma_f32 v240, -v240, v243, v242
	v_div_fmas_f32 v240, v240, v241, v243
	v_div_fixup_f32 v240, v240, v239, v237
	v_mul_f32_e32 v247, v238, v240
	v_fmac_f32_e32 v229, v247, v247
	v_lshlrev_b32_e32 v236, 16, v141
	v_lshlrev_b32_e32 v237, 16, v149
	v_fma_f32 v238, s61, v236, v34
	v_mul_f32_e32 v239, 0xbfb8aa3b, v237
	v_exp_f32_e32 v239, v239
	s_nop 0
	v_add_f32_e32 v239, 1.0, v239
	v_div_scale_f32 v240, s[0:1], v239, v239, v237
	v_rcp_f32_e32 v241, v240
	s_nop 0
	v_fma_f32 v242, -v240, v241, 1.0
	v_fmac_f32_e32 v241, v242, v241
	v_div_scale_f32 v242, vcc, v237, v239, v237
	v_mul_f32_e32 v243, v242, v241
	v_fma_f32 v244, -v240, v243, v242
	v_fmac_f32_e32 v243, v244, v241
	v_fma_f32 v240, -v240, v243, v242
	v_div_fmas_f32 v240, v240, v241, v243
	v_div_fixup_f32 v240, v240, v239, v237
	v_mul_f32_e32 v248, v238, v240
	v_fmac_f32_e32 v230, v248, v248
	v_and_b32_e32 v236, 0xffff0000, v141
	v_and_b32_e32 v237, 0xffff0000, v149
	v_fma_f32 v238, s61, v236, v35
	v_mul_f32_e32 v239, 0xbfb8aa3b, v237
	v_exp_f32_e32 v239, v239
	s_nop 0
	v_add_f32_e32 v239, 1.0, v239
	v_div_scale_f32 v240, s[0:1], v239, v239, v237
	v_rcp_f32_e32 v241, v240
	s_nop 0
	v_fma_f32 v242, -v240, v241, 1.0
	v_fmac_f32_e32 v241, v242, v241
	v_div_scale_f32 v242, vcc, v237, v239, v237
	v_mul_f32_e32 v243, v242, v241
	v_fma_f32 v244, -v240, v243, v242
	v_fmac_f32_e32 v243, v244, v241
	v_fma_f32 v240, -v240, v243, v242
	v_div_fmas_f32 v240, v240, v241, v243
	v_div_fixup_f32 v240, v240, v239, v237
	v_mul_f32_e32 v249, v238, v240
	v_fmac_f32_e32 v231, v249, v249
	v_cvt_pk_bf16_f32 v186, v246, v247
	v_cvt_pk_bf16_f32 v187, v248, v249
	s_waitcnt lgkmcnt(4)
	v_lshlrev_b32_e32 v236, 16, v142
	v_lshlrev_b32_e32 v237, 16, v150
	v_fma_f32 v238, s61, v236, v36
	v_mul_f32_e32 v239, 0xbfb8aa3b, v237
	v_exp_f32_e32 v239, v239
	s_nop 0
	v_add_f32_e32 v239, 1.0, v239
	v_div_scale_f32 v240, s[0:1], v239, v239, v237
	v_rcp_f32_e32 v241, v240
	s_nop 0
	v_fma_f32 v242, -v240, v241, 1.0
	v_fmac_f32_e32 v241, v242, v241
	v_div_scale_f32 v242, vcc, v237, v239, v237
	v_mul_f32_e32 v243, v242, v241
	v_fma_f32 v244, -v240, v243, v242
	v_fmac_f32_e32 v243, v244, v241
	v_fma_f32 v240, -v240, v243, v242
	v_div_fmas_f32 v240, v240, v241, v243
	v_div_fixup_f32 v240, v240, v239, v237
	v_mul_f32_e32 v246, v238, v240
	v_fmac_f32_e32 v228, v246, v246
	v_and_b32_e32 v236, 0xffff0000, v142
	v_and_b32_e32 v237, 0xffff0000, v150
	v_fma_f32 v238, s61, v236, v37
	v_mul_f32_e32 v239, 0xbfb8aa3b, v237
	v_exp_f32_e32 v239, v239
	s_nop 0
	v_add_f32_e32 v239, 1.0, v239
	v_div_scale_f32 v240, s[0:1], v239, v239, v237
	v_rcp_f32_e32 v241, v240
	s_nop 0
	v_fma_f32 v242, -v240, v241, 1.0
	v_fmac_f32_e32 v241, v242, v241
	v_div_scale_f32 v242, vcc, v237, v239, v237
	v_mul_f32_e32 v243, v242, v241
	v_fma_f32 v244, -v240, v243, v242
	v_fmac_f32_e32 v243, v244, v241
	v_fma_f32 v240, -v240, v243, v242
	v_div_fmas_f32 v240, v240, v241, v243
	v_div_fixup_f32 v240, v240, v239, v237
	v_mul_f32_e32 v247, v238, v240
	v_fmac_f32_e32 v229, v247, v247
	v_lshlrev_b32_e32 v236, 16, v143
	v_lshlrev_b32_e32 v237, 16, v151
	v_fma_f32 v238, s61, v236, v38
	v_mul_f32_e32 v239, 0xbfb8aa3b, v237
	v_exp_f32_e32 v239, v239
	s_nop 0
	v_add_f32_e32 v239, 1.0, v239
	v_div_scale_f32 v240, s[0:1], v239, v239, v237
	v_rcp_f32_e32 v241, v240
	s_nop 0
	v_fma_f32 v242, -v240, v241, 1.0
	v_fmac_f32_e32 v241, v242, v241
	v_div_scale_f32 v242, vcc, v237, v239, v237
	v_mul_f32_e32 v243, v242, v241
	v_fma_f32 v244, -v240, v243, v242
	v_fmac_f32_e32 v243, v244, v241
	v_fma_f32 v240, -v240, v243, v242
	v_div_fmas_f32 v240, v240, v241, v243
	v_div_fixup_f32 v240, v240, v239, v237
	v_mul_f32_e32 v248, v238, v240
	v_fmac_f32_e32 v230, v248, v248
	v_and_b32_e32 v236, 0xffff0000, v143
	v_and_b32_e32 v237, 0xffff0000, v151
	v_fma_f32 v238, s61, v236, v39
	v_mul_f32_e32 v239, 0xbfb8aa3b, v237
	v_exp_f32_e32 v239, v239
	s_nop 0
	v_add_f32_e32 v239, 1.0, v239
	v_div_scale_f32 v240, s[0:1], v239, v239, v237
	v_rcp_f32_e32 v241, v240
	s_nop 0
	v_fma_f32 v242, -v240, v241, 1.0
	v_fmac_f32_e32 v241, v242, v241
	v_div_scale_f32 v242, vcc, v237, v239, v237
	v_mul_f32_e32 v243, v242, v241
	v_fma_f32 v244, -v240, v243, v242
	v_fmac_f32_e32 v243, v244, v241
	v_fma_f32 v240, -v240, v243, v242
	v_div_fmas_f32 v240, v240, v241, v243
	v_div_fixup_f32 v240, v240, v239, v237
	v_mul_f32_e32 v249, v238, v240
	v_fmac_f32_e32 v231, v249, v249
	v_cvt_pk_bf16_f32 v188, v246, v247
	v_cvt_pk_bf16_f32 v189, v248, v249
	s_waitcnt lgkmcnt(2)
	v_lshlrev_b32_e32 v236, 16, v144
	v_lshlrev_b32_e32 v237, 16, v152
	v_fma_f32 v238, s61, v236, v40
	v_mul_f32_e32 v239, 0xbfb8aa3b, v237
	v_exp_f32_e32 v239, v239
	s_nop 0
	v_add_f32_e32 v239, 1.0, v239
	v_div_scale_f32 v240, s[0:1], v239, v239, v237
	v_rcp_f32_e32 v241, v240
	s_nop 0
	v_fma_f32 v242, -v240, v241, 1.0
	v_fmac_f32_e32 v241, v242, v241
	v_div_scale_f32 v242, vcc, v237, v239, v237
	v_mul_f32_e32 v243, v242, v241
	v_fma_f32 v244, -v240, v243, v242
	v_fmac_f32_e32 v243, v244, v241
	v_fma_f32 v240, -v240, v243, v242
	v_div_fmas_f32 v240, v240, v241, v243
	v_div_fixup_f32 v240, v240, v239, v237
	v_mul_f32_e32 v246, v238, v240
	v_fmac_f32_e32 v228, v246, v246
	v_and_b32_e32 v236, 0xffff0000, v144
	v_and_b32_e32 v237, 0xffff0000, v152
	v_fma_f32 v238, s61, v236, v41
	v_mul_f32_e32 v239, 0xbfb8aa3b, v237
	v_exp_f32_e32 v239, v239
	s_nop 0
	v_add_f32_e32 v239, 1.0, v239
	v_div_scale_f32 v240, s[0:1], v239, v239, v237
	v_rcp_f32_e32 v241, v240
	s_nop 0
	v_fma_f32 v242, -v240, v241, 1.0
	v_fmac_f32_e32 v241, v242, v241
	v_div_scale_f32 v242, vcc, v237, v239, v237
	v_mul_f32_e32 v243, v242, v241
	v_fma_f32 v244, -v240, v243, v242
	v_fmac_f32_e32 v243, v244, v241
	v_fma_f32 v240, -v240, v243, v242
	v_div_fmas_f32 v240, v240, v241, v243
	v_div_fixup_f32 v240, v240, v239, v237
	v_mul_f32_e32 v247, v238, v240
	v_fmac_f32_e32 v229, v247, v247
	v_lshlrev_b32_e32 v236, 16, v145
	v_lshlrev_b32_e32 v237, 16, v153
	v_fma_f32 v238, s61, v236, v42
	v_mul_f32_e32 v239, 0xbfb8aa3b, v237
	v_exp_f32_e32 v239, v239
	s_nop 0
	v_add_f32_e32 v239, 1.0, v239
	v_div_scale_f32 v240, s[0:1], v239, v239, v237
	v_rcp_f32_e32 v241, v240
	s_nop 0
	v_fma_f32 v242, -v240, v241, 1.0
	v_fmac_f32_e32 v241, v242, v241
	v_div_scale_f32 v242, vcc, v237, v239, v237
	v_mul_f32_e32 v243, v242, v241
	v_fma_f32 v244, -v240, v243, v242
	v_fmac_f32_e32 v243, v244, v241
	v_fma_f32 v240, -v240, v243, v242
	v_div_fmas_f32 v240, v240, v241, v243
	v_div_fixup_f32 v240, v240, v239, v237
	v_mul_f32_e32 v248, v238, v240
	v_fmac_f32_e32 v230, v248, v248
	v_and_b32_e32 v236, 0xffff0000, v145
	v_and_b32_e32 v237, 0xffff0000, v153
	v_fma_f32 v238, s61, v236, v43
	v_mul_f32_e32 v239, 0xbfb8aa3b, v237
	v_exp_f32_e32 v239, v239
	s_nop 0
	v_add_f32_e32 v239, 1.0, v239
	v_div_scale_f32 v240, s[0:1], v239, v239, v237
	v_rcp_f32_e32 v241, v240
	s_nop 0
	v_fma_f32 v242, -v240, v241, 1.0
	v_fmac_f32_e32 v241, v242, v241
	v_div_scale_f32 v242, vcc, v237, v239, v237
	v_mul_f32_e32 v243, v242, v241
	v_fma_f32 v244, -v240, v243, v242
	v_fmac_f32_e32 v243, v244, v241
	v_fma_f32 v240, -v240, v243, v242
	v_div_fmas_f32 v240, v240, v241, v243
	v_div_fixup_f32 v240, v240, v239, v237
	v_mul_f32_e32 v249, v238, v240
	v_fmac_f32_e32 v231, v249, v249
	v_cvt_pk_bf16_f32 v190, v246, v247
	v_cvt_pk_bf16_f32 v191, v248, v249
	s_waitcnt lgkmcnt(0)
	v_lshlrev_b32_e32 v236, 16, v146
	v_lshlrev_b32_e32 v237, 16, v154
	v_fma_f32 v238, s61, v236, v44
	v_mul_f32_e32 v239, 0xbfb8aa3b, v237
	v_exp_f32_e32 v239, v239
	s_nop 0
	v_add_f32_e32 v239, 1.0, v239
	v_div_scale_f32 v240, s[0:1], v239, v239, v237
	v_rcp_f32_e32 v241, v240
	s_nop 0
	v_fma_f32 v242, -v240, v241, 1.0
	v_fmac_f32_e32 v241, v242, v241
	v_div_scale_f32 v242, vcc, v237, v239, v237
	v_mul_f32_e32 v243, v242, v241
	v_fma_f32 v244, -v240, v243, v242
	v_fmac_f32_e32 v243, v244, v241
	v_fma_f32 v240, -v240, v243, v242
	v_div_fmas_f32 v240, v240, v241, v243
	v_div_fixup_f32 v240, v240, v239, v237
	v_mul_f32_e32 v246, v238, v240
	v_fmac_f32_e32 v228, v246, v246
	v_and_b32_e32 v236, 0xffff0000, v146
	v_and_b32_e32 v237, 0xffff0000, v154
	v_fma_f32 v238, s61, v236, v45
	v_mul_f32_e32 v239, 0xbfb8aa3b, v237
	v_exp_f32_e32 v239, v239
	s_nop 0
	v_add_f32_e32 v239, 1.0, v239
	v_div_scale_f32 v240, s[0:1], v239, v239, v237
	v_rcp_f32_e32 v241, v240
	s_nop 0
	v_fma_f32 v242, -v240, v241, 1.0
	v_fmac_f32_e32 v241, v242, v241
	v_div_scale_f32 v242, vcc, v237, v239, v237
	v_mul_f32_e32 v243, v242, v241
	v_fma_f32 v244, -v240, v243, v242
	v_fmac_f32_e32 v243, v244, v241
	v_fma_f32 v240, -v240, v243, v242
	v_div_fmas_f32 v240, v240, v241, v243
	v_div_fixup_f32 v240, v240, v239, v237
	v_mul_f32_e32 v247, v238, v240
	v_fmac_f32_e32 v229, v247, v247
	v_lshlrev_b32_e32 v236, 16, v147
	v_lshlrev_b32_e32 v237, 16, v155
	v_fma_f32 v238, s61, v236, v46
	v_mul_f32_e32 v239, 0xbfb8aa3b, v237
	v_exp_f32_e32 v239, v239
	s_nop 0
	v_add_f32_e32 v239, 1.0, v239
	v_div_scale_f32 v240, s[0:1], v239, v239, v237
	v_rcp_f32_e32 v241, v240
	s_nop 0
	v_fma_f32 v242, -v240, v241, 1.0
	v_fmac_f32_e32 v241, v242, v241
	v_div_scale_f32 v242, vcc, v237, v239, v237
	v_mul_f32_e32 v243, v242, v241
	v_fma_f32 v244, -v240, v243, v242
	v_fmac_f32_e32 v243, v244, v241
	v_fma_f32 v240, -v240, v243, v242
	v_div_fmas_f32 v240, v240, v241, v243
	v_div_fixup_f32 v240, v240, v239, v237
	v_mul_f32_e32 v248, v238, v240
	v_fmac_f32_e32 v230, v248, v248
	v_and_b32_e32 v236, 0xffff0000, v147
	v_and_b32_e32 v237, 0xffff0000, v155
	v_fma_f32 v238, s61, v236, v47
	v_mul_f32_e32 v239, 0xbfb8aa3b, v237
	v_exp_f32_e32 v239, v239
	s_nop 0
	v_add_f32_e32 v239, 1.0, v239
	v_div_scale_f32 v240, s[0:1], v239, v239, v237
	v_rcp_f32_e32 v241, v240
	s_nop 0
	v_fma_f32 v242, -v240, v241, 1.0
	v_fmac_f32_e32 v241, v242, v241
	v_div_scale_f32 v242, vcc, v237, v239, v237
	v_mul_f32_e32 v243, v242, v241
	v_fma_f32 v244, -v240, v243, v242
	v_fmac_f32_e32 v243, v244, v241
	v_fma_f32 v240, -v240, v243, v242
	v_div_fmas_f32 v240, v240, v241, v243
	v_div_fixup_f32 v240, v240, v239, v237
	v_mul_f32_e32 v249, v238, v240
	v_fmac_f32_e32 v231, v249, v249
	v_cvt_pk_bf16_f32 v192, v246, v247
	v_cvt_pk_bf16_f32 v193, v248, v249
	s_waitcnt lgkmcnt(0)
	s_barrier
	s_waitcnt vmcnt(4)
	ds_write_b128 v3, v[64:67]
	ds_write_b128 v3, v[68:71] offset:9216
	ds_write_b128 v3, v[72:75] offset:18432
	ds_write_b128 v3, v[76:79] offset:27648
	ds_write_b128 v3, v[80:83] offset:36864
	ds_write_b128 v3, v[84:87] offset:46080
	ds_write_b128 v3, v[88:91] offset:55296
	ds_write_b128 v3, v[92:95] offset:64512
	ds_write_b128 v4, v[96:99]
	ds_write_b128 v4, v[100:103] offset:8704
	ds_write_b128 v4, v[104:107] offset:17408
	ds_write_b128 v4, v[108:111] offset:26112
	ds_write_b128 v5, v[112:115]
	ds_write_b128 v5, v[116:119] offset:8704
	ds_write_b128 v5, v[120:123] offset:17408
	ds_write_b128 v5, v[124:127] offset:26112
	s_waitcnt lgkmcnt(0)
	s_barrier
	s_add_u32 s52, s42, 0x18000
	s_addc_u32 s53, s43, 0
	global_load_dwordx4 v[124:127], v2, s[52:53]
	s_add_u32 s52, s42, 0x1a000
	s_addc_u32 s53, s43, 0
	global_load_dwordx4 v[128:131], v2, s[52:53]
	s_add_u32 s52, s42, 0x1c000
	s_addc_u32 s53, s43, 0
	global_load_dwordx4 v[132:135], v2, s[52:53]
	s_add_u32 s52, s42, 0x1e000
	s_addc_u32 s53, s43, 0
	global_load_dwordx4 v[136:139], v2, s[52:53]
	ds_read_b32 v156, v167 offset:5120
	ds_read_b32 v157, v167 offset:7168
	ds_read_b32 v158, v167 offset:5632
	ds_read_b32 v159, v167 offset:7680
	ds_read_b128 v[64:67], v169 offset:0
	ds_read_b128 v[68:71], v169 offset:64
	ds_read_b128 v[72:75], v169 offset:128
	ds_read_b128 v[76:79], v169 offset:192
	ds_read_b128 v[80:83], v169 offset:4352
	ds_read_b128 v[84:87], v169 offset:4416
	ds_read_b128 v[88:91], v169 offset:4480
	ds_read_b128 v[92:95], v169 offset:4544
	s_waitcnt vmcnt(4)
	s_waitcnt lgkmcnt(0)
	v_mfma_f32_16x16x32_bf16 v[96:99], v[64:67], v[48:51], 0
	v_mfma_f32_16x16x32_bf16 v[96:99], v[68:71], v[52:55], v[96:99]
	v_mfma_f32_16x16x32_bf16 v[96:99], v[72:75], v[56:59], v[96:99]
	v_mfma_f32_16x16x32_bf16 v[96:99], v[76:79], v[60:63], v[96:99]
	v_mfma_f32_16x16x32_bf16 v[100:103], v[80:83], v[48:51], 0
	v_mfma_f32_16x16x32_bf16 v[100:103], v[84:87], v[52:55], v[100:103]
	v_mfma_f32_16x16x32_bf16 v[100:103], v[88:91], v[56:59], v[100:103]
	v_mfma_f32_16x16x32_bf16 v[100:103], v[92:95], v[60:63], v[100:103]
	ds_read_b128 v[64:67], v168 offset:1024
	ds_read_b128 v[68:71], v168 offset:3072
	ds_read_b128 v[72:75], v168 offset:5120
	ds_read_b128 v[76:79], v168 offset:7168
	ds_read_b128 v[80:83], v168 offset:1088
	ds_read_b128 v[84:87], v168 offset:3136
	ds_read_b128 v[88:91], v168 offset:5184
	ds_read_b128 v[92:95], v168 offset:7232
	ds_read_b64_tr_b16 v[108:109], v166 offset:0
	ds_read_b64_tr_b16 v[110:111], v166 offset:4608
	ds_read_b64_tr_b16 v[112:113], v166 offset:32
	ds_read_b64_tr_b16 v[114:115], v166 offset:4640
	s_waitcnt lgkmcnt(4)
	v_subrev_u32_e32 v236, 0, v175
	v_cmp_gt_i32_e64 s[78:79], v236, 0
	v_cmp_gt_i32_e64 s[80:81], v236, 1
	v_cmp_gt_i32_e64 s[82:83], v236, 2
	v_cmp_gt_i32_e64 s[84:85], v236, 3
	v_cmp_eq_u32_e64 s[86:87], v236, 0
	v_cmp_eq_u32_e64 s[88:89], v236, 1
	v_cmp_eq_u32_e64 s[90:91], v236, 2
	v_cmp_eq_u32_e64 s[92:93], v236, 3
	v_cndmask_b32_e64 v237, v76, v72, s[78:79]
	v_cndmask_b32_e64 v238, v157, v156, s[78:79]
	v_sub_f32_e32 v237, v238, v237
	v_min_f32_e32 v237, 0, v237
	v_mul_f32_e32 v237, 0x3fb8aa3b, v237
	v_exp_f32_e32 v237, v237
	v_cndmask_b32_e64 v239, v68, v64, s[78:79]
	v_add_f32_e32 v240, v64, v68
	v_mul_f32_e32 v237, v239, v237
	v_cndmask_b32_e64 v237, v237, v240, s[86:87]
	v_mul_f32_e32 v241, v96, v237
	v_cndmask_b32_e64 v237, v77, v73, s[80:81]
	v_cndmask_b32_e64 v238, v157, v156, s[80:81]
	v_sub_f32_e32 v237, v238, v237
	v_min_f32_e32 v237, 0, v237
	v_mul_f32_e32 v237, 0x3fb8aa3b, v237
	v_exp_f32_e32 v237, v237
	v_cndmask_b32_e64 v239, v69, v65, s[80:81]
	v_add_f32_e32 v240, v65, v69
	v_mul_f32_e32 v237, v239, v237
	v_cndmask_b32_e64 v237, v237, v240, s[88:89]
	v_mul_f32_e32 v242, v97, v237
	v_cndmask_b32_e64 v237, v78, v74, s[82:83]
	v_cndmask_b32_e64 v238, v157, v156, s[82:83]
	v_sub_f32_e32 v237, v238, v237
	v_min_f32_e32 v237, 0, v237
	v_mul_f32_e32 v237, 0x3fb8aa3b, v237
	v_exp_f32_e32 v237, v237
	v_cndmask_b32_e64 v239, v70, v66, s[82:83]
	v_add_f32_e32 v240, v66, v70
	v_mul_f32_e32 v237, v239, v237
	v_cndmask_b32_e64 v237, v237, v240, s[90:91]
	v_mul_f32_e32 v243, v98, v237
	v_cndmask_b32_e64 v237, v79, v75, s[84:85]
	v_cndmask_b32_e64 v238, v157, v156, s[84:85]
	v_sub_f32_e32 v237, v238, v237
	v_min_f32_e32 v237, 0, v237
	v_mul_f32_e32 v237, 0x3fb8aa3b, v237
	v_exp_f32_e32 v237, v237
	v_cndmask_b32_e64 v239, v71, v67, s[84:85]
	v_add_f32_e32 v240, v67, v71
	v_mul_f32_e32 v237, v239, v237
	v_cndmask_b32_e64 v237, v237, v240, s[92:93]
	v_mul_f32_e32 v244, v99, v237
	ds_read_b64_tr_b16 v[116:117], v166 offset:64
	ds_read_b64_tr_b16 v[118:119], v166 offset:4672
	ds_read_b64_tr_b16 v[120:121], v166 offset:96
	ds_read_b64_tr_b16 v[122:123], v166 offset:4704
	v_subrev_u32_e32 v236, 16, v175
	v_cmp_gt_i32_e64 s[78:79], v236, 0
	v_cmp_gt_i32_e64 s[80:81], v236, 1
	v_cmp_gt_i32_e64 s[82:83], v236, 2
	v_cmp_gt_i32_e64 s[84:85], v236, 3
	v_cmp_eq_u32_e64 s[86:87], v236, 0
	v_cmp_eq_u32_e64 s[88:89], v236, 1
	v_cmp_eq_u32_e64 s[90:91], v236, 2
	v_cmp_eq_u32_e64 s[92:93], v236, 3
	v_cndmask_b32_e64 v237, v92, v88, s[78:79]
	v_cndmask_b32_e64 v238, v157, v156, s[78:79]
	v_sub_f32_e32 v237, v238, v237
	v_min_f32_e32 v237, 0, v237
	v_mul_f32_e32 v237, 0x3fb8aa3b, v237
	v_exp_f32_e32 v237, v237
	v_cndmask_b32_e64 v239, v84, v80, s[78:79]
	v_add_f32_e32 v240, v80, v84
	v_mul_f32_e32 v237, v239, v237
	v_cndmask_b32_e64 v237, v237, v240, s[86:87]
	v_mul_f32_e32 v245, v100, v237
	v_cndmask_b32_e64 v237, v93, v89, s[80:81]
	v_cndmask_b32_e64 v238, v157, v156, s[80:81]
	v_sub_f32_e32 v237, v238, v237
	v_min_f32_e32 v237, 0, v237
	v_mul_f32_e32 v237, 0x3fb8aa3b, v237
	v_exp_f32_e32 v237, v237
	v_cndmask_b32_e64 v239, v85, v81, s[80:81]
	v_add_f32_e32 v240, v81, v85
	v_mul_f32_e32 v237, v239, v237
	v_cndmask_b32_e64 v237, v237, v240, s[88:89]
	v_mul_f32_e32 v246, v101, v237
	v_cndmask_b32_e64 v237, v94, v90, s[82:83]
	v_cndmask_b32_e64 v238, v157, v156, s[82:83]
	v_sub_f32_e32 v237, v238, v237
	v_min_f32_e32 v237, 0, v237
	v_mul_f32_e32 v237, 0x3fb8aa3b, v237
	v_exp_f32_e32 v237, v237
	v_cndmask_b32_e64 v239, v86, v82, s[82:83]
	v_add_f32_e32 v240, v82, v86
	v_mul_f32_e32 v237, v239, v237
	v_cndmask_b32_e64 v237, v237, v240, s[90:91]
	v_mul_f32_e32 v247, v102, v237
	v_cndmask_b32_e64 v237, v95, v91, s[84:85]
	v_cndmask_b32_e64 v238, v157, v156, s[84:85]
	v_sub_f32_e32 v237, v238, v237
	v_min_f32_e32 v237, 0, v237
	v_mul_f32_e32 v237, 0x3fb8aa3b, v237
	v_exp_f32_e32 v237, v237
	v_cndmask_b32_e64 v239, v87, v83, s[84:85]
	v_add_f32_e32 v240, v83, v87
	v_mul_f32_e32 v237, v239, v237
	v_cndmask_b32_e64 v237, v237, v240, s[92:93]
	v_mul_f32_e32 v248, v103, v237
	v_cvt_pk_bf16_f32 v104, v241, v242
	v_cvt_pk_bf16_f32 v105, v243, v244
	v_cvt_pk_bf16_f32 v106, v245, v246
	v_cvt_pk_bf16_f32 v107, v247, v248
	s_waitcnt lgkmcnt(0)
	s_nop 1
	v_mfma_f32_16x16x32_bf16 v[16:19], v[104:107], v[108:111], 0
	v_mfma_f32_16x16x32_bf16 v[20:23], v[104:107], v[112:115], 0
	v_mfma_f32_16x16x32_bf16 v[24:27], v[104:107], v[116:119], 0
	v_mfma_f32_16x16x32_bf16 v[28:31], v[104:107], v[120:123], 0
	ds_read_b128 v[64:67], v168 offset:1536
	ds_read_b128 v[68:71], v168 offset:3584
	ds_read_b128 v[72:75], v168 offset:5632
	ds_read_b128 v[76:79], v168 offset:7680
	ds_read_b128 v[80:83], v168 offset:1600
	ds_read_b128 v[84:87], v168 offset:3648
	ds_read_b128 v[88:91], v168 offset:5696
	ds_read_b128 v[92:95], v168 offset:7744
	ds_read_b64_tr_b16 v[108:109], v166 offset:128
	ds_read_b64_tr_b16 v[110:111], v166 offset:4736
	ds_read_b64_tr_b16 v[112:113], v166 offset:160
	ds_read_b64_tr_b16 v[114:115], v166 offset:4768
	s_waitcnt lgkmcnt(4)
	v_subrev_u32_e32 v236, 0, v175
	v_cmp_gt_i32_e64 s[78:79], v236, 0
	v_cmp_gt_i32_e64 s[80:81], v236, 1
	v_cmp_gt_i32_e64 s[82:83], v236, 2
	v_cmp_gt_i32_e64 s[84:85], v236, 3
	v_cmp_eq_u32_e64 s[86:87], v236, 0
	v_cmp_eq_u32_e64 s[88:89], v236, 1
	v_cmp_eq_u32_e64 s[90:91], v236, 2
	v_cmp_eq_u32_e64 s[92:93], v236, 3
	v_cndmask_b32_e64 v237, v76, v72, s[78:79]
	v_cndmask_b32_e64 v238, v159, v158, s[78:79]
	v_sub_f32_e32 v237, v238, v237
	v_min_f32_e32 v237, 0, v237
	v_mul_f32_e32 v237, 0x3fb8aa3b, v237
	v_exp_f32_e32 v237, v237
	v_cndmask_b32_e64 v239, v68, v64, s[78:79]
	v_add_f32_e32 v240, v64, v68
	v_mul_f32_e32 v237, v239, v237
	v_cndmask_b32_e64 v237, v237, v240, s[86:87]
	v_mul_f32_e32 v241, v96, v237
	v_cndmask_b32_e64 v237, v77, v73, s[80:81]
	v_cndmask_b32_e64 v238, v159, v158, s[80:81]
	v_sub_f32_e32 v237, v238, v237
	v_min_f32_e32 v237, 0, v237
	v_mul_f32_e32 v237, 0x3fb8aa3b, v237
	v_exp_f32_e32 v237, v237
	v_cndmask_b32_e64 v239, v69, v65, s[80:81]
	v_add_f32_e32 v240, v65, v69
	v_mul_f32_e32 v237, v239, v237
	v_cndmask_b32_e64 v237, v237, v240, s[88:89]
	v_mul_f32_e32 v242, v97, v237
	v_cndmask_b32_e64 v237, v78, v74, s[82:83]
	v_cndmask_b32_e64 v238, v159, v158, s[82:83]
	v_sub_f32_e32 v237, v238, v237
	v_min_f32_e32 v237, 0, v237
	v_mul_f32_e32 v237, 0x3fb8aa3b, v237
	v_exp_f32_e32 v237, v237
	v_cndmask_b32_e64 v239, v70, v66, s[82:83]
	v_add_f32_e32 v240, v66, v70
	v_mul_f32_e32 v237, v239, v237
	v_cndmask_b32_e64 v237, v237, v240, s[90:91]
	v_mul_f32_e32 v243, v98, v237
	v_cndmask_b32_e64 v237, v79, v75, s[84:85]
	v_cndmask_b32_e64 v238, v159, v158, s[84:85]
	v_sub_f32_e32 v237, v238, v237
	v_min_f32_e32 v237, 0, v237
	v_mul_f32_e32 v237, 0x3fb8aa3b, v237
	v_exp_f32_e32 v237, v237
	v_cndmask_b32_e64 v239, v71, v67, s[84:85]
	v_add_f32_e32 v240, v67, v71
	v_mul_f32_e32 v237, v239, v237
	v_cndmask_b32_e64 v237, v237, v240, s[92:93]
	v_mul_f32_e32 v244, v99, v237
	ds_read_b64_tr_b16 v[116:117], v166 offset:192
	ds_read_b64_tr_b16 v[118:119], v166 offset:4800
	ds_read_b64_tr_b16 v[120:121], v166 offset:224
	ds_read_b64_tr_b16 v[122:123], v166 offset:4832
	v_subrev_u32_e32 v236, 16, v175
	v_cmp_gt_i32_e64 s[78:79], v236, 0
	v_cmp_gt_i32_e64 s[80:81], v236, 1
	v_cmp_gt_i32_e64 s[82:83], v236, 2
	v_cmp_gt_i32_e64 s[84:85], v236, 3
	v_cmp_eq_u32_e64 s[86:87], v236, 0
	v_cmp_eq_u32_e64 s[88:89], v236, 1
	v_cmp_eq_u32_e64 s[90:91], v236, 2
	v_cmp_eq_u32_e64 s[92:93], v236, 3
	v_cndmask_b32_e64 v237, v92, v88, s[78:79]
	v_cndmask_b32_e64 v238, v159, v158, s[78:79]
	v_sub_f32_e32 v237, v238, v237
	v_min_f32_e32 v237, 0, v237
	v_mul_f32_e32 v237, 0x3fb8aa3b, v237
	v_exp_f32_e32 v237, v237
	v_cndmask_b32_e64 v239, v84, v80, s[78:79]
	v_add_f32_e32 v240, v80, v84
	v_mul_f32_e32 v237, v239, v237
	v_cndmask_b32_e64 v237, v237, v240, s[86:87]
	v_mul_f32_e32 v245, v100, v237
	v_cndmask_b32_e64 v237, v93, v89, s[80:81]
	v_cndmask_b32_e64 v238, v159, v158, s[80:81]
	v_sub_f32_e32 v237, v238, v237
	v_min_f32_e32 v237, 0, v237
	v_mul_f32_e32 v237, 0x3fb8aa3b, v237
	v_exp_f32_e32 v237, v237
	v_cndmask_b32_e64 v239, v85, v81, s[80:81]
	v_add_f32_e32 v240, v81, v85
	v_mul_f32_e32 v237, v239, v237
	v_cndmask_b32_e64 v237, v237, v240, s[88:89]
	v_mul_f32_e32 v246, v101, v237
	v_cndmask_b32_e64 v237, v94, v90, s[82:83]
	v_cndmask_b32_e64 v238, v159, v158, s[82:83]
	v_sub_f32_e32 v237, v238, v237
	v_min_f32_e32 v237, 0, v237
	v_mul_f32_e32 v237, 0x3fb8aa3b, v237
	v_exp_f32_e32 v237, v237
	v_cndmask_b32_e64 v239, v86, v82, s[82:83]
	v_add_f32_e32 v240, v82, v86
	v_mul_f32_e32 v237, v239, v237
	v_cndmask_b32_e64 v237, v237, v240, s[90:91]
	v_mul_f32_e32 v247, v102, v237
	v_cndmask_b32_e64 v237, v95, v91, s[84:85]
	v_cndmask_b32_e64 v238, v159, v158, s[84:85]
	v_sub_f32_e32 v237, v238, v237
	v_min_f32_e32 v237, 0, v237
	v_mul_f32_e32 v237, 0x3fb8aa3b, v237
	v_exp_f32_e32 v237, v237
	v_cndmask_b32_e64 v239, v87, v83, s[84:85]
	v_add_f32_e32 v240, v83, v87
	v_mul_f32_e32 v237, v239, v237
	v_cndmask_b32_e64 v237, v237, v240, s[92:93]
	v_mul_f32_e32 v248, v103, v237
	v_cvt_pk_bf16_f32 v104, v241, v242
	v_cvt_pk_bf16_f32 v105, v243, v244
	v_cvt_pk_bf16_f32 v106, v245, v246
	v_cvt_pk_bf16_f32 v107, v247, v248
	s_waitcnt lgkmcnt(0)
	s_nop 1
	v_mfma_f32_16x16x32_bf16 v[32:35], v[104:107], v[108:111], 0
	v_mfma_f32_16x16x32_bf16 v[36:39], v[104:107], v[112:115], 0
	v_mfma_f32_16x16x32_bf16 v[40:43], v[104:107], v[116:119], 0
	v_mfma_f32_16x16x32_bf16 v[44:47], v[104:107], v[120:123], 0
	ds_read_b128 v[64:67], v169 offset:8704
	ds_read_b128 v[68:71], v169 offset:8768
	ds_read_b128 v[72:75], v169 offset:8832
	ds_read_b128 v[76:79], v169 offset:8896
	ds_read_b128 v[80:83], v169 offset:13056
	ds_read_b128 v[84:87], v169 offset:13120
	ds_read_b128 v[88:91], v169 offset:13184
	ds_read_b128 v[92:95], v169 offset:13248
	s_waitcnt lgkmcnt(0)
	v_mfma_f32_16x16x32_bf16 v[96:99], v[64:67], v[48:51], 0
	v_mfma_f32_16x16x32_bf16 v[96:99], v[68:71], v[52:55], v[96:99]
	v_mfma_f32_16x16x32_bf16 v[96:99], v[72:75], v[56:59], v[96:99]
	v_mfma_f32_16x16x32_bf16 v[96:99], v[76:79], v[60:63], v[96:99]
	v_mfma_f32_16x16x32_bf16 v[100:103], v[80:83], v[48:51], 0
	v_mfma_f32_16x16x32_bf16 v[100:103], v[84:87], v[52:55], v[100:103]
	v_mfma_f32_16x16x32_bf16 v[100:103], v[88:91], v[56:59], v[100:103]
	v_mfma_f32_16x16x32_bf16 v[100:103], v[92:95], v[60:63], v[100:103]
	ds_read_b128 v[64:67], v168 offset:1152
	ds_read_b128 v[68:71], v168 offset:3200
	ds_read_b128 v[72:75], v168 offset:5248
	ds_read_b128 v[76:79], v168 offset:7296
	ds_read_b128 v[80:83], v168 offset:1216
	ds_read_b128 v[84:87], v168 offset:3264
	ds_read_b128 v[88:91], v168 offset:5312
	ds_read_b128 v[92:95], v168 offset:7360
	ds_read_b64_tr_b16 v[108:109], v166 offset:9216
	ds_read_b64_tr_b16 v[110:111], v166 offset:13824
	ds_read_b64_tr_b16 v[112:113], v166 offset:9248
	ds_read_b64_tr_b16 v[114:115], v166 offset:13856
	s_waitcnt lgkmcnt(4)
	v_subrev_u32_e32 v236, 32, v175
	v_cmp_gt_i32_e64 s[78:79], v236, 0
	v_cmp_gt_i32_e64 s[80:81], v236, 1
	v_cmp_gt_i32_e64 s[82:83], v236, 2
	v_cmp_gt_i32_e64 s[84:85], v236, 3
	v_cmp_eq_u32_e64 s[86:87], v236, 0
	v_cmp_eq_u32_e64 s[88:89], v236, 1
	v_cmp_eq_u32_e64 s[90:91], v236, 2
	v_cmp_eq_u32_e64 s[92:93], v236, 3
	v_cndmask_b32_e64 v237, v76, v72, s[78:79]
	v_cndmask_b32_e64 v238, v157, v156, s[78:79]
	v_sub_f32_e32 v237, v238, v237
	v_min_f32_e32 v237, 0, v237
	v_mul_f32_e32 v237, 0x3fb8aa3b, v237
	v_exp_f32_e32 v237, v237
	v_cndmask_b32_e64 v239, v68, v64, s[78:79]
	v_add_f32_e32 v240, v64, v68
	v_mul_f32_e32 v237, v239, v237
	v_cndmask_b32_e64 v237, v237, v240, s[86:87]
	v_mul_f32_e32 v241, v96, v237
	v_cndmask_b32_e64 v237, v77, v73, s[80:81]
	v_cndmask_b32_e64 v238, v157, v156, s[80:81]
	v_sub_f32_e32 v237, v238, v237
	v_min_f32_e32 v237, 0, v237
	v_mul_f32_e32 v237, 0x3fb8aa3b, v237
	v_exp_f32_e32 v237, v237
	v_cndmask_b32_e64 v239, v69, v65, s[80:81]
	v_add_f32_e32 v240, v65, v69
	v_mul_f32_e32 v237, v239, v237
	v_cndmask_b32_e64 v237, v237, v240, s[88:89]
	v_mul_f32_e32 v242, v97, v237
	v_cndmask_b32_e64 v237, v78, v74, s[82:83]
	v_cndmask_b32_e64 v238, v157, v156, s[82:83]
	v_sub_f32_e32 v237, v238, v237
	v_min_f32_e32 v237, 0, v237
	v_mul_f32_e32 v237, 0x3fb8aa3b, v237
	v_exp_f32_e32 v237, v237
	v_cndmask_b32_e64 v239, v70, v66, s[82:83]
	v_add_f32_e32 v240, v66, v70
	v_mul_f32_e32 v237, v239, v237
	v_cndmask_b32_e64 v237, v237, v240, s[90:91]
	v_mul_f32_e32 v243, v98, v237
	v_cndmask_b32_e64 v237, v79, v75, s[84:85]
	v_cndmask_b32_e64 v238, v157, v156, s[84:85]
	v_sub_f32_e32 v237, v238, v237
	v_min_f32_e32 v237, 0, v237
	v_mul_f32_e32 v237, 0x3fb8aa3b, v237
	v_exp_f32_e32 v237, v237
	v_cndmask_b32_e64 v239, v71, v67, s[84:85]
	v_add_f32_e32 v240, v67, v71
	v_mul_f32_e32 v237, v239, v237
	v_cndmask_b32_e64 v237, v237, v240, s[92:93]
	v_mul_f32_e32 v244, v99, v237
	ds_read_b64_tr_b16 v[116:117], v166 offset:9280
	ds_read_b64_tr_b16 v[118:119], v166 offset:13888
	ds_read_b64_tr_b16 v[120:121], v166 offset:9312
	ds_read_b64_tr_b16 v[122:123], v166 offset:13920
	v_subrev_u32_e32 v236, 48, v175
	v_cmp_gt_i32_e64 s[78:79], v236, 0
	v_cmp_gt_i32_e64 s[80:81], v236, 1
	v_cmp_gt_i32_e64 s[82:83], v236, 2
	v_cmp_gt_i32_e64 s[84:85], v236, 3
	v_cmp_eq_u32_e64 s[86:87], v236, 0
	v_cmp_eq_u32_e64 s[88:89], v236, 1
	v_cmp_eq_u32_e64 s[90:91], v236, 2
	v_cmp_eq_u32_e64 s[92:93], v236, 3
	v_cndmask_b32_e64 v237, v92, v88, s[78:79]
	v_cndmask_b32_e64 v238, v157, v156, s[78:79]
	v_sub_f32_e32 v237, v238, v237
	v_min_f32_e32 v237, 0, v237
	v_mul_f32_e32 v237, 0x3fb8aa3b, v237
	v_exp_f32_e32 v237, v237
	v_cndmask_b32_e64 v239, v84, v80, s[78:79]
	v_add_f32_e32 v240, v80, v84
	v_mul_f32_e32 v237, v239, v237
	v_cndmask_b32_e64 v237, v237, v240, s[86:87]
	v_mul_f32_e32 v245, v100, v237
	v_cndmask_b32_e64 v237, v93, v89, s[80:81]
	v_cndmask_b32_e64 v238, v157, v156, s[80:81]
	v_sub_f32_e32 v237, v238, v237
	v_min_f32_e32 v237, 0, v237
	v_mul_f32_e32 v237, 0x3fb8aa3b, v237
	v_exp_f32_e32 v237, v237
	v_cndmask_b32_e64 v239, v85, v81, s[80:81]
	v_add_f32_e32 v240, v81, v85
	v_mul_f32_e32 v237, v239, v237
	v_cndmask_b32_e64 v237, v237, v240, s[88:89]
	v_mul_f32_e32 v246, v101, v237
	v_cndmask_b32_e64 v237, v94, v90, s[82:83]
	v_cndmask_b32_e64 v238, v157, v156, s[82:83]
	v_sub_f32_e32 v237, v238, v237
	v_min_f32_e32 v237, 0, v237
	v_mul_f32_e32 v237, 0x3fb8aa3b, v237
	v_exp_f32_e32 v237, v237
	v_cndmask_b32_e64 v239, v86, v82, s[82:83]
	v_add_f32_e32 v240, v82, v86
	v_mul_f32_e32 v237, v239, v237
	v_cndmask_b32_e64 v237, v237, v240, s[90:91]
	v_mul_f32_e32 v247, v102, v237
	v_cndmask_b32_e64 v237, v95, v91, s[84:85]
	v_cndmask_b32_e64 v238, v157, v156, s[84:85]
	v_sub_f32_e32 v237, v238, v237
	v_min_f32_e32 v237, 0, v237
	v_mul_f32_e32 v237, 0x3fb8aa3b, v237
	v_exp_f32_e32 v237, v237
	v_cndmask_b32_e64 v239, v87, v83, s[84:85]
	v_add_f32_e32 v240, v83, v87
	v_mul_f32_e32 v237, v239, v237
	v_cndmask_b32_e64 v237, v237, v240, s[92:93]
	v_mul_f32_e32 v248, v103, v237
	v_cvt_pk_bf16_f32 v104, v241, v242
	v_cvt_pk_bf16_f32 v105, v243, v244
	v_cvt_pk_bf16_f32 v106, v245, v246
	v_cvt_pk_bf16_f32 v107, v247, v248
	s_waitcnt lgkmcnt(0)
	s_nop 1
	v_mfma_f32_16x16x32_bf16 v[16:19], v[104:107], v[108:111], v[16:19]
	v_mfma_f32_16x16x32_bf16 v[20:23], v[104:107], v[112:115], v[20:23]
	v_mfma_f32_16x16x32_bf16 v[24:27], v[104:107], v[116:119], v[24:27]
	v_mfma_f32_16x16x32_bf16 v[28:31], v[104:107], v[120:123], v[28:31]
	ds_read_b128 v[64:67], v168 offset:1664
	ds_read_b128 v[68:71], v168 offset:3712
	ds_read_b128 v[72:75], v168 offset:5760
	ds_read_b128 v[76:79], v168 offset:7808
	ds_read_b128 v[80:83], v168 offset:1728
	ds_read_b128 v[84:87], v168 offset:3776
	ds_read_b128 v[88:91], v168 offset:5824
	ds_read_b128 v[92:95], v168 offset:7872
	ds_read_b64_tr_b16 v[108:109], v166 offset:9344
	ds_read_b64_tr_b16 v[110:111], v166 offset:13952
	ds_read_b64_tr_b16 v[112:113], v166 offset:9376
	ds_read_b64_tr_b16 v[114:115], v166 offset:13984
	s_waitcnt lgkmcnt(4)
	v_subrev_u32_e32 v236, 32, v175
	v_cmp_gt_i32_e64 s[78:79], v236, 0
	v_cmp_gt_i32_e64 s[80:81], v236, 1
	v_cmp_gt_i32_e64 s[82:83], v236, 2
	v_cmp_gt_i32_e64 s[84:85], v236, 3
	v_cmp_eq_u32_e64 s[86:87], v236, 0
	v_cmp_eq_u32_e64 s[88:89], v236, 1
	v_cmp_eq_u32_e64 s[90:91], v236, 2
	v_cmp_eq_u32_e64 s[92:93], v236, 3
	v_cndmask_b32_e64 v237, v76, v72, s[78:79]
	v_cndmask_b32_e64 v238, v159, v158, s[78:79]
	v_sub_f32_e32 v237, v238, v237
	v_min_f32_e32 v237, 0, v237
	v_mul_f32_e32 v237, 0x3fb8aa3b, v237
	v_exp_f32_e32 v237, v237
	v_cndmask_b32_e64 v239, v68, v64, s[78:79]
	v_add_f32_e32 v240, v64, v68
	v_mul_f32_e32 v237, v239, v237
	v_cndmask_b32_e64 v237, v237, v240, s[86:87]
	v_mul_f32_e32 v241, v96, v237
	v_cndmask_b32_e64 v237, v77, v73, s[80:81]
	v_cndmask_b32_e64 v238, v159, v158, s[80:81]
	v_sub_f32_e32 v237, v238, v237
	v_min_f32_e32 v237, 0, v237
	v_mul_f32_e32 v237, 0x3fb8aa3b, v237
	v_exp_f32_e32 v237, v237
	v_cndmask_b32_e64 v239, v69, v65, s[80:81]
	v_add_f32_e32 v240, v65, v69
	v_mul_f32_e32 v237, v239, v237
	v_cndmask_b32_e64 v237, v237, v240, s[88:89]
	v_mul_f32_e32 v242, v97, v237
	v_cndmask_b32_e64 v237, v78, v74, s[82:83]
	v_cndmask_b32_e64 v238, v159, v158, s[82:83]
	v_sub_f32_e32 v237, v238, v237
	v_min_f32_e32 v237, 0, v237
	v_mul_f32_e32 v237, 0x3fb8aa3b, v237
	v_exp_f32_e32 v237, v237
	v_cndmask_b32_e64 v239, v70, v66, s[82:83]
	v_add_f32_e32 v240, v66, v70
	v_mul_f32_e32 v237, v239, v237
	v_cndmask_b32_e64 v237, v237, v240, s[90:91]
	v_mul_f32_e32 v243, v98, v237
	v_cndmask_b32_e64 v237, v79, v75, s[84:85]
	v_cndmask_b32_e64 v238, v159, v158, s[84:85]
	v_sub_f32_e32 v237, v238, v237
	v_min_f32_e32 v237, 0, v237
	v_mul_f32_e32 v237, 0x3fb8aa3b, v237
	v_exp_f32_e32 v237, v237
	v_cndmask_b32_e64 v239, v71, v67, s[84:85]
	v_add_f32_e32 v240, v67, v71
	v_mul_f32_e32 v237, v239, v237
	v_cndmask_b32_e64 v237, v237, v240, s[92:93]
	v_mul_f32_e32 v244, v99, v237
	ds_read_b64_tr_b16 v[116:117], v166 offset:9408
	ds_read_b64_tr_b16 v[118:119], v166 offset:14016
	ds_read_b64_tr_b16 v[120:121], v166 offset:9440
	ds_read_b64_tr_b16 v[122:123], v166 offset:14048
	v_subrev_u32_e32 v236, 48, v175
	v_cmp_gt_i32_e64 s[78:79], v236, 0
	v_cmp_gt_i32_e64 s[80:81], v236, 1
	v_cmp_gt_i32_e64 s[82:83], v236, 2
	v_cmp_gt_i32_e64 s[84:85], v236, 3
	v_cmp_eq_u32_e64 s[86:87], v236, 0
	v_cmp_eq_u32_e64 s[88:89], v236, 1
	v_cmp_eq_u32_e64 s[90:91], v236, 2
	v_cmp_eq_u32_e64 s[92:93], v236, 3
	v_cndmask_b32_e64 v237, v92, v88, s[78:79]
	v_cndmask_b32_e64 v238, v159, v158, s[78:79]
	v_sub_f32_e32 v237, v238, v237
	v_min_f32_e32 v237, 0, v237
	v_mul_f32_e32 v237, 0x3fb8aa3b, v237
	v_exp_f32_e32 v237, v237
	v_cndmask_b32_e64 v239, v84, v80, s[78:79]
	v_add_f32_e32 v240, v80, v84
	v_mul_f32_e32 v237, v239, v237
	v_cndmask_b32_e64 v237, v237, v240, s[86:87]
	v_mul_f32_e32 v245, v100, v237
	v_cndmask_b32_e64 v237, v93, v89, s[80:81]
	v_cndmask_b32_e64 v238, v159, v158, s[80:81]
	v_sub_f32_e32 v237, v238, v237
	v_min_f32_e32 v237, 0, v237
	v_mul_f32_e32 v237, 0x3fb8aa3b, v237
	v_exp_f32_e32 v237, v237
	v_cndmask_b32_e64 v239, v85, v81, s[80:81]
	v_add_f32_e32 v240, v81, v85
	v_mul_f32_e32 v237, v239, v237
	v_cndmask_b32_e64 v237, v237, v240, s[88:89]
	v_mul_f32_e32 v246, v101, v237
	v_cndmask_b32_e64 v237, v94, v90, s[82:83]
	v_cndmask_b32_e64 v238, v159, v158, s[82:83]
	v_sub_f32_e32 v237, v238, v237
	v_min_f32_e32 v237, 0, v237
	v_mul_f32_e32 v237, 0x3fb8aa3b, v237
	v_exp_f32_e32 v237, v237
	v_cndmask_b32_e64 v239, v86, v82, s[82:83]
	v_add_f32_e32 v240, v82, v86
	v_mul_f32_e32 v237, v239, v237
	v_cndmask_b32_e64 v237, v237, v240, s[90:91]
	v_mul_f32_e32 v247, v102, v237
	v_cndmask_b32_e64 v237, v95, v91, s[84:85]
	v_cndmask_b32_e64 v238, v159, v158, s[84:85]
	v_sub_f32_e32 v237, v238, v237
	v_min_f32_e32 v237, 0, v237
	v_mul_f32_e32 v237, 0x3fb8aa3b, v237
	v_exp_f32_e32 v237, v237
	v_cndmask_b32_e64 v239, v87, v83, s[84:85]
	v_add_f32_e32 v240, v83, v87
	v_mul_f32_e32 v237, v239, v237
	v_cndmask_b32_e64 v237, v237, v240, s[92:93]
	v_mul_f32_e32 v248, v103, v237
	v_cvt_pk_bf16_f32 v104, v241, v242
	v_cvt_pk_bf16_f32 v105, v243, v244
	v_cvt_pk_bf16_f32 v106, v245, v246
	v_cvt_pk_bf16_f32 v107, v247, v248
	s_waitcnt lgkmcnt(0)
	s_nop 1
	v_mfma_f32_16x16x32_bf16 v[32:35], v[104:107], v[108:111], v[32:35]
	v_mfma_f32_16x16x32_bf16 v[36:39], v[104:107], v[112:115], v[36:39]
	v_mfma_f32_16x16x32_bf16 v[40:43], v[104:107], v[116:119], v[40:43]
	v_mfma_f32_16x16x32_bf16 v[44:47], v[104:107], v[120:123], v[44:47]
	ds_read_b128 v[64:67], v169 offset:17408
	ds_read_b128 v[68:71], v169 offset:17472
	ds_read_b128 v[72:75], v169 offset:17536
	ds_read_b128 v[76:79], v169 offset:17600
	ds_read_b128 v[80:83], v169 offset:21760
	ds_read_b128 v[84:87], v169 offset:21824
	ds_read_b128 v[88:91], v169 offset:21888
	ds_read_b128 v[92:95], v169 offset:21952
	s_waitcnt lgkmcnt(0)
	v_mfma_f32_16x16x32_bf16 v[96:99], v[64:67], v[48:51], 0
	v_mfma_f32_16x16x32_bf16 v[96:99], v[68:71], v[52:55], v[96:99]
	v_mfma_f32_16x16x32_bf16 v[96:99], v[72:75], v[56:59], v[96:99]
	v_mfma_f32_16x16x32_bf16 v[96:99], v[76:79], v[60:63], v[96:99]
	v_mfma_f32_16x16x32_bf16 v[100:103], v[80:83], v[48:51], 0
	v_mfma_f32_16x16x32_bf16 v[100:103], v[84:87], v[52:55], v[100:103]
	v_mfma_f32_16x16x32_bf16 v[100:103], v[88:91], v[56:59], v[100:103]
	v_mfma_f32_16x16x32_bf16 v[100:103], v[92:95], v[60:63], v[100:103]
	ds_read_b128 v[64:67], v168 offset:1280
	ds_read_b128 v[68:71], v168 offset:3328
	ds_read_b128 v[72:75], v168 offset:5376
	ds_read_b128 v[76:79], v168 offset:7424
	ds_read_b128 v[80:83], v168 offset:1344
	ds_read_b128 v[84:87], v168 offset:3392
	ds_read_b128 v[88:91], v168 offset:5440
	ds_read_b128 v[92:95], v168 offset:7488
	ds_read_b64_tr_b16 v[108:109], v166 offset:18432
	ds_read_b64_tr_b16 v[110:111], v166 offset:23040
	ds_read_b64_tr_b16 v[112:113], v166 offset:18464
	ds_read_b64_tr_b16 v[114:115], v166 offset:23072
	s_waitcnt lgkmcnt(4)
	v_subrev_u32_e32 v236, 64, v175
	v_cmp_gt_i32_e64 s[78:79], v236, 0
	v_cmp_gt_i32_e64 s[80:81], v236, 1
	v_cmp_gt_i32_e64 s[82:83], v236, 2
	v_cmp_gt_i32_e64 s[84:85], v236, 3
	v_cmp_eq_u32_e64 s[86:87], v236, 0
	v_cmp_eq_u32_e64 s[88:89], v236, 1
	v_cmp_eq_u32_e64 s[90:91], v236, 2
	v_cmp_eq_u32_e64 s[92:93], v236, 3
	v_cndmask_b32_e64 v237, v76, v72, s[78:79]
	v_cndmask_b32_e64 v238, v157, v156, s[78:79]
	v_sub_f32_e32 v237, v238, v237
	v_min_f32_e32 v237, 0, v237
	v_mul_f32_e32 v237, 0x3fb8aa3b, v237
	v_exp_f32_e32 v237, v237
	v_cndmask_b32_e64 v239, v68, v64, s[78:79]
	v_add_f32_e32 v240, v64, v68
	v_mul_f32_e32 v237, v239, v237
	v_cndmask_b32_e64 v237, v237, v240, s[86:87]
	v_mul_f32_e32 v241, v96, v237
	v_cndmask_b32_e64 v237, v77, v73, s[80:81]
	v_cndmask_b32_e64 v238, v157, v156, s[80:81]
	v_sub_f32_e32 v237, v238, v237
	v_min_f32_e32 v237, 0, v237
	v_mul_f32_e32 v237, 0x3fb8aa3b, v237
	v_exp_f32_e32 v237, v237
	v_cndmask_b32_e64 v239, v69, v65, s[80:81]
	v_add_f32_e32 v240, v65, v69
	v_mul_f32_e32 v237, v239, v237
	v_cndmask_b32_e64 v237, v237, v240, s[88:89]
	v_mul_f32_e32 v242, v97, v237
	v_cndmask_b32_e64 v237, v78, v74, s[82:83]
	v_cndmask_b32_e64 v238, v157, v156, s[82:83]
	v_sub_f32_e32 v237, v238, v237
	v_min_f32_e32 v237, 0, v237
	v_mul_f32_e32 v237, 0x3fb8aa3b, v237
	v_exp_f32_e32 v237, v237
	v_cndmask_b32_e64 v239, v70, v66, s[82:83]
	v_add_f32_e32 v240, v66, v70
	v_mul_f32_e32 v237, v239, v237
	v_cndmask_b32_e64 v237, v237, v240, s[90:91]
	v_mul_f32_e32 v243, v98, v237
	v_cndmask_b32_e64 v237, v79, v75, s[84:85]
	v_cndmask_b32_e64 v238, v157, v156, s[84:85]
	v_sub_f32_e32 v237, v238, v237
	v_min_f32_e32 v237, 0, v237
	v_mul_f32_e32 v237, 0x3fb8aa3b, v237
	v_exp_f32_e32 v237, v237
	v_cndmask_b32_e64 v239, v71, v67, s[84:85]
	v_add_f32_e32 v240, v67, v71
	v_mul_f32_e32 v237, v239, v237
	v_cndmask_b32_e64 v237, v237, v240, s[92:93]
	v_mul_f32_e32 v244, v99, v237
	ds_read_b64_tr_b16 v[116:117], v166 offset:18496
	ds_read_b64_tr_b16 v[118:119], v166 offset:23104
	ds_read_b64_tr_b16 v[120:121], v166 offset:18528
	ds_read_b64_tr_b16 v[122:123], v166 offset:23136
	v_subrev_u32_e32 v236, 80, v175
	v_cmp_gt_i32_e64 s[78:79], v236, 0
	v_cmp_gt_i32_e64 s[80:81], v236, 1
	v_cmp_gt_i32_e64 s[82:83], v236, 2
	v_cmp_gt_i32_e64 s[84:85], v236, 3
	v_cmp_eq_u32_e64 s[86:87], v236, 0
	v_cmp_eq_u32_e64 s[88:89], v236, 1
	v_cmp_eq_u32_e64 s[90:91], v236, 2
	v_cmp_eq_u32_e64 s[92:93], v236, 3
	v_cndmask_b32_e64 v237, v92, v88, s[78:79]
	v_cndmask_b32_e64 v238, v157, v156, s[78:79]
	v_sub_f32_e32 v237, v238, v237
	v_min_f32_e32 v237, 0, v237
	v_mul_f32_e32 v237, 0x3fb8aa3b, v237
	v_exp_f32_e32 v237, v237
	v_cndmask_b32_e64 v239, v84, v80, s[78:79]
	v_add_f32_e32 v240, v80, v84
	v_mul_f32_e32 v237, v239, v237
	v_cndmask_b32_e64 v237, v237, v240, s[86:87]
	v_mul_f32_e32 v245, v100, v237
	v_cndmask_b32_e64 v237, v93, v89, s[80:81]
	v_cndmask_b32_e64 v238, v157, v156, s[80:81]
	v_sub_f32_e32 v237, v238, v237
	v_min_f32_e32 v237, 0, v237
	v_mul_f32_e32 v237, 0x3fb8aa3b, v237
	v_exp_f32_e32 v237, v237
	v_cndmask_b32_e64 v239, v85, v81, s[80:81]
	v_add_f32_e32 v240, v81, v85
	v_mul_f32_e32 v237, v239, v237
	v_cndmask_b32_e64 v237, v237, v240, s[88:89]
	v_mul_f32_e32 v246, v101, v237
	v_cndmask_b32_e64 v237, v94, v90, s[82:83]
	v_cndmask_b32_e64 v238, v157, v156, s[82:83]
	v_sub_f32_e32 v237, v238, v237
	v_min_f32_e32 v237, 0, v237
	v_mul_f32_e32 v237, 0x3fb8aa3b, v237
	v_exp_f32_e32 v237, v237
	v_cndmask_b32_e64 v239, v86, v82, s[82:83]
	v_add_f32_e32 v240, v82, v86
	v_mul_f32_e32 v237, v239, v237
	v_cndmask_b32_e64 v237, v237, v240, s[90:91]
	v_mul_f32_e32 v247, v102, v237
	v_cndmask_b32_e64 v237, v95, v91, s[84:85]
	v_cndmask_b32_e64 v238, v157, v156, s[84:85]
	v_sub_f32_e32 v237, v238, v237
	v_min_f32_e32 v237, 0, v237
	v_mul_f32_e32 v237, 0x3fb8aa3b, v237
	v_exp_f32_e32 v237, v237
	v_cndmask_b32_e64 v239, v87, v83, s[84:85]
	v_add_f32_e32 v240, v83, v87
	v_mul_f32_e32 v237, v239, v237
	v_cndmask_b32_e64 v237, v237, v240, s[92:93]
	v_mul_f32_e32 v248, v103, v237
	v_cvt_pk_bf16_f32 v104, v241, v242
	v_cvt_pk_bf16_f32 v105, v243, v244
	v_cvt_pk_bf16_f32 v106, v245, v246
	v_cvt_pk_bf16_f32 v107, v247, v248
	s_waitcnt lgkmcnt(0)
	s_nop 1
	v_mfma_f32_16x16x32_bf16 v[16:19], v[104:107], v[108:111], v[16:19]
	v_mfma_f32_16x16x32_bf16 v[20:23], v[104:107], v[112:115], v[20:23]
	v_mfma_f32_16x16x32_bf16 v[24:27], v[104:107], v[116:119], v[24:27]
	v_mfma_f32_16x16x32_bf16 v[28:31], v[104:107], v[120:123], v[28:31]
	ds_read_b128 v[64:67], v168 offset:1792
	ds_read_b128 v[68:71], v168 offset:3840
	ds_read_b128 v[72:75], v168 offset:5888
	ds_read_b128 v[76:79], v168 offset:7936
	ds_read_b128 v[80:83], v168 offset:1856
	ds_read_b128 v[84:87], v168 offset:3904
	ds_read_b128 v[88:91], v168 offset:5952
	ds_read_b128 v[92:95], v168 offset:8000
	ds_read_b64_tr_b16 v[108:109], v166 offset:18560
	ds_read_b64_tr_b16 v[110:111], v166 offset:23168
	ds_read_b64_tr_b16 v[112:113], v166 offset:18592
	ds_read_b64_tr_b16 v[114:115], v166 offset:23200
	s_waitcnt lgkmcnt(4)
	v_subrev_u32_e32 v236, 64, v175
	v_cmp_gt_i32_e64 s[78:79], v236, 0
	v_cmp_gt_i32_e64 s[80:81], v236, 1
	v_cmp_gt_i32_e64 s[82:83], v236, 2
	v_cmp_gt_i32_e64 s[84:85], v236, 3
	v_cmp_eq_u32_e64 s[86:87], v236, 0
	v_cmp_eq_u32_e64 s[88:89], v236, 1
	v_cmp_eq_u32_e64 s[90:91], v236, 2
	v_cmp_eq_u32_e64 s[92:93], v236, 3
	v_cndmask_b32_e64 v237, v76, v72, s[78:79]
	v_cndmask_b32_e64 v238, v159, v158, s[78:79]
	v_sub_f32_e32 v237, v238, v237
	v_min_f32_e32 v237, 0, v237
	v_mul_f32_e32 v237, 0x3fb8aa3b, v237
	v_exp_f32_e32 v237, v237
	v_cndmask_b32_e64 v239, v68, v64, s[78:79]
	v_add_f32_e32 v240, v64, v68
	v_mul_f32_e32 v237, v239, v237
	v_cndmask_b32_e64 v237, v237, v240, s[86:87]
	v_mul_f32_e32 v241, v96, v237
	v_cndmask_b32_e64 v237, v77, v73, s[80:81]
	v_cndmask_b32_e64 v238, v159, v158, s[80:81]
	v_sub_f32_e32 v237, v238, v237
	v_min_f32_e32 v237, 0, v237
	v_mul_f32_e32 v237, 0x3fb8aa3b, v237
	v_exp_f32_e32 v237, v237
	v_cndmask_b32_e64 v239, v69, v65, s[80:81]
	v_add_f32_e32 v240, v65, v69
	v_mul_f32_e32 v237, v239, v237
	v_cndmask_b32_e64 v237, v237, v240, s[88:89]
	v_mul_f32_e32 v242, v97, v237
	v_cndmask_b32_e64 v237, v78, v74, s[82:83]
	v_cndmask_b32_e64 v238, v159, v158, s[82:83]
	v_sub_f32_e32 v237, v238, v237
	v_min_f32_e32 v237, 0, v237
	v_mul_f32_e32 v237, 0x3fb8aa3b, v237
	v_exp_f32_e32 v237, v237
	v_cndmask_b32_e64 v239, v70, v66, s[82:83]
	v_add_f32_e32 v240, v66, v70
	v_mul_f32_e32 v237, v239, v237
	v_cndmask_b32_e64 v237, v237, v240, s[90:91]
	v_mul_f32_e32 v243, v98, v237
	v_cndmask_b32_e64 v237, v79, v75, s[84:85]
	v_cndmask_b32_e64 v238, v159, v158, s[84:85]
	v_sub_f32_e32 v237, v238, v237
	v_min_f32_e32 v237, 0, v237
	v_mul_f32_e32 v237, 0x3fb8aa3b, v237
	v_exp_f32_e32 v237, v237
	v_cndmask_b32_e64 v239, v71, v67, s[84:85]
	v_add_f32_e32 v240, v67, v71
	v_mul_f32_e32 v237, v239, v237
	v_cndmask_b32_e64 v237, v237, v240, s[92:93]
	v_mul_f32_e32 v244, v99, v237
	ds_read_b64_tr_b16 v[116:117], v166 offset:18624
	ds_read_b64_tr_b16 v[118:119], v166 offset:23232
	ds_read_b64_tr_b16 v[120:121], v166 offset:18656
	ds_read_b64_tr_b16 v[122:123], v166 offset:23264
	v_subrev_u32_e32 v236, 80, v175
	v_cmp_gt_i32_e64 s[78:79], v236, 0
	v_cmp_gt_i32_e64 s[80:81], v236, 1
	v_cmp_gt_i32_e64 s[82:83], v236, 2
	v_cmp_gt_i32_e64 s[84:85], v236, 3
	v_cmp_eq_u32_e64 s[86:87], v236, 0
	v_cmp_eq_u32_e64 s[88:89], v236, 1
	v_cmp_eq_u32_e64 s[90:91], v236, 2
	v_cmp_eq_u32_e64 s[92:93], v236, 3
	v_cndmask_b32_e64 v237, v92, v88, s[78:79]
	v_cndmask_b32_e64 v238, v159, v158, s[78:79]
	v_sub_f32_e32 v237, v238, v237
	v_min_f32_e32 v237, 0, v237
	v_mul_f32_e32 v237, 0x3fb8aa3b, v237
	v_exp_f32_e32 v237, v237
	v_cndmask_b32_e64 v239, v84, v80, s[78:79]
	v_add_f32_e32 v240, v80, v84
	v_mul_f32_e32 v237, v239, v237
	v_cndmask_b32_e64 v237, v237, v240, s[86:87]
	v_mul_f32_e32 v245, v100, v237
	v_cndmask_b32_e64 v237, v93, v89, s[80:81]
	v_cndmask_b32_e64 v238, v159, v158, s[80:81]
	v_sub_f32_e32 v237, v238, v237
	v_min_f32_e32 v237, 0, v237
	v_mul_f32_e32 v237, 0x3fb8aa3b, v237
	v_exp_f32_e32 v237, v237
	v_cndmask_b32_e64 v239, v85, v81, s[80:81]
	v_add_f32_e32 v240, v81, v85
	v_mul_f32_e32 v237, v239, v237
	v_cndmask_b32_e64 v237, v237, v240, s[88:89]
	v_mul_f32_e32 v246, v101, v237
	v_cndmask_b32_e64 v237, v94, v90, s[82:83]
	v_cndmask_b32_e64 v238, v159, v158, s[82:83]
	v_sub_f32_e32 v237, v238, v237
	v_min_f32_e32 v237, 0, v237
	v_mul_f32_e32 v237, 0x3fb8aa3b, v237
	v_exp_f32_e32 v237, v237
	v_cndmask_b32_e64 v239, v86, v82, s[82:83]
	v_add_f32_e32 v240, v82, v86
	v_mul_f32_e32 v237, v239, v237
	v_cndmask_b32_e64 v237, v237, v240, s[90:91]
	v_mul_f32_e32 v247, v102, v237
	v_cndmask_b32_e64 v237, v95, v91, s[84:85]
	v_cndmask_b32_e64 v238, v159, v158, s[84:85]
	v_sub_f32_e32 v237, v238, v237
	v_min_f32_e32 v237, 0, v237
	v_mul_f32_e32 v237, 0x3fb8aa3b, v237
	v_exp_f32_e32 v237, v237
	v_cndmask_b32_e64 v239, v87, v83, s[84:85]
	v_add_f32_e32 v240, v83, v87
	v_mul_f32_e32 v237, v239, v237
	v_cndmask_b32_e64 v237, v237, v240, s[92:93]
	v_mul_f32_e32 v248, v103, v237
	v_cvt_pk_bf16_f32 v104, v241, v242
	v_cvt_pk_bf16_f32 v105, v243, v244
	v_cvt_pk_bf16_f32 v106, v245, v246
	v_cvt_pk_bf16_f32 v107, v247, v248
	s_waitcnt lgkmcnt(0)
	s_nop 1
	v_mfma_f32_16x16x32_bf16 v[32:35], v[104:107], v[108:111], v[32:35]
	v_mfma_f32_16x16x32_bf16 v[36:39], v[104:107], v[112:115], v[36:39]
	v_mfma_f32_16x16x32_bf16 v[40:43], v[104:107], v[116:119], v[40:43]
	v_mfma_f32_16x16x32_bf16 v[44:47], v[104:107], v[120:123], v[44:47]
	ds_read_b128 v[64:67], v169 offset:26112
	ds_read_b128 v[68:71], v169 offset:26176
	ds_read_b128 v[72:75], v169 offset:26240
	ds_read_b128 v[76:79], v169 offset:26304
	ds_read_b128 v[80:83], v169 offset:30464
	ds_read_b128 v[84:87], v169 offset:30528
	ds_read_b128 v[88:91], v169 offset:30592
	ds_read_b128 v[92:95], v169 offset:30656
	s_waitcnt lgkmcnt(0)
	v_mfma_f32_16x16x32_bf16 v[96:99], v[64:67], v[48:51], 0
	v_mfma_f32_16x16x32_bf16 v[96:99], v[68:71], v[52:55], v[96:99]
	v_mfma_f32_16x16x32_bf16 v[96:99], v[72:75], v[56:59], v[96:99]
	v_mfma_f32_16x16x32_bf16 v[96:99], v[76:79], v[60:63], v[96:99]
	v_mfma_f32_16x16x32_bf16 v[100:103], v[80:83], v[48:51], 0
	v_mfma_f32_16x16x32_bf16 v[100:103], v[84:87], v[52:55], v[100:103]
	v_mfma_f32_16x16x32_bf16 v[100:103], v[88:91], v[56:59], v[100:103]
	v_mfma_f32_16x16x32_bf16 v[100:103], v[92:95], v[60:63], v[100:103]
	ds_read_b128 v[64:67], v168 offset:1408
	ds_read_b128 v[68:71], v168 offset:3456
	ds_read_b128 v[72:75], v168 offset:5504
	ds_read_b128 v[76:79], v168 offset:7552
	ds_read_b128 v[80:83], v168 offset:1472
	ds_read_b128 v[84:87], v168 offset:3520
	ds_read_b128 v[88:91], v168 offset:5568
	ds_read_b128 v[92:95], v168 offset:7616
	ds_read_b64_tr_b16 v[108:109], v166 offset:27648
	ds_read_b64_tr_b16 v[110:111], v166 offset:32256
	ds_read_b64_tr_b16 v[112:113], v166 offset:27680
	ds_read_b64_tr_b16 v[114:115], v166 offset:32288
	s_waitcnt lgkmcnt(4)
	v_subrev_u32_e32 v236, 96, v175
	v_cmp_gt_i32_e64 s[78:79], v236, 0
	v_cmp_gt_i32_e64 s[80:81], v236, 1
	v_cmp_gt_i32_e64 s[82:83], v236, 2
	v_cmp_gt_i32_e64 s[84:85], v236, 3
	v_cmp_eq_u32_e64 s[86:87], v236, 0
	v_cmp_eq_u32_e64 s[88:89], v236, 1
	v_cmp_eq_u32_e64 s[90:91], v236, 2
	v_cmp_eq_u32_e64 s[92:93], v236, 3
	v_cndmask_b32_e64 v237, v76, v72, s[78:79]
	v_cndmask_b32_e64 v238, v157, v156, s[78:79]
	v_sub_f32_e32 v237, v238, v237
	v_min_f32_e32 v237, 0, v237
	v_mul_f32_e32 v237, 0x3fb8aa3b, v237
	v_exp_f32_e32 v237, v237
	v_cndmask_b32_e64 v239, v68, v64, s[78:79]
	v_add_f32_e32 v240, v64, v68
	v_mul_f32_e32 v237, v239, v237
	v_cndmask_b32_e64 v237, v237, v240, s[86:87]
	v_mul_f32_e32 v241, v96, v237
	v_cndmask_b32_e64 v237, v77, v73, s[80:81]
	v_cndmask_b32_e64 v238, v157, v156, s[80:81]
	v_sub_f32_e32 v237, v238, v237
	v_min_f32_e32 v237, 0, v237
	v_mul_f32_e32 v237, 0x3fb8aa3b, v237
	v_exp_f32_e32 v237, v237
	v_cndmask_b32_e64 v239, v69, v65, s[80:81]
	v_add_f32_e32 v240, v65, v69
	v_mul_f32_e32 v237, v239, v237
	v_cndmask_b32_e64 v237, v237, v240, s[88:89]
	v_mul_f32_e32 v242, v97, v237
	v_cndmask_b32_e64 v237, v78, v74, s[82:83]
	v_cndmask_b32_e64 v238, v157, v156, s[82:83]
	v_sub_f32_e32 v237, v238, v237
	v_min_f32_e32 v237, 0, v237
	v_mul_f32_e32 v237, 0x3fb8aa3b, v237
	v_exp_f32_e32 v237, v237
	v_cndmask_b32_e64 v239, v70, v66, s[82:83]
	v_add_f32_e32 v240, v66, v70
	v_mul_f32_e32 v237, v239, v237
	v_cndmask_b32_e64 v237, v237, v240, s[90:91]
	v_mul_f32_e32 v243, v98, v237
	v_cndmask_b32_e64 v237, v79, v75, s[84:85]
	v_cndmask_b32_e64 v238, v157, v156, s[84:85]
	v_sub_f32_e32 v237, v238, v237
	v_min_f32_e32 v237, 0, v237
	v_mul_f32_e32 v237, 0x3fb8aa3b, v237
	v_exp_f32_e32 v237, v237
	v_cndmask_b32_e64 v239, v71, v67, s[84:85]
	v_add_f32_e32 v240, v67, v71
	v_mul_f32_e32 v237, v239, v237
	v_cndmask_b32_e64 v237, v237, v240, s[92:93]
	v_mul_f32_e32 v244, v99, v237
	ds_read_b64_tr_b16 v[116:117], v166 offset:27712
	ds_read_b64_tr_b16 v[118:119], v166 offset:32320
	ds_read_b64_tr_b16 v[120:121], v166 offset:27744
	ds_read_b64_tr_b16 v[122:123], v166 offset:32352
	v_subrev_u32_e32 v236, 112, v175
	v_cmp_gt_i32_e64 s[78:79], v236, 0
	v_cmp_gt_i32_e64 s[80:81], v236, 1
	v_cmp_gt_i32_e64 s[82:83], v236, 2
	v_cmp_gt_i32_e64 s[84:85], v236, 3
	v_cmp_eq_u32_e64 s[86:87], v236, 0
	v_cmp_eq_u32_e64 s[88:89], v236, 1
	v_cmp_eq_u32_e64 s[90:91], v236, 2
	v_cmp_eq_u32_e64 s[92:93], v236, 3
	v_cndmask_b32_e64 v237, v92, v88, s[78:79]
	v_cndmask_b32_e64 v238, v157, v156, s[78:79]
	v_sub_f32_e32 v237, v238, v237
	v_min_f32_e32 v237, 0, v237
	v_mul_f32_e32 v237, 0x3fb8aa3b, v237
	v_exp_f32_e32 v237, v237
	v_cndmask_b32_e64 v239, v84, v80, s[78:79]
	v_add_f32_e32 v240, v80, v84
	v_mul_f32_e32 v237, v239, v237
	v_cndmask_b32_e64 v237, v237, v240, s[86:87]
	v_mul_f32_e32 v245, v100, v237
	v_cndmask_b32_e64 v237, v93, v89, s[80:81]
	v_cndmask_b32_e64 v238, v157, v156, s[80:81]
	v_sub_f32_e32 v237, v238, v237
	v_min_f32_e32 v237, 0, v237
	v_mul_f32_e32 v237, 0x3fb8aa3b, v237
	v_exp_f32_e32 v237, v237
	v_cndmask_b32_e64 v239, v85, v81, s[80:81]
	v_add_f32_e32 v240, v81, v85
	v_mul_f32_e32 v237, v239, v237
	v_cndmask_b32_e64 v237, v237, v240, s[88:89]
	v_mul_f32_e32 v246, v101, v237
	v_cndmask_b32_e64 v237, v94, v90, s[82:83]
	v_cndmask_b32_e64 v238, v157, v156, s[82:83]
	v_sub_f32_e32 v237, v238, v237
	v_min_f32_e32 v237, 0, v237
	v_mul_f32_e32 v237, 0x3fb8aa3b, v237
	v_exp_f32_e32 v237, v237
	v_cndmask_b32_e64 v239, v86, v82, s[82:83]
	v_add_f32_e32 v240, v82, v86
	v_mul_f32_e32 v237, v239, v237
	v_cndmask_b32_e64 v237, v237, v240, s[90:91]
	v_mul_f32_e32 v247, v102, v237
	v_cndmask_b32_e64 v237, v95, v91, s[84:85]
	v_cndmask_b32_e64 v238, v157, v156, s[84:85]
	v_sub_f32_e32 v237, v238, v237
	v_min_f32_e32 v237, 0, v237
	v_mul_f32_e32 v237, 0x3fb8aa3b, v237
	v_exp_f32_e32 v237, v237
	v_cndmask_b32_e64 v239, v87, v83, s[84:85]
	v_add_f32_e32 v240, v83, v87
	v_mul_f32_e32 v237, v239, v237
	v_cndmask_b32_e64 v237, v237, v240, s[92:93]
	v_mul_f32_e32 v248, v103, v237
	v_cvt_pk_bf16_f32 v104, v241, v242
	v_cvt_pk_bf16_f32 v105, v243, v244
	v_cvt_pk_bf16_f32 v106, v245, v246
	v_cvt_pk_bf16_f32 v107, v247, v248
	s_waitcnt lgkmcnt(0)
	s_nop 1
	v_mfma_f32_16x16x32_bf16 v[16:19], v[104:107], v[108:111], v[16:19]
	v_mfma_f32_16x16x32_bf16 v[20:23], v[104:107], v[112:115], v[20:23]
	v_mfma_f32_16x16x32_bf16 v[24:27], v[104:107], v[116:119], v[24:27]
	v_mfma_f32_16x16x32_bf16 v[28:31], v[104:107], v[120:123], v[28:31]
	ds_read_b128 v[64:67], v168 offset:1920
	ds_read_b128 v[68:71], v168 offset:3968
	ds_read_b128 v[72:75], v168 offset:6016
	ds_read_b128 v[76:79], v168 offset:8064
	ds_read_b128 v[80:83], v168 offset:1984
	ds_read_b128 v[84:87], v168 offset:4032
	ds_read_b128 v[88:91], v168 offset:6080
	ds_read_b128 v[92:95], v168 offset:8128
	ds_read_b64_tr_b16 v[108:109], v166 offset:27776
	ds_read_b64_tr_b16 v[110:111], v166 offset:32384
	ds_read_b64_tr_b16 v[112:113], v166 offset:27808
	ds_read_b64_tr_b16 v[114:115], v166 offset:32416
	s_waitcnt lgkmcnt(4)
	v_subrev_u32_e32 v236, 96, v175
	v_cmp_gt_i32_e64 s[78:79], v236, 0
	v_cmp_gt_i32_e64 s[80:81], v236, 1
	v_cmp_gt_i32_e64 s[82:83], v236, 2
	v_cmp_gt_i32_e64 s[84:85], v236, 3
	v_cmp_eq_u32_e64 s[86:87], v236, 0
	v_cmp_eq_u32_e64 s[88:89], v236, 1
	v_cmp_eq_u32_e64 s[90:91], v236, 2
	v_cmp_eq_u32_e64 s[92:93], v236, 3
	v_cndmask_b32_e64 v237, v76, v72, s[78:79]
	v_cndmask_b32_e64 v238, v159, v158, s[78:79]
	v_sub_f32_e32 v237, v238, v237
	v_min_f32_e32 v237, 0, v237
	v_mul_f32_e32 v237, 0x3fb8aa3b, v237
	v_exp_f32_e32 v237, v237
	v_cndmask_b32_e64 v239, v68, v64, s[78:79]
	v_add_f32_e32 v240, v64, v68
	v_mul_f32_e32 v237, v239, v237
	v_cndmask_b32_e64 v237, v237, v240, s[86:87]
	v_mul_f32_e32 v241, v96, v237
	v_cndmask_b32_e64 v237, v77, v73, s[80:81]
	v_cndmask_b32_e64 v238, v159, v158, s[80:81]
	v_sub_f32_e32 v237, v238, v237
	v_min_f32_e32 v237, 0, v237
	v_mul_f32_e32 v237, 0x3fb8aa3b, v237
	v_exp_f32_e32 v237, v237
	v_cndmask_b32_e64 v239, v69, v65, s[80:81]
	v_add_f32_e32 v240, v65, v69
	v_mul_f32_e32 v237, v239, v237
	v_cndmask_b32_e64 v237, v237, v240, s[88:89]
	v_mul_f32_e32 v242, v97, v237
	v_cndmask_b32_e64 v237, v78, v74, s[82:83]
	v_cndmask_b32_e64 v238, v159, v158, s[82:83]
	v_sub_f32_e32 v237, v238, v237
	v_min_f32_e32 v237, 0, v237
	v_mul_f32_e32 v237, 0x3fb8aa3b, v237
	v_exp_f32_e32 v237, v237
	v_cndmask_b32_e64 v239, v70, v66, s[82:83]
	v_add_f32_e32 v240, v66, v70
	v_mul_f32_e32 v237, v239, v237
	v_cndmask_b32_e64 v237, v237, v240, s[90:91]
	v_mul_f32_e32 v243, v98, v237
	v_cndmask_b32_e64 v237, v79, v75, s[84:85]
	v_cndmask_b32_e64 v238, v159, v158, s[84:85]
	v_sub_f32_e32 v237, v238, v237
	v_min_f32_e32 v237, 0, v237
	v_mul_f32_e32 v237, 0x3fb8aa3b, v237
	v_exp_f32_e32 v237, v237
	v_cndmask_b32_e64 v239, v71, v67, s[84:85]
	v_add_f32_e32 v240, v67, v71
	v_mul_f32_e32 v237, v239, v237
	v_cndmask_b32_e64 v237, v237, v240, s[92:93]
	v_mul_f32_e32 v244, v99, v237
	ds_read_b64_tr_b16 v[116:117], v166 offset:27840
	ds_read_b64_tr_b16 v[118:119], v166 offset:32448
	ds_read_b64_tr_b16 v[120:121], v166 offset:27872
	ds_read_b64_tr_b16 v[122:123], v166 offset:32480
	v_subrev_u32_e32 v236, 112, v175
	v_cmp_gt_i32_e64 s[78:79], v236, 0
	v_cmp_gt_i32_e64 s[80:81], v236, 1
	v_cmp_gt_i32_e64 s[82:83], v236, 2
	v_cmp_gt_i32_e64 s[84:85], v236, 3
	v_cmp_eq_u32_e64 s[86:87], v236, 0
	v_cmp_eq_u32_e64 s[88:89], v236, 1
	v_cmp_eq_u32_e64 s[90:91], v236, 2
	v_cmp_eq_u32_e64 s[92:93], v236, 3
	v_cndmask_b32_e64 v237, v92, v88, s[78:79]
	v_cndmask_b32_e64 v238, v159, v158, s[78:79]
	v_sub_f32_e32 v237, v238, v237
	v_min_f32_e32 v237, 0, v237
	v_mul_f32_e32 v237, 0x3fb8aa3b, v237
	v_exp_f32_e32 v237, v237
	v_cndmask_b32_e64 v239, v84, v80, s[78:79]
	v_add_f32_e32 v240, v80, v84
	v_mul_f32_e32 v237, v239, v237
	v_cndmask_b32_e64 v237, v237, v240, s[86:87]
	v_mul_f32_e32 v245, v100, v237
	v_cndmask_b32_e64 v237, v93, v89, s[80:81]
	v_cndmask_b32_e64 v238, v159, v158, s[80:81]
	v_sub_f32_e32 v237, v238, v237
	v_min_f32_e32 v237, 0, v237
	v_mul_f32_e32 v237, 0x3fb8aa3b, v237
	v_exp_f32_e32 v237, v237
	v_cndmask_b32_e64 v239, v85, v81, s[80:81]
	v_add_f32_e32 v240, v81, v85
	v_mul_f32_e32 v237, v239, v237
	v_cndmask_b32_e64 v237, v237, v240, s[88:89]
	v_mul_f32_e32 v246, v101, v237
	v_cndmask_b32_e64 v237, v94, v90, s[82:83]
	v_cndmask_b32_e64 v238, v159, v158, s[82:83]
	v_sub_f32_e32 v237, v238, v237
	v_min_f32_e32 v237, 0, v237
	v_mul_f32_e32 v237, 0x3fb8aa3b, v237
	v_exp_f32_e32 v237, v237
	v_cndmask_b32_e64 v239, v86, v82, s[82:83]
	v_add_f32_e32 v240, v82, v86
	v_mul_f32_e32 v237, v239, v237
	v_cndmask_b32_e64 v237, v237, v240, s[90:91]
	v_mul_f32_e32 v247, v102, v237
	v_cndmask_b32_e64 v237, v95, v91, s[84:85]
	v_cndmask_b32_e64 v238, v159, v158, s[84:85]
	v_sub_f32_e32 v237, v238, v237
	v_min_f32_e32 v237, 0, v237
	v_mul_f32_e32 v237, 0x3fb8aa3b, v237
	v_exp_f32_e32 v237, v237
	v_cndmask_b32_e64 v239, v87, v83, s[84:85]
	v_add_f32_e32 v240, v83, v87
	v_mul_f32_e32 v237, v239, v237
	v_cndmask_b32_e64 v237, v237, v240, s[92:93]
	v_mul_f32_e32 v248, v103, v237
	v_cvt_pk_bf16_f32 v104, v241, v242
	v_cvt_pk_bf16_f32 v105, v243, v244
	v_cvt_pk_bf16_f32 v106, v245, v246
	v_cvt_pk_bf16_f32 v107, v247, v248
	s_waitcnt lgkmcnt(0)
	s_nop 1
	v_mfma_f32_16x16x32_bf16 v[32:35], v[104:107], v[108:111], v[32:35]
	v_mfma_f32_16x16x32_bf16 v[36:39], v[104:107], v[112:115], v[36:39]
	v_mfma_f32_16x16x32_bf16 v[40:43], v[104:107], v[116:119], v[40:43]
	v_mfma_f32_16x16x32_bf16 v[44:47], v[104:107], v[120:123], v[44:47]
	ds_read_b128 v[108:111], v170 offset:0
	ds_read_b128 v[112:115], v170 offset:4352
	ds_read_b128 v[116:119], v170 offset:8704
	ds_read_b128 v[120:123], v170 offset:13056
	ds_read_b128 v[64:67], v170 offset:64
	ds_read_b128 v[68:71], v170 offset:4416
	ds_read_b128 v[72:75], v170 offset:8768
	ds_read_b128 v[76:79], v170 offset:13120
	v_mul_f32_e32 v236, 0x3fb8aa3b, v156
	v_exp_f32_e32 v236, v236
	s_nop 0
	v_lshlrev_b32_e32 v237, 16, v48
	v_and_b32_e32 v238, 0xffff0000, v48
	v_mul_f32_e32 v237, v236, v237
	v_mul_f32_e32 v238, v236, v238
	v_cvt_pk_bf16_f32 v104, v237, v238
	v_lshlrev_b32_e32 v237, 16, v49
	v_and_b32_e32 v238, 0xffff0000, v49
	v_mul_f32_e32 v237, v236, v237
	v_mul_f32_e32 v238, v236, v238
	v_cvt_pk_bf16_f32 v105, v237, v238
	v_lshlrev_b32_e32 v237, 16, v50
	v_and_b32_e32 v238, 0xffff0000, v50
	v_mul_f32_e32 v237, v236, v237
	v_mul_f32_e32 v238, v236, v238
	v_cvt_pk_bf16_f32 v106, v237, v238
	v_lshlrev_b32_e32 v237, 16, v51
	v_and_b32_e32 v238, 0xffff0000, v51
	v_mul_f32_e32 v237, v236, v237
	v_mul_f32_e32 v238, v236, v238
	v_cvt_pk_bf16_f32 v107, v237, v238
	s_waitcnt lgkmcnt(4)
	s_nop 0
	v_mfma_f32_16x16x32_bf16 v[16:19], v[104:107], v[108:111], v[16:19]
	v_mfma_f32_16x16x32_bf16 v[20:23], v[104:107], v[112:115], v[20:23]
	v_mfma_f32_16x16x32_bf16 v[24:27], v[104:107], v[116:119], v[24:27]
	v_mfma_f32_16x16x32_bf16 v[28:31], v[104:107], v[120:123], v[28:31]
	ds_read_b128 v[108:111], v170 offset:128
	ds_read_b128 v[112:115], v170 offset:4480
	ds_read_b128 v[116:119], v170 offset:8832
	ds_read_b128 v[120:123], v170 offset:13184
	v_lshlrev_b32_e32 v237, 16, v52
	v_and_b32_e32 v238, 0xffff0000, v52
	v_mul_f32_e32 v237, v236, v237
	v_mul_f32_e32 v238, v236, v238
	v_cvt_pk_bf16_f32 v104, v237, v238
	v_lshlrev_b32_e32 v237, 16, v53
	v_and_b32_e32 v238, 0xffff0000, v53
	v_mul_f32_e32 v237, v236, v237
	v_mul_f32_e32 v238, v236, v238
	v_cvt_pk_bf16_f32 v105, v237, v238
	v_lshlrev_b32_e32 v237, 16, v54
	v_and_b32_e32 v238, 0xffff0000, v54
	v_mul_f32_e32 v237, v236, v237
	v_mul_f32_e32 v238, v236, v238
	v_cvt_pk_bf16_f32 v106, v237, v238
	v_lshlrev_b32_e32 v237, 16, v55
	v_and_b32_e32 v238, 0xffff0000, v55
	v_mul_f32_e32 v237, v236, v237
	v_mul_f32_e32 v238, v236, v238
	v_cvt_pk_bf16_f32 v107, v237, v238
	s_waitcnt lgkmcnt(4)
	s_nop 0
	v_mfma_f32_16x16x32_bf16 v[16:19], v[104:107], v[64:67], v[16:19]
	v_mfma_f32_16x16x32_bf16 v[20:23], v[104:107], v[68:71], v[20:23]
	v_mfma_f32_16x16x32_bf16 v[24:27], v[104:107], v[72:75], v[24:27]
	v_mfma_f32_16x16x32_bf16 v[28:31], v[104:107], v[76:79], v[28:31]
	ds_read_b128 v[64:67], v170 offset:192
	ds_read_b128 v[68:71], v170 offset:4544
	ds_read_b128 v[72:75], v170 offset:8896
	ds_read_b128 v[76:79], v170 offset:13248
	v_lshlrev_b32_e32 v237, 16, v56
	v_and_b32_e32 v238, 0xffff0000, v56
	v_mul_f32_e32 v237, v236, v237
	v_mul_f32_e32 v238, v236, v238
	v_cvt_pk_bf16_f32 v104, v237, v238
	v_lshlrev_b32_e32 v237, 16, v57
	v_and_b32_e32 v238, 0xffff0000, v57
	v_mul_f32_e32 v237, v236, v237
	v_mul_f32_e32 v238, v236, v238
	v_cvt_pk_bf16_f32 v105, v237, v238
	v_lshlrev_b32_e32 v237, 16, v58
	v_and_b32_e32 v238, 0xffff0000, v58
	v_mul_f32_e32 v237, v236, v237
	v_mul_f32_e32 v238, v236, v238
	v_cvt_pk_bf16_f32 v106, v237, v238
	v_lshlrev_b32_e32 v237, 16, v59
	v_and_b32_e32 v238, 0xffff0000, v59
	v_mul_f32_e32 v237, v236, v237
	v_mul_f32_e32 v238, v236, v238
	v_cvt_pk_bf16_f32 v107, v237, v238
	s_waitcnt lgkmcnt(4)
	s_nop 0
	v_mfma_f32_16x16x32_bf16 v[16:19], v[104:107], v[108:111], v[16:19]
	v_mfma_f32_16x16x32_bf16 v[20:23], v[104:107], v[112:115], v[20:23]
	v_mfma_f32_16x16x32_bf16 v[24:27], v[104:107], v[116:119], v[24:27]
	v_mfma_f32_16x16x32_bf16 v[28:31], v[104:107], v[120:123], v[28:31]
	ds_read_b128 v[108:111], v170 offset:17408
	ds_read_b128 v[112:115], v170 offset:21760
	ds_read_b128 v[116:119], v170 offset:26112
	ds_read_b128 v[120:123], v170 offset:30464
	v_lshlrev_b32_e32 v237, 16, v60
	v_and_b32_e32 v238, 0xffff0000, v60
	v_mul_f32_e32 v237, v236, v237
	v_mul_f32_e32 v238, v236, v238
	v_cvt_pk_bf16_f32 v104, v237, v238
	v_lshlrev_b32_e32 v237, 16, v61
	v_and_b32_e32 v238, 0xffff0000, v61
	v_mul_f32_e32 v237, v236, v237
	v_mul_f32_e32 v238, v236, v238
	v_cvt_pk_bf16_f32 v105, v237, v238
	v_lshlrev_b32_e32 v237, 16, v62
	v_and_b32_e32 v238, 0xffff0000, v62
	v_mul_f32_e32 v237, v236, v237
	v_mul_f32_e32 v238, v236, v238
	v_cvt_pk_bf16_f32 v106, v237, v238
	v_lshlrev_b32_e32 v237, 16, v63
	v_and_b32_e32 v238, 0xffff0000, v63
	v_mul_f32_e32 v237, v236, v237
	v_mul_f32_e32 v238, v236, v238
	v_cvt_pk_bf16_f32 v107, v237, v238
	s_waitcnt lgkmcnt(4)
	s_nop 0
	v_mfma_f32_16x16x32_bf16 v[16:19], v[104:107], v[64:67], v[16:19]
	v_mfma_f32_16x16x32_bf16 v[20:23], v[104:107], v[68:71], v[20:23]
	v_mfma_f32_16x16x32_bf16 v[24:27], v[104:107], v[72:75], v[24:27]
	v_mfma_f32_16x16x32_bf16 v[28:31], v[104:107], v[76:79], v[28:31]
	ds_read_b128 v[64:67], v170 offset:17472
	ds_read_b128 v[68:71], v170 offset:21824
	ds_read_b128 v[72:75], v170 offset:26176
	ds_read_b128 v[76:79], v170 offset:30528
	v_mul_f32_e32 v236, 0x3fb8aa3b, v157
	v_exp_f32_e32 v236, v236
	s_nop 0
	v_lshlrev_b32_e32 v237, 16, v48
	v_and_b32_e32 v238, 0xffff0000, v48
	v_mul_f32_e32 v237, v236, v237
	v_mul_f32_e32 v238, v236, v238
	v_cvt_pk_bf16_f32 v104, v237, v238
	v_lshlrev_b32_e32 v237, 16, v49
	v_and_b32_e32 v238, 0xffff0000, v49
	v_mul_f32_e32 v237, v236, v237
	v_mul_f32_e32 v238, v236, v238
	v_cvt_pk_bf16_f32 v105, v237, v238
	v_lshlrev_b32_e32 v237, 16, v50
	v_and_b32_e32 v238, 0xffff0000, v50
	v_mul_f32_e32 v237, v236, v237
	v_mul_f32_e32 v238, v236, v238
	v_cvt_pk_bf16_f32 v106, v237, v238
	v_lshlrev_b32_e32 v237, 16, v51
	v_and_b32_e32 v238, 0xffff0000, v51
	v_mul_f32_e32 v237, v236, v237
	v_mul_f32_e32 v238, v236, v238
	v_cvt_pk_bf16_f32 v107, v237, v238
	s_waitcnt lgkmcnt(4)
	s_nop 0
	v_mfma_f32_16x16x32_bf16 v[16:19], v[104:107], v[108:111], v[16:19]
	v_mfma_f32_16x16x32_bf16 v[20:23], v[104:107], v[112:115], v[20:23]
	v_mfma_f32_16x16x32_bf16 v[24:27], v[104:107], v[116:119], v[24:27]
	v_mfma_f32_16x16x32_bf16 v[28:31], v[104:107], v[120:123], v[28:31]
	ds_read_b128 v[108:111], v170 offset:17536
	ds_read_b128 v[112:115], v170 offset:21888
	ds_read_b128 v[116:119], v170 offset:26240
	ds_read_b128 v[120:123], v170 offset:30592
	v_lshlrev_b32_e32 v237, 16, v52
	v_and_b32_e32 v238, 0xffff0000, v52
	v_mul_f32_e32 v237, v236, v237
	v_mul_f32_e32 v238, v236, v238
	v_cvt_pk_bf16_f32 v104, v237, v238
	v_lshlrev_b32_e32 v237, 16, v53
	v_and_b32_e32 v238, 0xffff0000, v53
	v_mul_f32_e32 v237, v236, v237
	v_mul_f32_e32 v238, v236, v238
	v_cvt_pk_bf16_f32 v105, v237, v238
	v_lshlrev_b32_e32 v237, 16, v54
	v_and_b32_e32 v238, 0xffff0000, v54
	v_mul_f32_e32 v237, v236, v237
	v_mul_f32_e32 v238, v236, v238
	v_cvt_pk_bf16_f32 v106, v237, v238
	v_lshlrev_b32_e32 v237, 16, v55
	v_and_b32_e32 v238, 0xffff0000, v55
	v_mul_f32_e32 v237, v236, v237
	v_mul_f32_e32 v238, v236, v238
	v_cvt_pk_bf16_f32 v107, v237, v238
	s_waitcnt lgkmcnt(4)
	s_nop 0
	v_mfma_f32_16x16x32_bf16 v[16:19], v[104:107], v[64:67], v[16:19]
	v_mfma_f32_16x16x32_bf16 v[20:23], v[104:107], v[68:71], v[20:23]
	v_mfma_f32_16x16x32_bf16 v[24:27], v[104:107], v[72:75], v[24:27]
	v_mfma_f32_16x16x32_bf16 v[28:31], v[104:107], v[76:79], v[28:31]
	ds_read_b128 v[64:67], v170 offset:17600
	ds_read_b128 v[68:71], v170 offset:21952
	ds_read_b128 v[72:75], v170 offset:26304
	ds_read_b128 v[76:79], v170 offset:30656
	v_lshlrev_b32_e32 v237, 16, v56
	v_and_b32_e32 v238, 0xffff0000, v56
	v_mul_f32_e32 v237, v236, v237
	v_mul_f32_e32 v238, v236, v238
	v_cvt_pk_bf16_f32 v104, v237, v238
	v_lshlrev_b32_e32 v237, 16, v57
	v_and_b32_e32 v238, 0xffff0000, v57
	v_mul_f32_e32 v237, v236, v237
	v_mul_f32_e32 v238, v236, v238
	v_cvt_pk_bf16_f32 v105, v237, v238
	v_lshlrev_b32_e32 v237, 16, v58
	v_and_b32_e32 v238, 0xffff0000, v58
	v_mul_f32_e32 v237, v236, v237
	v_mul_f32_e32 v238, v236, v238
	v_cvt_pk_bf16_f32 v106, v237, v238
	v_lshlrev_b32_e32 v237, 16, v59
	v_and_b32_e32 v238, 0xffff0000, v59
	v_mul_f32_e32 v237, v236, v237
	v_mul_f32_e32 v238, v236, v238
	v_cvt_pk_bf16_f32 v107, v237, v238
	s_waitcnt lgkmcnt(4)
	s_nop 0
	v_mfma_f32_16x16x32_bf16 v[16:19], v[104:107], v[108:111], v[16:19]
	v_mfma_f32_16x16x32_bf16 v[20:23], v[104:107], v[112:115], v[20:23]
	v_mfma_f32_16x16x32_bf16 v[24:27], v[104:107], v[116:119], v[24:27]
	v_mfma_f32_16x16x32_bf16 v[28:31], v[104:107], v[120:123], v[28:31]
	v_lshlrev_b32_e32 v237, 16, v60
	v_and_b32_e32 v238, 0xffff0000, v60
	v_mul_f32_e32 v237, v236, v237
	v_mul_f32_e32 v238, v236, v238
	v_cvt_pk_bf16_f32 v104, v237, v238
	v_lshlrev_b32_e32 v237, 16, v61
	v_and_b32_e32 v238, 0xffff0000, v61
	v_mul_f32_e32 v237, v236, v237
	v_mul_f32_e32 v238, v236, v238
	v_cvt_pk_bf16_f32 v105, v237, v238
	v_lshlrev_b32_e32 v237, 16, v62
	v_and_b32_e32 v238, 0xffff0000, v62
	v_mul_f32_e32 v237, v236, v237
	v_mul_f32_e32 v238, v236, v238
	v_cvt_pk_bf16_f32 v106, v237, v238
	v_lshlrev_b32_e32 v237, 16, v63
	v_and_b32_e32 v238, 0xffff0000, v63
	v_mul_f32_e32 v237, v236, v237
	v_mul_f32_e32 v238, v236, v238
	v_cvt_pk_bf16_f32 v107, v237, v238
	s_waitcnt lgkmcnt(0)
	s_nop 0
	v_mfma_f32_16x16x32_bf16 v[16:19], v[104:107], v[64:67], v[16:19]
	v_mfma_f32_16x16x32_bf16 v[20:23], v[104:107], v[68:71], v[20:23]
	v_mfma_f32_16x16x32_bf16 v[24:27], v[104:107], v[72:75], v[24:27]
	v_mfma_f32_16x16x32_bf16 v[28:31], v[104:107], v[76:79], v[28:31]
	s_waitcnt lgkmcnt(0)
	s_barrier
	s_waitcnt vmcnt(0)
	ds_write_b128 v5, v[124:127]
	ds_write_b128 v5, v[128:131] offset:8704
	ds_write_b128 v5, v[132:135] offset:17408
	ds_write_b128 v5, v[136:139] offset:26112
	s_waitcnt lgkmcnt(0)
	s_barrier
	ds_read_b128 v[108:111], v170 offset:0
	ds_read_b128 v[112:115], v170 offset:4352
	ds_read_b128 v[116:119], v170 offset:8704
	ds_read_b128 v[120:123], v170 offset:13056
	ds_read_b128 v[64:67], v170 offset:64
	ds_read_b128 v[68:71], v170 offset:4416
	ds_read_b128 v[72:75], v170 offset:8768
	ds_read_b128 v[76:79], v170 offset:13120
	v_mul_f32_e32 v236, 0x3fb8aa3b, v158
	v_exp_f32_e32 v236, v236
	s_nop 0
	v_lshlrev_b32_e32 v237, 16, v48
	v_and_b32_e32 v238, 0xffff0000, v48
	v_mul_f32_e32 v237, v236, v237
	v_mul_f32_e32 v238, v236, v238
	v_cvt_pk_bf16_f32 v104, v237, v238
	v_lshlrev_b32_e32 v237, 16, v49
	v_and_b32_e32 v238, 0xffff0000, v49
	v_mul_f32_e32 v237, v236, v237
	v_mul_f32_e32 v238, v236, v238
	v_cvt_pk_bf16_f32 v105, v237, v238
	v_lshlrev_b32_e32 v237, 16, v50
	v_and_b32_e32 v238, 0xffff0000, v50
	v_mul_f32_e32 v237, v236, v237
	v_mul_f32_e32 v238, v236, v238
	v_cvt_pk_bf16_f32 v106, v237, v238
	v_lshlrev_b32_e32 v237, 16, v51
	v_and_b32_e32 v238, 0xffff0000, v51
	v_mul_f32_e32 v237, v236, v237
	v_mul_f32_e32 v238, v236, v238
	v_cvt_pk_bf16_f32 v107, v237, v238
	s_waitcnt lgkmcnt(4)
	s_nop 0
	v_mfma_f32_16x16x32_bf16 v[32:35], v[104:107], v[108:111], v[32:35]
	v_mfma_f32_16x16x32_bf16 v[36:39], v[104:107], v[112:115], v[36:39]
	v_mfma_f32_16x16x32_bf16 v[40:43], v[104:107], v[116:119], v[40:43]
	v_mfma_f32_16x16x32_bf16 v[44:47], v[104:107], v[120:123], v[44:47]
	ds_read_b128 v[108:111], v170 offset:128
	ds_read_b128 v[112:115], v170 offset:4480
	ds_read_b128 v[116:119], v170 offset:8832
	ds_read_b128 v[120:123], v170 offset:13184
	v_lshlrev_b32_e32 v237, 16, v52
	v_and_b32_e32 v238, 0xffff0000, v52
	v_mul_f32_e32 v237, v236, v237
	v_mul_f32_e32 v238, v236, v238
	v_cvt_pk_bf16_f32 v104, v237, v238
	v_lshlrev_b32_e32 v237, 16, v53
	v_and_b32_e32 v238, 0xffff0000, v53
	v_mul_f32_e32 v237, v236, v237
	v_mul_f32_e32 v238, v236, v238
	v_cvt_pk_bf16_f32 v105, v237, v238
	v_lshlrev_b32_e32 v237, 16, v54
	v_and_b32_e32 v238, 0xffff0000, v54
	v_mul_f32_e32 v237, v236, v237
	v_mul_f32_e32 v238, v236, v238
	v_cvt_pk_bf16_f32 v106, v237, v238
	v_lshlrev_b32_e32 v237, 16, v55
	v_and_b32_e32 v238, 0xffff0000, v55
	v_mul_f32_e32 v237, v236, v237
	v_mul_f32_e32 v238, v236, v238
	v_cvt_pk_bf16_f32 v107, v237, v238
	s_waitcnt lgkmcnt(4)
	s_nop 0
	v_mfma_f32_16x16x32_bf16 v[32:35], v[104:107], v[64:67], v[32:35]
	v_mfma_f32_16x16x32_bf16 v[36:39], v[104:107], v[68:71], v[36:39]
	v_mfma_f32_16x16x32_bf16 v[40:43], v[104:107], v[72:75], v[40:43]
	v_mfma_f32_16x16x32_bf16 v[44:47], v[104:107], v[76:79], v[44:47]
	ds_read_b128 v[64:67], v170 offset:192
	ds_read_b128 v[68:71], v170 offset:4544
	ds_read_b128 v[72:75], v170 offset:8896
	ds_read_b128 v[76:79], v170 offset:13248
	v_lshlrev_b32_e32 v237, 16, v56
	v_and_b32_e32 v238, 0xffff0000, v56
	v_mul_f32_e32 v237, v236, v237
	v_mul_f32_e32 v238, v236, v238
	v_cvt_pk_bf16_f32 v104, v237, v238
	v_lshlrev_b32_e32 v237, 16, v57
	v_and_b32_e32 v238, 0xffff0000, v57
	v_mul_f32_e32 v237, v236, v237
	v_mul_f32_e32 v238, v236, v238
	v_cvt_pk_bf16_f32 v105, v237, v238
	v_lshlrev_b32_e32 v237, 16, v58
	v_and_b32_e32 v238, 0xffff0000, v58
	v_mul_f32_e32 v237, v236, v237
	v_mul_f32_e32 v238, v236, v238
	v_cvt_pk_bf16_f32 v106, v237, v238
	v_lshlrev_b32_e32 v237, 16, v59
	v_and_b32_e32 v238, 0xffff0000, v59
	v_mul_f32_e32 v237, v236, v237
	v_mul_f32_e32 v238, v236, v238
	v_cvt_pk_bf16_f32 v107, v237, v238
	s_waitcnt lgkmcnt(4)
	s_nop 0
	v_mfma_f32_16x16x32_bf16 v[32:35], v[104:107], v[108:111], v[32:35]
	v_mfma_f32_16x16x32_bf16 v[36:39], v[104:107], v[112:115], v[36:39]
	v_mfma_f32_16x16x32_bf16 v[40:43], v[104:107], v[116:119], v[40:43]
	v_mfma_f32_16x16x32_bf16 v[44:47], v[104:107], v[120:123], v[44:47]
	ds_read_b128 v[108:111], v170 offset:17408
	ds_read_b128 v[112:115], v170 offset:21760
	ds_read_b128 v[116:119], v170 offset:26112
	ds_read_b128 v[120:123], v170 offset:30464
	v_lshlrev_b32_e32 v237, 16, v60
	v_and_b32_e32 v238, 0xffff0000, v60
	v_mul_f32_e32 v237, v236, v237
	v_mul_f32_e32 v238, v236, v238
	v_cvt_pk_bf16_f32 v104, v237, v238
	v_lshlrev_b32_e32 v237, 16, v61
	v_and_b32_e32 v238, 0xffff0000, v61
	v_mul_f32_e32 v237, v236, v237
	v_mul_f32_e32 v238, v236, v238
	v_cvt_pk_bf16_f32 v105, v237, v238
	v_lshlrev_b32_e32 v237, 16, v62
	v_and_b32_e32 v238, 0xffff0000, v62
	v_mul_f32_e32 v237, v236, v237
	v_mul_f32_e32 v238, v236, v238
	v_cvt_pk_bf16_f32 v106, v237, v238
	v_lshlrev_b32_e32 v237, 16, v63
	v_and_b32_e32 v238, 0xffff0000, v63
	v_mul_f32_e32 v237, v236, v237
	v_mul_f32_e32 v238, v236, v238
	v_cvt_pk_bf16_f32 v107, v237, v238
	s_waitcnt lgkmcnt(4)
	s_nop 0
	v_mfma_f32_16x16x32_bf16 v[32:35], v[104:107], v[64:67], v[32:35]
	v_mfma_f32_16x16x32_bf16 v[36:39], v[104:107], v[68:71], v[36:39]
	v_mfma_f32_16x16x32_bf16 v[40:43], v[104:107], v[72:75], v[40:43]
	v_mfma_f32_16x16x32_bf16 v[44:47], v[104:107], v[76:79], v[44:47]
	ds_read_b128 v[64:67], v170 offset:17472
	ds_read_b128 v[68:71], v170 offset:21824
	ds_read_b128 v[72:75], v170 offset:26176
	ds_read_b128 v[76:79], v170 offset:30528
	v_mul_f32_e32 v236, 0x3fb8aa3b, v159
	v_exp_f32_e32 v236, v236
	s_nop 0
	v_lshlrev_b32_e32 v237, 16, v48
	v_and_b32_e32 v238, 0xffff0000, v48
	v_mul_f32_e32 v237, v236, v237
	v_mul_f32_e32 v238, v236, v238
	v_cvt_pk_bf16_f32 v104, v237, v238
	v_lshlrev_b32_e32 v237, 16, v49
	v_and_b32_e32 v238, 0xffff0000, v49
	v_mul_f32_e32 v237, v236, v237
	v_mul_f32_e32 v238, v236, v238
	v_cvt_pk_bf16_f32 v105, v237, v238
	v_lshlrev_b32_e32 v237, 16, v50
	v_and_b32_e32 v238, 0xffff0000, v50
	v_mul_f32_e32 v237, v236, v237
	v_mul_f32_e32 v238, v236, v238
	v_cvt_pk_bf16_f32 v106, v237, v238
	v_lshlrev_b32_e32 v237, 16, v51
	v_and_b32_e32 v238, 0xffff0000, v51
	v_mul_f32_e32 v237, v236, v237
	v_mul_f32_e32 v238, v236, v238
	v_cvt_pk_bf16_f32 v107, v237, v238
	s_waitcnt lgkmcnt(4)
	s_nop 0
	v_mfma_f32_16x16x32_bf16 v[32:35], v[104:107], v[108:111], v[32:35]
	v_mfma_f32_16x16x32_bf16 v[36:39], v[104:107], v[112:115], v[36:39]
	v_mfma_f32_16x16x32_bf16 v[40:43], v[104:107], v[116:119], v[40:43]
	v_mfma_f32_16x16x32_bf16 v[44:47], v[104:107], v[120:123], v[44:47]
	ds_read_b128 v[108:111], v170 offset:17536
	ds_read_b128 v[112:115], v170 offset:21888
	ds_read_b128 v[116:119], v170 offset:26240
	ds_read_b128 v[120:123], v170 offset:30592
	v_lshlrev_b32_e32 v237, 16, v52
	v_and_b32_e32 v238, 0xffff0000, v52
	v_mul_f32_e32 v237, v236, v237
	v_mul_f32_e32 v238, v236, v238
	v_cvt_pk_bf16_f32 v104, v237, v238
	v_lshlrev_b32_e32 v237, 16, v53
	v_and_b32_e32 v238, 0xffff0000, v53
	v_mul_f32_e32 v237, v236, v237
	v_mul_f32_e32 v238, v236, v238
	v_cvt_pk_bf16_f32 v105, v237, v238
	v_lshlrev_b32_e32 v237, 16, v54
	v_and_b32_e32 v238, 0xffff0000, v54
	v_mul_f32_e32 v237, v236, v237
	v_mul_f32_e32 v238, v236, v238
	v_cvt_pk_bf16_f32 v106, v237, v238
	v_lshlrev_b32_e32 v237, 16, v55
	v_and_b32_e32 v238, 0xffff0000, v55
	v_mul_f32_e32 v237, v236, v237
	v_mul_f32_e32 v238, v236, v238
	v_cvt_pk_bf16_f32 v107, v237, v238
	s_waitcnt lgkmcnt(4)
	s_nop 0
	v_mfma_f32_16x16x32_bf16 v[32:35], v[104:107], v[64:67], v[32:35]
	v_mfma_f32_16x16x32_bf16 v[36:39], v[104:107], v[68:71], v[36:39]
	v_mfma_f32_16x16x32_bf16 v[40:43], v[104:107], v[72:75], v[40:43]
	v_mfma_f32_16x16x32_bf16 v[44:47], v[104:107], v[76:79], v[44:47]
	ds_read_b128 v[64:67], v170 offset:17600
	ds_read_b128 v[68:71], v170 offset:21952
	ds_read_b128 v[72:75], v170 offset:26304
	ds_read_b128 v[76:79], v170 offset:30656
	v_lshlrev_b32_e32 v237, 16, v56
	v_and_b32_e32 v238, 0xffff0000, v56
	v_mul_f32_e32 v237, v236, v237
	v_mul_f32_e32 v238, v236, v238
	v_cvt_pk_bf16_f32 v104, v237, v238
	v_lshlrev_b32_e32 v237, 16, v57
	v_and_b32_e32 v238, 0xffff0000, v57
	v_mul_f32_e32 v237, v236, v237
	v_mul_f32_e32 v238, v236, v238
	v_cvt_pk_bf16_f32 v105, v237, v238
	v_lshlrev_b32_e32 v237, 16, v58
	v_and_b32_e32 v238, 0xffff0000, v58
	v_mul_f32_e32 v237, v236, v237
	v_mul_f32_e32 v238, v236, v238
	v_cvt_pk_bf16_f32 v106, v237, v238
	v_lshlrev_b32_e32 v237, 16, v59
	v_and_b32_e32 v238, 0xffff0000, v59
	v_mul_f32_e32 v237, v236, v237
	v_mul_f32_e32 v238, v236, v238
	v_cvt_pk_bf16_f32 v107, v237, v238
	s_waitcnt lgkmcnt(4)
	s_nop 0
	v_mfma_f32_16x16x32_bf16 v[32:35], v[104:107], v[108:111], v[32:35]
	v_mfma_f32_16x16x32_bf16 v[36:39], v[104:107], v[112:115], v[36:39]
	v_mfma_f32_16x16x32_bf16 v[40:43], v[104:107], v[116:119], v[40:43]
	v_mfma_f32_16x16x32_bf16 v[44:47], v[104:107], v[120:123], v[44:47]
	v_lshlrev_b32_e32 v237, 16, v60
	v_and_b32_e32 v238, 0xffff0000, v60
	v_mul_f32_e32 v237, v236, v237
	v_mul_f32_e32 v238, v236, v238
	v_cvt_pk_bf16_f32 v104, v237, v238
	v_lshlrev_b32_e32 v237, 16, v61
	v_and_b32_e32 v238, 0xffff0000, v61
	v_mul_f32_e32 v237, v236, v237
	v_mul_f32_e32 v238, v236, v238
	v_cvt_pk_bf16_f32 v105, v237, v238
	v_lshlrev_b32_e32 v237, 16, v62
	v_and_b32_e32 v238, 0xffff0000, v62
	v_mul_f32_e32 v237, v236, v237
	v_mul_f32_e32 v238, v236, v238
	v_cvt_pk_bf16_f32 v106, v237, v238
	v_lshlrev_b32_e32 v237, 16, v63
	v_and_b32_e32 v238, 0xffff0000, v63
	v_mul_f32_e32 v237, v236, v237
	v_mul_f32_e32 v238, v236, v238
	v_cvt_pk_bf16_f32 v107, v237, v238
	s_waitcnt lgkmcnt(0)
	s_nop 0
	v_mfma_f32_16x16x32_bf16 v[32:35], v[104:107], v[64:67], v[32:35]
	v_mfma_f32_16x16x32_bf16 v[36:39], v[104:107], v[68:71], v[36:39]
	v_mfma_f32_16x16x32_bf16 v[40:43], v[104:107], v[72:75], v[40:43]
	v_mfma_f32_16x16x32_bf16 v[44:47], v[104:107], v[76:79], v[44:47]
	global_load_dword v64, v234, s[50:51] offset:0
	global_load_dword v65, v234, s[50:51] offset:64
	global_load_dword v66, v234, s[50:51] offset:128
	global_load_dword v67, v234, s[50:51] offset:192
	global_load_dword v68, v234, s[50:51] offset:256
	global_load_dword v69, v234, s[50:51] offset:320
	global_load_dword v70, v234, s[50:51] offset:384
	global_load_dword v71, v234, s[50:51] offset:448
	global_load_dword v72, v234, s[50:51] offset:512
	global_load_dword v73, v234, s[50:51] offset:576
	global_load_dword v74, v234, s[50:51] offset:640
	global_load_dword v75, v234, s[50:51] offset:704
	global_load_dword v76, v234, s[50:51] offset:768
	global_load_dword v77, v234, s[50:51] offset:832
	global_load_dword v78, v234, s[50:51] offset:896
	global_load_dword v79, v234, s[50:51] offset:960
	s_nop 7
	ds_read_b64_tr_b16 v[140:141], v174 offset:0
	ds_read_b64_tr_b16 v[148:149], v227 offset:0
	ds_read_b64_tr_b16 v[142:143], v174 offset:32
	ds_read_b64_tr_b16 v[150:151], v227 offset:32
	ds_read_b64_tr_b16 v[144:145], v174 offset:64
	ds_read_b64_tr_b16 v[152:153], v227 offset:64
	ds_read_b64_tr_b16 v[146:147], v174 offset:96
	ds_read_b64_tr_b16 v[154:155], v227 offset:96
	s_waitcnt lgkmcnt(6)
	v_lshlrev_b32_e32 v236, 16, v140
	v_lshlrev_b32_e32 v237, 16, v148
	v_fma_f32 v238, s62, v236, v16
	v_mul_f32_e32 v239, 0xbfb8aa3b, v237
	v_exp_f32_e32 v239, v239
	s_nop 0
	v_add_f32_e32 v239, 1.0, v239
	v_div_scale_f32 v240, s[0:1], v239, v239, v237
	v_rcp_f32_e32 v241, v240
	s_nop 0
	v_fma_f32 v242, -v240, v241, 1.0
	v_fmac_f32_e32 v241, v242, v241
	v_div_scale_f32 v242, vcc, v237, v239, v237
	v_mul_f32_e32 v243, v242, v241
	v_fma_f32 v244, -v240, v243, v242
	v_fmac_f32_e32 v243, v244, v241
	v_fma_f32 v240, -v240, v243, v242
	v_div_fmas_f32 v240, v240, v241, v243
	v_div_fixup_f32 v240, v240, v239, v237
	v_mul_f32_e32 v246, v238, v240
	v_fmac_f32_e32 v228, v246, v246
	v_and_b32_e32 v236, 0xffff0000, v140
	v_and_b32_e32 v237, 0xffff0000, v148
	v_fma_f32 v238, s62, v236, v17
	v_mul_f32_e32 v239, 0xbfb8aa3b, v237
	v_exp_f32_e32 v239, v239
	s_nop 0
	v_add_f32_e32 v239, 1.0, v239
	v_div_scale_f32 v240, s[0:1], v239, v239, v237
	v_rcp_f32_e32 v241, v240
	s_nop 0
	v_fma_f32 v242, -v240, v241, 1.0
	v_fmac_f32_e32 v241, v242, v241
	v_div_scale_f32 v242, vcc, v237, v239, v237
	v_mul_f32_e32 v243, v242, v241
	v_fma_f32 v244, -v240, v243, v242
	v_fmac_f32_e32 v243, v244, v241
	v_fma_f32 v240, -v240, v243, v242
	v_div_fmas_f32 v240, v240, v241, v243
	v_div_fixup_f32 v240, v240, v239, v237
	v_mul_f32_e32 v247, v238, v240
	v_fmac_f32_e32 v229, v247, v247
	v_lshlrev_b32_e32 v236, 16, v141
	v_lshlrev_b32_e32 v237, 16, v149
	v_fma_f32 v238, s62, v236, v18
	v_mul_f32_e32 v239, 0xbfb8aa3b, v237
	v_exp_f32_e32 v239, v239
	s_nop 0
	v_add_f32_e32 v239, 1.0, v239
	v_div_scale_f32 v240, s[0:1], v239, v239, v237
	v_rcp_f32_e32 v241, v240
	s_nop 0
	v_fma_f32 v242, -v240, v241, 1.0
	v_fmac_f32_e32 v241, v242, v241
	v_div_scale_f32 v242, vcc, v237, v239, v237
	v_mul_f32_e32 v243, v242, v241
	v_fma_f32 v244, -v240, v243, v242
	v_fmac_f32_e32 v243, v244, v241
	v_fma_f32 v240, -v240, v243, v242
	v_div_fmas_f32 v240, v240, v241, v243
	v_div_fixup_f32 v240, v240, v239, v237
	v_mul_f32_e32 v248, v238, v240
	v_fmac_f32_e32 v230, v248, v248
	v_and_b32_e32 v236, 0xffff0000, v141
	v_and_b32_e32 v237, 0xffff0000, v149
	v_fma_f32 v238, s62, v236, v19
	v_mul_f32_e32 v239, 0xbfb8aa3b, v237
	v_exp_f32_e32 v239, v239
	s_nop 0
	v_add_f32_e32 v239, 1.0, v239
	v_div_scale_f32 v240, s[0:1], v239, v239, v237
	v_rcp_f32_e32 v241, v240
	s_nop 0
	v_fma_f32 v242, -v240, v241, 1.0
	v_fmac_f32_e32 v241, v242, v241
	v_div_scale_f32 v242, vcc, v237, v239, v237
	v_mul_f32_e32 v243, v242, v241
	v_fma_f32 v244, -v240, v243, v242
	v_fmac_f32_e32 v243, v244, v241
	v_fma_f32 v240, -v240, v243, v242
	v_div_fmas_f32 v240, v240, v241, v243
	v_div_fixup_f32 v240, v240, v239, v237
	v_mul_f32_e32 v249, v238, v240
	v_fmac_f32_e32 v231, v249, v249
	v_cvt_pk_bf16_f32 v204, v246, v247
	v_cvt_pk_bf16_f32 v205, v248, v249
	s_waitcnt lgkmcnt(4)
	v_lshlrev_b32_e32 v236, 16, v142
	v_lshlrev_b32_e32 v237, 16, v150
	v_fma_f32 v238, s62, v236, v20
	v_mul_f32_e32 v239, 0xbfb8aa3b, v237
	v_exp_f32_e32 v239, v239
	s_nop 0
	v_add_f32_e32 v239, 1.0, v239
	v_div_scale_f32 v240, s[0:1], v239, v239, v237
	v_rcp_f32_e32 v241, v240
	s_nop 0
	v_fma_f32 v242, -v240, v241, 1.0
	v_fmac_f32_e32 v241, v242, v241
	v_div_scale_f32 v242, vcc, v237, v239, v237
	v_mul_f32_e32 v243, v242, v241
	v_fma_f32 v244, -v240, v243, v242
	v_fmac_f32_e32 v243, v244, v241
	v_fma_f32 v240, -v240, v243, v242
	v_div_fmas_f32 v240, v240, v241, v243
	v_div_fixup_f32 v240, v240, v239, v237
	v_mul_f32_e32 v246, v238, v240
	v_fmac_f32_e32 v228, v246, v246
	v_and_b32_e32 v236, 0xffff0000, v142
	v_and_b32_e32 v237, 0xffff0000, v150
	v_fma_f32 v238, s62, v236, v21
	v_mul_f32_e32 v239, 0xbfb8aa3b, v237
	v_exp_f32_e32 v239, v239
	s_nop 0
	v_add_f32_e32 v239, 1.0, v239
	v_div_scale_f32 v240, s[0:1], v239, v239, v237
	v_rcp_f32_e32 v241, v240
	s_nop 0
	v_fma_f32 v242, -v240, v241, 1.0
	v_fmac_f32_e32 v241, v242, v241
	v_div_scale_f32 v242, vcc, v237, v239, v237
	v_mul_f32_e32 v243, v242, v241
	v_fma_f32 v244, -v240, v243, v242
	v_fmac_f32_e32 v243, v244, v241
	v_fma_f32 v240, -v240, v243, v242
	v_div_fmas_f32 v240, v240, v241, v243
	v_div_fixup_f32 v240, v240, v239, v237
	v_mul_f32_e32 v247, v238, v240
	v_fmac_f32_e32 v229, v247, v247
	v_lshlrev_b32_e32 v236, 16, v143
	v_lshlrev_b32_e32 v237, 16, v151
	v_fma_f32 v238, s62, v236, v22
	v_mul_f32_e32 v239, 0xbfb8aa3b, v237
	v_exp_f32_e32 v239, v239
	s_nop 0
	v_add_f32_e32 v239, 1.0, v239
	v_div_scale_f32 v240, s[0:1], v239, v239, v237
	v_rcp_f32_e32 v241, v240
	s_nop 0
	v_fma_f32 v242, -v240, v241, 1.0
	v_fmac_f32_e32 v241, v242, v241
	v_div_scale_f32 v242, vcc, v237, v239, v237
	v_mul_f32_e32 v243, v242, v241
	v_fma_f32 v244, -v240, v243, v242
	v_fmac_f32_e32 v243, v244, v241
	v_fma_f32 v240, -v240, v243, v242
	v_div_fmas_f32 v240, v240, v241, v243
	v_div_fixup_f32 v240, v240, v239, v237
	v_mul_f32_e32 v248, v238, v240
	v_fmac_f32_e32 v230, v248, v248
	v_and_b32_e32 v236, 0xffff0000, v143
	v_and_b32_e32 v237, 0xffff0000, v151
	v_fma_f32 v238, s62, v236, v23
	v_mul_f32_e32 v239, 0xbfb8aa3b, v237
	v_exp_f32_e32 v239, v239
	s_nop 0
	v_add_f32_e32 v239, 1.0, v239
	v_div_scale_f32 v240, s[0:1], v239, v239, v237
	v_rcp_f32_e32 v241, v240
	s_nop 0
	v_fma_f32 v242, -v240, v241, 1.0
	v_fmac_f32_e32 v241, v242, v241
	v_div_scale_f32 v242, vcc, v237, v239, v237
	v_mul_f32_e32 v243, v242, v241
	v_fma_f32 v244, -v240, v243, v242
	v_fmac_f32_e32 v243, v244, v241
	v_fma_f32 v240, -v240, v243, v242
	v_div_fmas_f32 v240, v240, v241, v243
	v_div_fixup_f32 v240, v240, v239, v237
	v_mul_f32_e32 v249, v238, v240
	v_fmac_f32_e32 v231, v249, v249
	v_cvt_pk_bf16_f32 v206, v246, v247
	v_cvt_pk_bf16_f32 v207, v248, v249
	s_waitcnt lgkmcnt(2)
	v_lshlrev_b32_e32 v236, 16, v144
	v_lshlrev_b32_e32 v237, 16, v152
	v_fma_f32 v238, s62, v236, v24
	v_mul_f32_e32 v239, 0xbfb8aa3b, v237
	v_exp_f32_e32 v239, v239
	s_nop 0
	v_add_f32_e32 v239, 1.0, v239
	v_div_scale_f32 v240, s[0:1], v239, v239, v237
	v_rcp_f32_e32 v241, v240
	s_nop 0
	v_fma_f32 v242, -v240, v241, 1.0
	v_fmac_f32_e32 v241, v242, v241
	v_div_scale_f32 v242, vcc, v237, v239, v237
	v_mul_f32_e32 v243, v242, v241
	v_fma_f32 v244, -v240, v243, v242
	v_fmac_f32_e32 v243, v244, v241
	v_fma_f32 v240, -v240, v243, v242
	v_div_fmas_f32 v240, v240, v241, v243
	v_div_fixup_f32 v240, v240, v239, v237
	v_mul_f32_e32 v246, v238, v240
	v_fmac_f32_e32 v228, v246, v246
	v_and_b32_e32 v236, 0xffff0000, v144
	v_and_b32_e32 v237, 0xffff0000, v152
	v_fma_f32 v238, s62, v236, v25
	v_mul_f32_e32 v239, 0xbfb8aa3b, v237
	v_exp_f32_e32 v239, v239
	s_nop 0
	v_add_f32_e32 v239, 1.0, v239
	v_div_scale_f32 v240, s[0:1], v239, v239, v237
	v_rcp_f32_e32 v241, v240
	s_nop 0
	v_fma_f32 v242, -v240, v241, 1.0
	v_fmac_f32_e32 v241, v242, v241
	v_div_scale_f32 v242, vcc, v237, v239, v237
	v_mul_f32_e32 v243, v242, v241
	v_fma_f32 v244, -v240, v243, v242
	v_fmac_f32_e32 v243, v244, v241
	v_fma_f32 v240, -v240, v243, v242
	v_div_fmas_f32 v240, v240, v241, v243
	v_div_fixup_f32 v240, v240, v239, v237
	v_mul_f32_e32 v247, v238, v240
	v_fmac_f32_e32 v229, v247, v247
	v_lshlrev_b32_e32 v236, 16, v145
	v_lshlrev_b32_e32 v237, 16, v153
	v_fma_f32 v238, s62, v236, v26
	v_mul_f32_e32 v239, 0xbfb8aa3b, v237
	v_exp_f32_e32 v239, v239
	s_nop 0
	v_add_f32_e32 v239, 1.0, v239
	v_div_scale_f32 v240, s[0:1], v239, v239, v237
	v_rcp_f32_e32 v241, v240
	s_nop 0
	v_fma_f32 v242, -v240, v241, 1.0
	v_fmac_f32_e32 v241, v242, v241
	v_div_scale_f32 v242, vcc, v237, v239, v237
	v_mul_f32_e32 v243, v242, v241
	v_fma_f32 v244, -v240, v243, v242
	v_fmac_f32_e32 v243, v244, v241
	v_fma_f32 v240, -v240, v243, v242
	v_div_fmas_f32 v240, v240, v241, v243
	v_div_fixup_f32 v240, v240, v239, v237
	v_mul_f32_e32 v248, v238, v240
	v_fmac_f32_e32 v230, v248, v248
	v_and_b32_e32 v236, 0xffff0000, v145
	v_and_b32_e32 v237, 0xffff0000, v153
	v_fma_f32 v238, s62, v236, v27
	v_mul_f32_e32 v239, 0xbfb8aa3b, v237
	v_exp_f32_e32 v239, v239
	s_nop 0
	v_add_f32_e32 v239, 1.0, v239
	v_div_scale_f32 v240, s[0:1], v239, v239, v237
	v_rcp_f32_e32 v241, v240
	s_nop 0
	v_fma_f32 v242, -v240, v241, 1.0
	v_fmac_f32_e32 v241, v242, v241
	v_div_scale_f32 v242, vcc, v237, v239, v237
	v_mul_f32_e32 v243, v242, v241
	v_fma_f32 v244, -v240, v243, v242
	v_fmac_f32_e32 v243, v244, v241
	v_fma_f32 v240, -v240, v243, v242
	v_div_fmas_f32 v240, v240, v241, v243
	v_div_fixup_f32 v240, v240, v239, v237
	v_mul_f32_e32 v249, v238, v240
	v_fmac_f32_e32 v231, v249, v249
	v_cvt_pk_bf16_f32 v208, v246, v247
	v_cvt_pk_bf16_f32 v209, v248, v249
	s_waitcnt lgkmcnt(0)
	v_lshlrev_b32_e32 v236, 16, v146
	v_lshlrev_b32_e32 v237, 16, v154
	v_fma_f32 v238, s62, v236, v28
	v_mul_f32_e32 v239, 0xbfb8aa3b, v237
	v_exp_f32_e32 v239, v239
	s_nop 0
	v_add_f32_e32 v239, 1.0, v239
	v_div_scale_f32 v240, s[0:1], v239, v239, v237
	v_rcp_f32_e32 v241, v240
	s_nop 0
	v_fma_f32 v242, -v240, v241, 1.0
	v_fmac_f32_e32 v241, v242, v241
	v_div_scale_f32 v242, vcc, v237, v239, v237
	v_mul_f32_e32 v243, v242, v241
	v_fma_f32 v244, -v240, v243, v242
	v_fmac_f32_e32 v243, v244, v241
	v_fma_f32 v240, -v240, v243, v242
	v_div_fmas_f32 v240, v240, v241, v243
	v_div_fixup_f32 v240, v240, v239, v237
	v_mul_f32_e32 v246, v238, v240
	v_fmac_f32_e32 v228, v246, v246
	v_and_b32_e32 v236, 0xffff0000, v146
	v_and_b32_e32 v237, 0xffff0000, v154
	v_fma_f32 v238, s62, v236, v29
	v_mul_f32_e32 v239, 0xbfb8aa3b, v237
	v_exp_f32_e32 v239, v239
	s_nop 0
	v_add_f32_e32 v239, 1.0, v239
	v_div_scale_f32 v240, s[0:1], v239, v239, v237
	v_rcp_f32_e32 v241, v240
	s_nop 0
	v_fma_f32 v242, -v240, v241, 1.0
	v_fmac_f32_e32 v241, v242, v241
	v_div_scale_f32 v242, vcc, v237, v239, v237
	v_mul_f32_e32 v243, v242, v241
	v_fma_f32 v244, -v240, v243, v242
	v_fmac_f32_e32 v243, v244, v241
	v_fma_f32 v240, -v240, v243, v242
	v_div_fmas_f32 v240, v240, v241, v243
	v_div_fixup_f32 v240, v240, v239, v237
	v_mul_f32_e32 v247, v238, v240
	v_fmac_f32_e32 v229, v247, v247
	v_lshlrev_b32_e32 v236, 16, v147
	v_lshlrev_b32_e32 v237, 16, v155
	v_fma_f32 v238, s62, v236, v30
	v_mul_f32_e32 v239, 0xbfb8aa3b, v237
	v_exp_f32_e32 v239, v239
	s_nop 0
	v_add_f32_e32 v239, 1.0, v239
	v_div_scale_f32 v240, s[0:1], v239, v239, v237
	v_rcp_f32_e32 v241, v240
	s_nop 0
	v_fma_f32 v242, -v240, v241, 1.0
	v_fmac_f32_e32 v241, v242, v241
	v_div_scale_f32 v242, vcc, v237, v239, v237
	v_mul_f32_e32 v243, v242, v241
	v_fma_f32 v244, -v240, v243, v242
	v_fmac_f32_e32 v243, v244, v241
	v_fma_f32 v240, -v240, v243, v242
	v_div_fmas_f32 v240, v240, v241, v243
	v_div_fixup_f32 v240, v240, v239, v237
	v_mul_f32_e32 v248, v238, v240
	v_fmac_f32_e32 v230, v248, v248
	v_and_b32_e32 v236, 0xffff0000, v147
	v_and_b32_e32 v237, 0xffff0000, v155
	v_fma_f32 v238, s62, v236, v31
	v_mul_f32_e32 v239, 0xbfb8aa3b, v237
	v_exp_f32_e32 v239, v239
	s_nop 0
	v_add_f32_e32 v239, 1.0, v239
	v_div_scale_f32 v240, s[0:1], v239, v239, v237
	v_rcp_f32_e32 v241, v240
	s_nop 0
	v_fma_f32 v242, -v240, v241, 1.0
	v_fmac_f32_e32 v241, v242, v241
	v_div_scale_f32 v242, vcc, v237, v239, v237
	v_mul_f32_e32 v243, v242, v241
	v_fma_f32 v244, -v240, v243, v242
	v_fmac_f32_e32 v243, v244, v241
	v_fma_f32 v240, -v240, v243, v242
	v_div_fmas_f32 v240, v240, v241, v243
	v_div_fixup_f32 v240, v240, v239, v237
	v_mul_f32_e32 v249, v238, v240
	v_fmac_f32_e32 v231, v249, v249
	v_cvt_pk_bf16_f32 v210, v246, v247
	v_cvt_pk_bf16_f32 v211, v248, v249
	ds_read_b64_tr_b16 v[140:141], v174 offset:128
	ds_read_b64_tr_b16 v[148:149], v227 offset:128
	ds_read_b64_tr_b16 v[142:143], v174 offset:160
	ds_read_b64_tr_b16 v[150:151], v227 offset:160
	ds_read_b64_tr_b16 v[144:145], v174 offset:192
	ds_read_b64_tr_b16 v[152:153], v227 offset:192
	ds_read_b64_tr_b16 v[146:147], v174 offset:224
	ds_read_b64_tr_b16 v[154:155], v227 offset:224
	s_waitcnt lgkmcnt(6)
	v_lshlrev_b32_e32 v236, 16, v140
	v_lshlrev_b32_e32 v237, 16, v148
	v_fma_f32 v238, s63, v236, v32
	v_mul_f32_e32 v239, 0xbfb8aa3b, v237
	v_exp_f32_e32 v239, v239
	s_nop 0
	v_add_f32_e32 v239, 1.0, v239
	v_div_scale_f32 v240, s[0:1], v239, v239, v237
	v_rcp_f32_e32 v241, v240
	s_nop 0
	v_fma_f32 v242, -v240, v241, 1.0
	v_fmac_f32_e32 v241, v242, v241
	v_div_scale_f32 v242, vcc, v237, v239, v237
	v_mul_f32_e32 v243, v242, v241
	v_fma_f32 v244, -v240, v243, v242
	v_fmac_f32_e32 v243, v244, v241
	v_fma_f32 v240, -v240, v243, v242
	v_div_fmas_f32 v240, v240, v241, v243
	v_div_fixup_f32 v240, v240, v239, v237
	v_mul_f32_e32 v246, v238, v240
	v_fmac_f32_e32 v228, v246, v246
	v_and_b32_e32 v236, 0xffff0000, v140
	v_and_b32_e32 v237, 0xffff0000, v148
	v_fma_f32 v238, s63, v236, v33
	v_mul_f32_e32 v239, 0xbfb8aa3b, v237
	v_exp_f32_e32 v239, v239
	s_nop 0
	v_add_f32_e32 v239, 1.0, v239
	v_div_scale_f32 v240, s[0:1], v239, v239, v237
	v_rcp_f32_e32 v241, v240
	s_nop 0
	v_fma_f32 v242, -v240, v241, 1.0
	v_fmac_f32_e32 v241, v242, v241
	v_div_scale_f32 v242, vcc, v237, v239, v237
	v_mul_f32_e32 v243, v242, v241
	v_fma_f32 v244, -v240, v243, v242
	v_fmac_f32_e32 v243, v244, v241
	v_fma_f32 v240, -v240, v243, v242
	v_div_fmas_f32 v240, v240, v241, v243
	v_div_fixup_f32 v240, v240, v239, v237
	v_mul_f32_e32 v247, v238, v240
	v_fmac_f32_e32 v229, v247, v247
	v_lshlrev_b32_e32 v236, 16, v141
	v_lshlrev_b32_e32 v237, 16, v149
	v_fma_f32 v238, s63, v236, v34
	v_mul_f32_e32 v239, 0xbfb8aa3b, v237
	v_exp_f32_e32 v239, v239
	s_nop 0
	v_add_f32_e32 v239, 1.0, v239
	v_div_scale_f32 v240, s[0:1], v239, v239, v237
	v_rcp_f32_e32 v241, v240
	s_nop 0
	v_fma_f32 v242, -v240, v241, 1.0
	v_fmac_f32_e32 v241, v242, v241
	v_div_scale_f32 v242, vcc, v237, v239, v237
	v_mul_f32_e32 v243, v242, v241
	v_fma_f32 v244, -v240, v243, v242
	v_fmac_f32_e32 v243, v244, v241
	v_fma_f32 v240, -v240, v243, v242
	v_div_fmas_f32 v240, v240, v241, v243
	v_div_fixup_f32 v240, v240, v239, v237
	v_mul_f32_e32 v248, v238, v240
	v_fmac_f32_e32 v230, v248, v248
	v_and_b32_e32 v236, 0xffff0000, v141
	v_and_b32_e32 v237, 0xffff0000, v149
	v_fma_f32 v238, s63, v236, v35
	v_mul_f32_e32 v239, 0xbfb8aa3b, v237
	v_exp_f32_e32 v239, v239
	s_nop 0
	v_add_f32_e32 v239, 1.0, v239
	v_div_scale_f32 v240, s[0:1], v239, v239, v237
	v_rcp_f32_e32 v241, v240
	s_nop 0
	v_fma_f32 v242, -v240, v241, 1.0
	v_fmac_f32_e32 v241, v242, v241
	v_div_scale_f32 v242, vcc, v237, v239, v237
	v_mul_f32_e32 v243, v242, v241
	v_fma_f32 v244, -v240, v243, v242
	v_fmac_f32_e32 v243, v244, v241
	v_fma_f32 v240, -v240, v243, v242
	v_div_fmas_f32 v240, v240, v241, v243
	v_div_fixup_f32 v240, v240, v239, v237
	v_mul_f32_e32 v249, v238, v240
	v_fmac_f32_e32 v231, v249, v249
	v_cvt_pk_bf16_f32 v212, v246, v247
	v_cvt_pk_bf16_f32 v213, v248, v249
	s_waitcnt lgkmcnt(4)
	v_lshlrev_b32_e32 v236, 16, v142
	v_lshlrev_b32_e32 v237, 16, v150
	v_fma_f32 v238, s63, v236, v36
	v_mul_f32_e32 v239, 0xbfb8aa3b, v237
	v_exp_f32_e32 v239, v239
	s_nop 0
	v_add_f32_e32 v239, 1.0, v239
	v_div_scale_f32 v240, s[0:1], v239, v239, v237
	v_rcp_f32_e32 v241, v240
	s_nop 0
	v_fma_f32 v242, -v240, v241, 1.0
	v_fmac_f32_e32 v241, v242, v241
	v_div_scale_f32 v242, vcc, v237, v239, v237
	v_mul_f32_e32 v243, v242, v241
	v_fma_f32 v244, -v240, v243, v242
	v_fmac_f32_e32 v243, v244, v241
	v_fma_f32 v240, -v240, v243, v242
	v_div_fmas_f32 v240, v240, v241, v243
	v_div_fixup_f32 v240, v240, v239, v237
	v_mul_f32_e32 v246, v238, v240
	v_fmac_f32_e32 v228, v246, v246
	v_and_b32_e32 v236, 0xffff0000, v142
	v_and_b32_e32 v237, 0xffff0000, v150
	v_fma_f32 v238, s63, v236, v37
	v_mul_f32_e32 v239, 0xbfb8aa3b, v237
	v_exp_f32_e32 v239, v239
	s_nop 0
	v_add_f32_e32 v239, 1.0, v239
	v_div_scale_f32 v240, s[0:1], v239, v239, v237
	v_rcp_f32_e32 v241, v240
	s_nop 0
	v_fma_f32 v242, -v240, v241, 1.0
	v_fmac_f32_e32 v241, v242, v241
	v_div_scale_f32 v242, vcc, v237, v239, v237
	v_mul_f32_e32 v243, v242, v241
	v_fma_f32 v244, -v240, v243, v242
	v_fmac_f32_e32 v243, v244, v241
	v_fma_f32 v240, -v240, v243, v242
	v_div_fmas_f32 v240, v240, v241, v243
	v_div_fixup_f32 v240, v240, v239, v237
	v_mul_f32_e32 v247, v238, v240
	v_fmac_f32_e32 v229, v247, v247
	v_lshlrev_b32_e32 v236, 16, v143
	v_lshlrev_b32_e32 v237, 16, v151
	v_fma_f32 v238, s63, v236, v38
	v_mul_f32_e32 v239, 0xbfb8aa3b, v237
	v_exp_f32_e32 v239, v239
	s_nop 0
	v_add_f32_e32 v239, 1.0, v239
	v_div_scale_f32 v240, s[0:1], v239, v239, v237
	v_rcp_f32_e32 v241, v240
	s_nop 0
	v_fma_f32 v242, -v240, v241, 1.0
	v_fmac_f32_e32 v241, v242, v241
	v_div_scale_f32 v242, vcc, v237, v239, v237
	v_mul_f32_e32 v243, v242, v241
	v_fma_f32 v244, -v240, v243, v242
	v_fmac_f32_e32 v243, v244, v241
	v_fma_f32 v240, -v240, v243, v242
	v_div_fmas_f32 v240, v240, v241, v243
	v_div_fixup_f32 v240, v240, v239, v237
	v_mul_f32_e32 v248, v238, v240
	v_fmac_f32_e32 v230, v248, v248
	v_and_b32_e32 v236, 0xffff0000, v143
	v_and_b32_e32 v237, 0xffff0000, v151
	v_fma_f32 v238, s63, v236, v39
	v_mul_f32_e32 v239, 0xbfb8aa3b, v237
	v_exp_f32_e32 v239, v239
	s_nop 0
	v_add_f32_e32 v239, 1.0, v239
	v_div_scale_f32 v240, s[0:1], v239, v239, v237
	v_rcp_f32_e32 v241, v240
	s_nop 0
	v_fma_f32 v242, -v240, v241, 1.0
	v_fmac_f32_e32 v241, v242, v241
	v_div_scale_f32 v242, vcc, v237, v239, v237
	v_mul_f32_e32 v243, v242, v241
	v_fma_f32 v244, -v240, v243, v242
	v_fmac_f32_e32 v243, v244, v241
	v_fma_f32 v240, -v240, v243, v242
	v_div_fmas_f32 v240, v240, v241, v243
	v_div_fixup_f32 v240, v240, v239, v237
	v_mul_f32_e32 v249, v238, v240
	v_fmac_f32_e32 v231, v249, v249
	v_cvt_pk_bf16_f32 v214, v246, v247
	v_cvt_pk_bf16_f32 v215, v248, v249
	s_waitcnt lgkmcnt(2)
	v_lshlrev_b32_e32 v236, 16, v144
	v_lshlrev_b32_e32 v237, 16, v152
	v_fma_f32 v238, s63, v236, v40
	v_mul_f32_e32 v239, 0xbfb8aa3b, v237
	v_exp_f32_e32 v239, v239
	s_nop 0
	v_add_f32_e32 v239, 1.0, v239
	v_div_scale_f32 v240, s[0:1], v239, v239, v237
	v_rcp_f32_e32 v241, v240
	s_nop 0
	v_fma_f32 v242, -v240, v241, 1.0
	v_fmac_f32_e32 v241, v242, v241
	v_div_scale_f32 v242, vcc, v237, v239, v237
	v_mul_f32_e32 v243, v242, v241
	v_fma_f32 v244, -v240, v243, v242
	v_fmac_f32_e32 v243, v244, v241
	v_fma_f32 v240, -v240, v243, v242
	v_div_fmas_f32 v240, v240, v241, v243
	v_div_fixup_f32 v240, v240, v239, v237
	v_mul_f32_e32 v246, v238, v240
	v_fmac_f32_e32 v228, v246, v246
	v_and_b32_e32 v236, 0xffff0000, v144
	v_and_b32_e32 v237, 0xffff0000, v152
	v_fma_f32 v238, s63, v236, v41
	v_mul_f32_e32 v239, 0xbfb8aa3b, v237
	v_exp_f32_e32 v239, v239
	s_nop 0
	v_add_f32_e32 v239, 1.0, v239
	v_div_scale_f32 v240, s[0:1], v239, v239, v237
	v_rcp_f32_e32 v241, v240
	s_nop 0
	v_fma_f32 v242, -v240, v241, 1.0
	v_fmac_f32_e32 v241, v242, v241
	v_div_scale_f32 v242, vcc, v237, v239, v237
	v_mul_f32_e32 v243, v242, v241
	v_fma_f32 v244, -v240, v243, v242
	v_fmac_f32_e32 v243, v244, v241
	v_fma_f32 v240, -v240, v243, v242
	v_div_fmas_f32 v240, v240, v241, v243
	v_div_fixup_f32 v240, v240, v239, v237
	v_mul_f32_e32 v247, v238, v240
	v_fmac_f32_e32 v229, v247, v247
	v_lshlrev_b32_e32 v236, 16, v145
	v_lshlrev_b32_e32 v237, 16, v153
	v_fma_f32 v238, s63, v236, v42
	v_mul_f32_e32 v239, 0xbfb8aa3b, v237
	v_exp_f32_e32 v239, v239
	s_nop 0
	v_add_f32_e32 v239, 1.0, v239
	v_div_scale_f32 v240, s[0:1], v239, v239, v237
	v_rcp_f32_e32 v241, v240
	s_nop 0
	v_fma_f32 v242, -v240, v241, 1.0
	v_fmac_f32_e32 v241, v242, v241
	v_div_scale_f32 v242, vcc, v237, v239, v237
	v_mul_f32_e32 v243, v242, v241
	v_fma_f32 v244, -v240, v243, v242
	v_fmac_f32_e32 v243, v244, v241
	v_fma_f32 v240, -v240, v243, v242
	v_div_fmas_f32 v240, v240, v241, v243
	v_div_fixup_f32 v240, v240, v239, v237
	v_mul_f32_e32 v248, v238, v240
	v_fmac_f32_e32 v230, v248, v248
	v_and_b32_e32 v236, 0xffff0000, v145
	v_and_b32_e32 v237, 0xffff0000, v153
	v_fma_f32 v238, s63, v236, v43
	v_mul_f32_e32 v239, 0xbfb8aa3b, v237
	v_exp_f32_e32 v239, v239
	s_nop 0
	v_add_f32_e32 v239, 1.0, v239
	v_div_scale_f32 v240, s[0:1], v239, v239, v237
	v_rcp_f32_e32 v241, v240
	s_nop 0
	v_fma_f32 v242, -v240, v241, 1.0
	v_fmac_f32_e32 v241, v242, v241
	v_div_scale_f32 v242, vcc, v237, v239, v237
	v_mul_f32_e32 v243, v242, v241
	v_fma_f32 v244, -v240, v243, v242
	v_fmac_f32_e32 v243, v244, v241
	v_fma_f32 v240, -v240, v243, v242
	v_div_fmas_f32 v240, v240, v241, v243
	v_div_fixup_f32 v240, v240, v239, v237
	v_mul_f32_e32 v249, v238, v240
	v_fmac_f32_e32 v231, v249, v249
	v_cvt_pk_bf16_f32 v216, v246, v247
	v_cvt_pk_bf16_f32 v217, v248, v249
	s_waitcnt lgkmcnt(0)
	v_lshlrev_b32_e32 v236, 16, v146
	v_lshlrev_b32_e32 v237, 16, v154
	v_fma_f32 v238, s63, v236, v44
	v_mul_f32_e32 v239, 0xbfb8aa3b, v237
	v_exp_f32_e32 v239, v239
	s_nop 0
	v_add_f32_e32 v239, 1.0, v239
	v_div_scale_f32 v240, s[0:1], v239, v239, v237
	v_rcp_f32_e32 v241, v240
	s_nop 0
	v_fma_f32 v242, -v240, v241, 1.0
	v_fmac_f32_e32 v241, v242, v241
	v_div_scale_f32 v242, vcc, v237, v239, v237
	v_mul_f32_e32 v243, v242, v241
	v_fma_f32 v244, -v240, v243, v242
	v_fmac_f32_e32 v243, v244, v241
	v_fma_f32 v240, -v240, v243, v242
	v_div_fmas_f32 v240, v240, v241, v243
	v_div_fixup_f32 v240, v240, v239, v237
	v_mul_f32_e32 v246, v238, v240
	v_fmac_f32_e32 v228, v246, v246
	v_and_b32_e32 v236, 0xffff0000, v146
	v_and_b32_e32 v237, 0xffff0000, v154
	v_fma_f32 v238, s63, v236, v45
	v_mul_f32_e32 v239, 0xbfb8aa3b, v237
	v_exp_f32_e32 v239, v239
	s_nop 0
	v_add_f32_e32 v239, 1.0, v239
	v_div_scale_f32 v240, s[0:1], v239, v239, v237
	v_rcp_f32_e32 v241, v240
	s_nop 0
	v_fma_f32 v242, -v240, v241, 1.0
	v_fmac_f32_e32 v241, v242, v241
	v_div_scale_f32 v242, vcc, v237, v239, v237
	v_mul_f32_e32 v243, v242, v241
	v_fma_f32 v244, -v240, v243, v242
	v_fmac_f32_e32 v243, v244, v241
	v_fma_f32 v240, -v240, v243, v242
	v_div_fmas_f32 v240, v240, v241, v243
	v_div_fixup_f32 v240, v240, v239, v237
	v_mul_f32_e32 v247, v238, v240
	v_fmac_f32_e32 v229, v247, v247
	v_lshlrev_b32_e32 v236, 16, v147
	v_lshlrev_b32_e32 v237, 16, v155
	v_fma_f32 v238, s63, v236, v46
	v_mul_f32_e32 v239, 0xbfb8aa3b, v237
	v_exp_f32_e32 v239, v239
	s_nop 0
	v_add_f32_e32 v239, 1.0, v239
	v_div_scale_f32 v240, s[0:1], v239, v239, v237
	v_rcp_f32_e32 v241, v240
	s_nop 0
	v_fma_f32 v242, -v240, v241, 1.0
	v_fmac_f32_e32 v241, v242, v241
	v_div_scale_f32 v242, vcc, v237, v239, v237
	v_mul_f32_e32 v243, v242, v241
	v_fma_f32 v244, -v240, v243, v242
	v_fmac_f32_e32 v243, v244, v241
	v_fma_f32 v240, -v240, v243, v242
	v_div_fmas_f32 v240, v240, v241, v243
	v_div_fixup_f32 v240, v240, v239, v237
	v_mul_f32_e32 v248, v238, v240
	v_fmac_f32_e32 v230, v248, v248
	v_and_b32_e32 v236, 0xffff0000, v147
	v_and_b32_e32 v237, 0xffff0000, v155
	v_fma_f32 v238, s63, v236, v47
	v_mul_f32_e32 v239, 0xbfb8aa3b, v237
	v_exp_f32_e32 v239, v239
	s_nop 0
	v_add_f32_e32 v239, 1.0, v239
	v_div_scale_f32 v240, s[0:1], v239, v239, v237
	v_rcp_f32_e32 v241, v240
	s_nop 0
	v_fma_f32 v242, -v240, v241, 1.0
	v_fmac_f32_e32 v241, v242, v241
	v_div_scale_f32 v242, vcc, v237, v239, v237
	v_mul_f32_e32 v243, v242, v241
	v_fma_f32 v244, -v240, v243, v242
	v_fmac_f32_e32 v243, v244, v241
	v_fma_f32 v240, -v240, v243, v242
	v_div_fmas_f32 v240, v240, v241, v243
	v_div_fixup_f32 v240, v240, v239, v237
	v_mul_f32_e32 v249, v238, v240
	v_fmac_f32_e32 v231, v249, v249
	v_cvt_pk_bf16_f32 v224, v246, v247
	v_cvt_pk_bf16_f32 v225, v248, v249
	s_nop 1
	v_add_f32_dpp v228, v228, v228 quad_perm:[1,0,3,2] row_mask:0xf bank_mask:0xf
	v_add_f32_dpp v229, v229, v229 quad_perm:[1,0,3,2] row_mask:0xf bank_mask:0xf
	v_add_f32_dpp v230, v230, v230 quad_perm:[1,0,3,2] row_mask:0xf bank_mask:0xf
	v_add_f32_dpp v231, v231, v231 quad_perm:[1,0,3,2] row_mask:0xf bank_mask:0xf
	s_nop 1
	v_add_f32_dpp v228, v228, v228 quad_perm:[2,3,0,1] row_mask:0xf bank_mask:0xf
	v_add_f32_dpp v229, v229, v229 quad_perm:[2,3,0,1] row_mask:0xf bank_mask:0xf
	v_add_f32_dpp v230, v230, v230 quad_perm:[2,3,0,1] row_mask:0xf bank_mask:0xf
	v_add_f32_dpp v231, v231, v231 quad_perm:[2,3,0,1] row_mask:0xf bank_mask:0xf
	s_nop 1
	v_add_f32_dpp v228, v228, v228 row_half_mirror row_mask:0xf bank_mask:0xf
	v_add_f32_dpp v229, v229, v229 row_half_mirror row_mask:0xf bank_mask:0xf
	v_add_f32_dpp v230, v230, v230 row_half_mirror row_mask:0xf bank_mask:0xf
	v_add_f32_dpp v231, v231, v231 row_half_mirror row_mask:0xf bank_mask:0xf
	s_nop 1
	v_add_f32_dpp v228, v228, v228 row_mirror row_mask:0xf bank_mask:0xf
	v_add_f32_dpp v229, v229, v229 row_mirror row_mask:0xf bank_mask:0xf
	v_add_f32_dpp v230, v230, v230 row_mirror row_mask:0xf bank_mask:0xf
	v_add_f32_dpp v231, v231, v231 row_mirror row_mask:0xf bank_mask:0xf
	v_fma_f32 v228, v228, s25, v218
	v_fma_f32 v229, v229, s25, v218
	v_fma_f32 v230, v230, s25, v218
	v_fma_f32 v231, v231, s25, v218
	v_rsq_f32_e32 v228, v228
	v_rsq_f32_e32 v229, v229
	v_rsq_f32_e32 v230, v230
	v_rsq_f32_e32 v231, v231
	s_waitcnt vmcnt(0)
	v_lshlrev_b32_e32 v236, 16, v178
	v_mul_f32_e32 v236, v228, v236
	v_mul_f32_e32 v236, v64, v236
	v_cvt_pk_bf16_f32 v237, v236, v236
	ds_write_b16 v171, v237 offset:0
	v_and_b32_e32 v236, 0xffff0000, v178
	v_mul_f32_e32 v236, v229, v236
	v_mul_f32_e32 v236, v64, v236
	v_cvt_pk_bf16_f32 v238, v236, v236
	ds_write_b16 v171, v238 offset:288
	v_lshlrev_b32_e32 v236, 16, v179
	v_mul_f32_e32 v236, v230, v236
	v_mul_f32_e32 v236, v64, v236
	v_cvt_pk_bf16_f32 v239, v236, v236
	ds_write_b16 v171, v239 offset:576
	v_and_b32_e32 v236, 0xffff0000, v179
	v_mul_f32_e32 v236, v231, v236
	v_mul_f32_e32 v236, v64, v236
	v_cvt_pk_bf16_f32 v240, v236, v236
	ds_write_b16 v171, v240 offset:864
	v_lshlrev_b32_e32 v236, 16, v180
	v_mul_f32_e32 v236, v228, v236
	v_mul_f32_e32 v236, v65, v236
	v_cvt_pk_bf16_f32 v237, v236, v236
	ds_write_b16 v171, v237 offset:32
	v_and_b32_e32 v236, 0xffff0000, v180
	v_mul_f32_e32 v236, v229, v236
	v_mul_f32_e32 v236, v65, v236
	v_cvt_pk_bf16_f32 v238, v236, v236
	ds_write_b16 v171, v238 offset:320
	v_lshlrev_b32_e32 v236, 16, v181
	v_mul_f32_e32 v236, v230, v236
	v_mul_f32_e32 v236, v65, v236
	v_cvt_pk_bf16_f32 v239, v236, v236
	ds_write_b16 v171, v239 offset:608
	v_and_b32_e32 v236, 0xffff0000, v181
	v_mul_f32_e32 v236, v231, v236
	v_mul_f32_e32 v236, v65, v236
	v_cvt_pk_bf16_f32 v240, v236, v236
	ds_write_b16 v171, v240 offset:896
	v_lshlrev_b32_e32 v236, 16, v182
	v_mul_f32_e32 v236, v228, v236
	v_mul_f32_e32 v236, v66, v236
	v_cvt_pk_bf16_f32 v237, v236, v236
	ds_write_b16 v171, v237 offset:64
	v_and_b32_e32 v236, 0xffff0000, v182
	v_mul_f32_e32 v236, v229, v236
	v_mul_f32_e32 v236, v66, v236
	v_cvt_pk_bf16_f32 v238, v236, v236
	ds_write_b16 v171, v238 offset:352
	v_lshlrev_b32_e32 v236, 16, v183
	v_mul_f32_e32 v236, v230, v236
	v_mul_f32_e32 v236, v66, v236
	v_cvt_pk_bf16_f32 v239, v236, v236
	ds_write_b16 v171, v239 offset:640
	v_and_b32_e32 v236, 0xffff0000, v183
	v_mul_f32_e32 v236, v231, v236
	v_mul_f32_e32 v236, v66, v236
	v_cvt_pk_bf16_f32 v240, v236, v236
	ds_write_b16 v171, v240 offset:928
	v_lshlrev_b32_e32 v236, 16, v184
	v_mul_f32_e32 v236, v228, v236
	v_mul_f32_e32 v236, v67, v236
	v_cvt_pk_bf16_f32 v237, v236, v236
	ds_write_b16 v171, v237 offset:96
	v_and_b32_e32 v236, 0xffff0000, v184
	v_mul_f32_e32 v236, v229, v236
	v_mul_f32_e32 v236, v67, v236
	v_cvt_pk_bf16_f32 v238, v236, v236
	ds_write_b16 v171, v238 offset:384
	v_lshlrev_b32_e32 v236, 16, v185
	v_mul_f32_e32 v236, v230, v236
	v_mul_f32_e32 v236, v67, v236
	v_cvt_pk_bf16_f32 v239, v236, v236
	ds_write_b16 v171, v239 offset:672
	v_and_b32_e32 v236, 0xffff0000, v185
	v_mul_f32_e32 v236, v231, v236
	v_mul_f32_e32 v236, v67, v236
	v_cvt_pk_bf16_f32 v240, v236, v236
	ds_write_b16 v171, v240 offset:960
	v_lshlrev_b32_e32 v236, 16, v186
	v_mul_f32_e32 v236, v228, v236
	v_mul_f32_e32 v236, v68, v236
	v_cvt_pk_bf16_f32 v237, v236, v236
	ds_write_b16 v171, v237 offset:128
	v_and_b32_e32 v236, 0xffff0000, v186
	v_mul_f32_e32 v236, v229, v236
	v_mul_f32_e32 v236, v68, v236
	v_cvt_pk_bf16_f32 v238, v236, v236
	ds_write_b16 v171, v238 offset:416
	v_lshlrev_b32_e32 v236, 16, v187
	v_mul_f32_e32 v236, v230, v236
	v_mul_f32_e32 v236, v68, v236
	v_cvt_pk_bf16_f32 v239, v236, v236
	ds_write_b16 v171, v239 offset:704
	v_and_b32_e32 v236, 0xffff0000, v187
	v_mul_f32_e32 v236, v231, v236
	v_mul_f32_e32 v236, v68, v236
	v_cvt_pk_bf16_f32 v240, v236, v236
	ds_write_b16 v171, v240 offset:992
	v_lshlrev_b32_e32 v236, 16, v188
	v_mul_f32_e32 v236, v228, v236
	v_mul_f32_e32 v236, v69, v236
	v_cvt_pk_bf16_f32 v237, v236, v236
	ds_write_b16 v171, v237 offset:160
	v_and_b32_e32 v236, 0xffff0000, v188
	v_mul_f32_e32 v236, v229, v236
	v_mul_f32_e32 v236, v69, v236
	v_cvt_pk_bf16_f32 v238, v236, v236
	ds_write_b16 v171, v238 offset:448
	v_lshlrev_b32_e32 v236, 16, v189
	v_mul_f32_e32 v236, v230, v236
	v_mul_f32_e32 v236, v69, v236
	v_cvt_pk_bf16_f32 v239, v236, v236
	ds_write_b16 v171, v239 offset:736
	v_and_b32_e32 v236, 0xffff0000, v189
	v_mul_f32_e32 v236, v231, v236
	v_mul_f32_e32 v236, v69, v236
	v_cvt_pk_bf16_f32 v240, v236, v236
	ds_write_b16 v171, v240 offset:1024
	v_lshlrev_b32_e32 v236, 16, v190
	v_mul_f32_e32 v236, v228, v236
	v_mul_f32_e32 v236, v70, v236
	v_cvt_pk_bf16_f32 v237, v236, v236
	ds_write_b16 v171, v237 offset:192
	v_and_b32_e32 v236, 0xffff0000, v190
	v_mul_f32_e32 v236, v229, v236
	v_mul_f32_e32 v236, v70, v236
	v_cvt_pk_bf16_f32 v238, v236, v236
	ds_write_b16 v171, v238 offset:480
	v_lshlrev_b32_e32 v236, 16, v191
	v_mul_f32_e32 v236, v230, v236
	v_mul_f32_e32 v236, v70, v236
	v_cvt_pk_bf16_f32 v239, v236, v236
	ds_write_b16 v171, v239 offset:768
	v_and_b32_e32 v236, 0xffff0000, v191
	v_mul_f32_e32 v236, v231, v236
	v_mul_f32_e32 v236, v70, v236
	v_cvt_pk_bf16_f32 v240, v236, v236
	ds_write_b16 v171, v240 offset:1056
	v_lshlrev_b32_e32 v236, 16, v192
	v_mul_f32_e32 v236, v228, v236
	v_mul_f32_e32 v236, v71, v236
	v_cvt_pk_bf16_f32 v237, v236, v236
	ds_write_b16 v171, v237 offset:224
	v_and_b32_e32 v236, 0xffff0000, v192
	v_mul_f32_e32 v236, v229, v236
	v_mul_f32_e32 v236, v71, v236
	v_cvt_pk_bf16_f32 v238, v236, v236
	ds_write_b16 v171, v238 offset:512
	v_lshlrev_b32_e32 v236, 16, v193
	v_mul_f32_e32 v236, v230, v236
	v_mul_f32_e32 v236, v71, v236
	v_cvt_pk_bf16_f32 v239, v236, v236
	ds_write_b16 v171, v239 offset:800
	v_and_b32_e32 v236, 0xffff0000, v193
	v_mul_f32_e32 v236, v231, v236
	v_mul_f32_e32 v236, v71, v236
	v_cvt_pk_bf16_f32 v240, v236, v236
	ds_write_b16 v171, v240 offset:1088
	ds_read_b128 v[80:83], v172 offset:0
	ds_read_b128 v[84:87], v172 offset:1152
	ds_read_b128 v[88:91], v172 offset:2304
	ds_read_b128 v[92:95], v172 offset:3456
	s_mov_b32 s52, s46
	s_mov_b32 s53, s47
	s_waitcnt lgkmcnt(3)
	global_store_dwordx4 v173, v[80:83], s[52:53] offset:0
	s_add_u32 s52, s46, 0x2000
	s_addc_u32 s53, s47, 0
	s_waitcnt lgkmcnt(2)
	global_store_dwordx4 v173, v[84:87], s[52:53] offset:0
	s_add_u32 s52, s46, 0x4000
	s_addc_u32 s53, s47, 0
	s_waitcnt lgkmcnt(1)
	global_store_dwordx4 v173, v[88:91], s[52:53] offset:0
	s_add_u32 s52, s46, 0x6000
	s_addc_u32 s53, s47, 0
	s_waitcnt lgkmcnt(0)
	global_store_dwordx4 v173, v[92:95], s[52:53] offset:0
	v_lshlrev_b32_e32 v236, 16, v204
	v_mul_f32_e32 v236, v228, v236
	v_mul_f32_e32 v236, v72, v236
	v_cvt_pk_bf16_f32 v237, v236, v236
	ds_write_b16 v171, v237 offset:0
	v_and_b32_e32 v236, 0xffff0000, v204
	v_mul_f32_e32 v236, v229, v236
	v_mul_f32_e32 v236, v72, v236
	v_cvt_pk_bf16_f32 v238, v236, v236
	ds_write_b16 v171, v238 offset:288
	v_lshlrev_b32_e32 v236, 16, v205
	v_mul_f32_e32 v236, v230, v236
	v_mul_f32_e32 v236, v72, v236
	v_cvt_pk_bf16_f32 v239, v236, v236
	ds_write_b16 v171, v239 offset:576
	v_and_b32_e32 v236, 0xffff0000, v205
	v_mul_f32_e32 v236, v231, v236
	v_mul_f32_e32 v236, v72, v236
	v_cvt_pk_bf16_f32 v240, v236, v236
	ds_write_b16 v171, v240 offset:864
	v_lshlrev_b32_e32 v236, 16, v206
	v_mul_f32_e32 v236, v228, v236
	v_mul_f32_e32 v236, v73, v236
	v_cvt_pk_bf16_f32 v237, v236, v236
	ds_write_b16 v171, v237 offset:32
	v_and_b32_e32 v236, 0xffff0000, v206
	v_mul_f32_e32 v236, v229, v236
	v_mul_f32_e32 v236, v73, v236
	v_cvt_pk_bf16_f32 v238, v236, v236
	ds_write_b16 v171, v238 offset:320
	v_lshlrev_b32_e32 v236, 16, v207
	v_mul_f32_e32 v236, v230, v236
	v_mul_f32_e32 v236, v73, v236
	v_cvt_pk_bf16_f32 v239, v236, v236
	ds_write_b16 v171, v239 offset:608
	v_and_b32_e32 v236, 0xffff0000, v207
	v_mul_f32_e32 v236, v231, v236
	v_mul_f32_e32 v236, v73, v236
	v_cvt_pk_bf16_f32 v240, v236, v236
	ds_write_b16 v171, v240 offset:896
	v_lshlrev_b32_e32 v236, 16, v208
	v_mul_f32_e32 v236, v228, v236
	v_mul_f32_e32 v236, v74, v236
	v_cvt_pk_bf16_f32 v237, v236, v236
	ds_write_b16 v171, v237 offset:64
	v_and_b32_e32 v236, 0xffff0000, v208
	v_mul_f32_e32 v236, v229, v236
	v_mul_f32_e32 v236, v74, v236
	v_cvt_pk_bf16_f32 v238, v236, v236
	ds_write_b16 v171, v238 offset:352
	v_lshlrev_b32_e32 v236, 16, v209
	v_mul_f32_e32 v236, v230, v236
	v_mul_f32_e32 v236, v74, v236
	v_cvt_pk_bf16_f32 v239, v236, v236
	ds_write_b16 v171, v239 offset:640
	v_and_b32_e32 v236, 0xffff0000, v209
	v_mul_f32_e32 v236, v231, v236
	v_mul_f32_e32 v236, v74, v236
	v_cvt_pk_bf16_f32 v240, v236, v236
	ds_write_b16 v171, v240 offset:928
	v_lshlrev_b32_e32 v236, 16, v210
	v_mul_f32_e32 v236, v228, v236
	v_mul_f32_e32 v236, v75, v236
	v_cvt_pk_bf16_f32 v237, v236, v236
	ds_write_b16 v171, v237 offset:96
	v_and_b32_e32 v236, 0xffff0000, v210
	v_mul_f32_e32 v236, v229, v236
	v_mul_f32_e32 v236, v75, v236
	v_cvt_pk_bf16_f32 v238, v236, v236
	ds_write_b16 v171, v238 offset:384
	v_lshlrev_b32_e32 v236, 16, v211
	v_mul_f32_e32 v236, v230, v236
	v_mul_f32_e32 v236, v75, v236
	v_cvt_pk_bf16_f32 v239, v236, v236
	ds_write_b16 v171, v239 offset:672
	v_and_b32_e32 v236, 0xffff0000, v211
	v_mul_f32_e32 v236, v231, v236
	v_mul_f32_e32 v236, v75, v236
	v_cvt_pk_bf16_f32 v240, v236, v236
	ds_write_b16 v171, v240 offset:960
	v_lshlrev_b32_e32 v236, 16, v212
	v_mul_f32_e32 v236, v228, v236
	v_mul_f32_e32 v236, v76, v236
	v_cvt_pk_bf16_f32 v237, v236, v236
	ds_write_b16 v171, v237 offset:128
	v_and_b32_e32 v236, 0xffff0000, v212
	v_mul_f32_e32 v236, v229, v236
	v_mul_f32_e32 v236, v76, v236
	v_cvt_pk_bf16_f32 v238, v236, v236
	ds_write_b16 v171, v238 offset:416
	v_lshlrev_b32_e32 v236, 16, v213
	v_mul_f32_e32 v236, v230, v236
	v_mul_f32_e32 v236, v76, v236
	v_cvt_pk_bf16_f32 v239, v236, v236
	ds_write_b16 v171, v239 offset:704
	v_and_b32_e32 v236, 0xffff0000, v213
	v_mul_f32_e32 v236, v231, v236
	v_mul_f32_e32 v236, v76, v236
	v_cvt_pk_bf16_f32 v240, v236, v236
	ds_write_b16 v171, v240 offset:992
	v_lshlrev_b32_e32 v236, 16, v214
	v_mul_f32_e32 v236, v228, v236
	v_mul_f32_e32 v236, v77, v236
	v_cvt_pk_bf16_f32 v237, v236, v236
	ds_write_b16 v171, v237 offset:160
	v_and_b32_e32 v236, 0xffff0000, v214
	v_mul_f32_e32 v236, v229, v236
	v_mul_f32_e32 v236, v77, v236
	v_cvt_pk_bf16_f32 v238, v236, v236
	ds_write_b16 v171, v238 offset:448
	v_lshlrev_b32_e32 v236, 16, v215
	v_mul_f32_e32 v236, v230, v236
	v_mul_f32_e32 v236, v77, v236
	v_cvt_pk_bf16_f32 v239, v236, v236
	ds_write_b16 v171, v239 offset:736
	v_and_b32_e32 v236, 0xffff0000, v215
	v_mul_f32_e32 v236, v231, v236
	v_mul_f32_e32 v236, v77, v236
	v_cvt_pk_bf16_f32 v240, v236, v236
	ds_write_b16 v171, v240 offset:1024
	v_lshlrev_b32_e32 v236, 16, v216
	v_mul_f32_e32 v236, v228, v236
	v_mul_f32_e32 v236, v78, v236
	v_cvt_pk_bf16_f32 v237, v236, v236
	ds_write_b16 v171, v237 offset:192
	v_and_b32_e32 v236, 0xffff0000, v216
	v_mul_f32_e32 v236, v229, v236
	v_mul_f32_e32 v236, v78, v236
	v_cvt_pk_bf16_f32 v238, v236, v236
	ds_write_b16 v171, v238 offset:480
	v_lshlrev_b32_e32 v236, 16, v217
	v_mul_f32_e32 v236, v230, v236
	v_mul_f32_e32 v236, v78, v236
	v_cvt_pk_bf16_f32 v239, v236, v236
	ds_write_b16 v171, v239 offset:768
	v_and_b32_e32 v236, 0xffff0000, v217
	v_mul_f32_e32 v236, v231, v236
	v_mul_f32_e32 v236, v78, v236
	v_cvt_pk_bf16_f32 v240, v236, v236
	ds_write_b16 v171, v240 offset:1056
	v_lshlrev_b32_e32 v236, 16, v224
	v_mul_f32_e32 v236, v228, v236
	v_mul_f32_e32 v236, v79, v236
	v_cvt_pk_bf16_f32 v237, v236, v236
	ds_write_b16 v171, v237 offset:224
	v_and_b32_e32 v236, 0xffff0000, v224
	v_mul_f32_e32 v236, v229, v236
	v_mul_f32_e32 v236, v79, v236
	v_cvt_pk_bf16_f32 v238, v236, v236
	ds_write_b16 v171, v238 offset:512
	v_lshlrev_b32_e32 v236, 16, v225
	v_mul_f32_e32 v236, v230, v236
	v_mul_f32_e32 v236, v79, v236
	v_cvt_pk_bf16_f32 v239, v236, v236
	ds_write_b16 v171, v239 offset:800
	v_and_b32_e32 v236, 0xffff0000, v225
	v_mul_f32_e32 v236, v231, v236
	v_mul_f32_e32 v236, v79, v236
	v_cvt_pk_bf16_f32 v240, v236, v236
	ds_write_b16 v171, v240 offset:1088
	ds_read_b128 v[80:83], v172 offset:0
	ds_read_b128 v[84:87], v172 offset:1152
	ds_read_b128 v[88:91], v172 offset:2304
	ds_read_b128 v[92:95], v172 offset:3456
	s_mov_b32 s52, s46
	s_mov_b32 s53, s47
	s_waitcnt lgkmcnt(3)
	global_store_dwordx4 v173, v[80:83], s[52:53] offset:256
	s_add_u32 s52, s46, 0x2000
	s_addc_u32 s53, s47, 0
	s_waitcnt lgkmcnt(2)
	global_store_dwordx4 v173, v[84:87], s[52:53] offset:256
	s_add_u32 s52, s46, 0x4000
	s_addc_u32 s53, s47, 0
	s_waitcnt lgkmcnt(1)
	global_store_dwordx4 v173, v[88:91], s[52:53] offset:256
	s_add_u32 s52, s46, 0x6000
	s_addc_u32 s53, s47, 0
	s_waitcnt lgkmcnt(0)
	global_store_dwordx4 v173, v[92:95], s[52:53] offset:256
	s_waitcnt vmcnt(0) lgkmcnt(0)
	s_barrier
	s_branch .LBB0_106

.LBB0_211:
	s_or_b64 exec, exec, s[0:1]
	v_readlane_b32 s3, v255, 11
	s_nop 0
	s_cmp_eq_u32 s3, 0x88
	s_cbranch_scc0 .Lrm_done
	s_cmp_lt_u32 s2, 0x400
	s_cbranch_scc0 .Lrm_ctx
	s_lshr_b32 s3, s2, 7
	s_mul_i32 s3, s3, 0x88
	s_and_b32 s2, s2, 0x7f
	s_add_i32 s2, s2, s3
	s_branch .Lrm_done
.Lrm_ctx:
	s_sub_i32 s2, s2, 0x400
	s_lshr_b32 s3, s2, 3
	s_mul_i32 s3, s3, 0x88
	s_and_b32 s2, s2, 7
	s_add_i32 s2, s2, s3
	s_addk_i32 s2, 0x80
.Lrm_done:
	s_abs_i32 s1, s2
	v_readlane_b32 s3, v255, 12
	s_mul_hi_u32 s3, s1, s3
	v_readlane_b32 s6, v255, 11
	s_mul_i32 s4, s3, s6
	s_sub_i32 s1, s1, s4
	s_ashr_i32 s0, s2, 31
	s_add_i32 s4, s3, 1
	s_sub_i32 s5, s1, s6
	s_cmp_ge_u32 s1, s6
	s_cselect_b32 s3, s4, s3
	s_cselect_b32 s1, s5, s1
	s_add_i32 s4, s3, 1
	s_cmp_ge_u32 s1, s6
	s_cselect_b32 s1, s4, s3
	s_xor_b32 s1, s1, s0
	s_sub_i32 s7, s1, s0
	s_mul_i32 s0, s7, s6
	v_mov_b32_e32 v0, v203
	s_sub_i32 s24, s2, s0
	s_and_b32 s19, s24, 1
	v_readfirstlane_b32 s4, v0
	s_ashr_i32 s18, s4, 6
	s_and_b32 s0, s18, 3
	s_lshl_b32 s1, s19, 2
	v_and_b32_e32 v1, 63, v0
	s_or_b32 s5, s0, s1
	s_mul_i32 s0, s18, 0x1200
	s_ashr_i32 s25, s4, 8
	s_add_i32 s6, s0, 0
	v_and_b32_e32 v165, 15, v0
	v_lshlrev_b32_e32 v0, 4, v1
	v_lshrrev_b32_e32 v152, 3, v1
	s_mov_b64 s[0:1], -1
	s_cmpk_gt_i32 s24, 0x7f
	v_lshrrev_b32_e32 v166, 4, v1
	v_and_b32_e32 v130, 48, v1
	v_and_b32_e32 v8, 0x70, v0
	v_mul_u32_u24_e32 v151, 0x90, v152
	v_mul_u32_u24_e32 v150, 0x90, v165
	v_lshlrev_b32_e32 v132, 6, v165
	s_cbranch_scc0 .LBB0_229
	s_and_b32 s0, s24, 0x7fffffe
	s_add_i32 s0, s0, s25
	s_lshl_b32 s0, s0, 5
	s_lshl_b32 s1, s7, 8
	s_add_i32 s2, s0, s1
	s_addk_i32 s2, 0x7000
	v_or_b32_e32 v6, s2, v152
	v_mov_b64_e32 v[4:5], s[70:71]
	v_mad_i64_i32 v[0:1], s[0:1], v6, s77, v[4:5]
	s_lshl_b32 s26, s5, 7
	v_lshl_add_u64 v[0:1], v[0:1], 0, s[26:27]
	v_lshl_add_u64 v[0:1], v[0:1], 0, v[8:9]
	global_load_dwordx4 v[0:3], v[0:1], off offset:2048
	v_add3_u32 v7, s6, v8, v151
	s_lshl_b32 s3, s5, 6
	v_mov_b32_e32 v133, v9
	v_mov_b32_e32 v131, v9
	v_mov_b32_e32 v56, v9
	v_mov_b32_e32 v57, v9
	v_mov_b32_e32 v195, v194
	v_mov_b32_e32 v54, v9
	v_mov_b32_e32 v55, v9
	v_mov_b64_e32 v[72:73], v[56:57]
	v_mov_b64_e32 v[76:77], v[56:57]
	v_mov_b64_e32 v[80:81], v[56:57]
	v_mov_b64_e32 v[100:101], v[56:57]
	v_mov_b64_e32 v[104:105], v[56:57]
	v_mov_b64_e32 v[108:109], v[56:57]
	v_mov_b64_e32 v[112:113], v[56:57]
	v_mov_b32_e32 v140, 0
	v_mov_b64_e32 v[70:71], v[54:55]
	v_mov_b64_e32 v[74:75], v[54:55]
	v_mov_b64_e32 v[78:79], v[54:55]
	v_mov_b64_e32 v[98:99], v[54:55]
	v_mov_b64_e32 v[102:103], v[54:55]
	v_mov_b64_e32 v[106:107], v[54:55]
	v_mov_b64_e32 v[110:111], v[54:55]
	v_mov_b64_e32 v[142:143], v[194:195]
	v_mov_b32_e32 v82, 0
	s_waitcnt vmcnt(0)
	ds_write_b128 v7, v[0:3] offset:34816
	v_or_b32_e32 v0, 8, v6
	v_mad_i64_i32 v[0:1], s[0:1], v0, s77, v[4:5]
	v_lshl_add_u64 v[0:1], v[0:1], 0, s[26:27]
	v_lshl_add_u64 v[0:1], v[0:1], 0, v[8:9]
	global_load_dwordx4 v[0:3], v[0:1], off offset:2048
	s_waitcnt vmcnt(0)
	ds_write_b128 v7, v[0:3] offset:35968
	v_or_b32_e32 v0, 16, v6
	v_mad_i64_i32 v[0:1], s[0:1], v0, s77, v[4:5]
	v_lshl_add_u64 v[0:1], v[0:1], 0, s[26:27]
	v_lshl_add_u64 v[0:1], v[0:1], 0, v[8:9]
	global_load_dwordx4 v[0:3], v[0:1], off offset:2048
	s_waitcnt vmcnt(0)
	ds_write_b128 v7, v[0:3] offset:37120
	v_or_b32_e32 v0, 24, v6
	v_mad_i64_i32 v[0:1], s[0:1], v0, s77, v[4:5]
	v_lshl_add_u64 v[0:1], v[0:1], 0, s[26:27]
	v_lshl_add_u64 v[0:1], v[0:1], 0, v[8:9]
	global_load_dwordx4 v[0:3], v[0:1], off offset:2048
	s_lshl_b32 s0, s7, 3
	s_or_b32 s0, s5, s0
	s_ashr_i32 s1, s0, 31
	s_lshl_b64 s[0:1], s[0:1], 15
	s_add_u32 s28, s69, s0
	s_addc_u32 s29, s72, s1
	s_add_u32 s0, s73, s0
	s_addc_u32 s1, s74, s1
	v_add3_u32 v4, s6, v150, v130
	v_add_u32_e32 v153, 0x8800, v4
	s_waitcnt vmcnt(0)
	ds_write_b128 v7, v[0:3] offset:38272
	v_lshl_add_u64 v[2:3], s[0:1], 0, v[132:133]
	v_lshl_add_u64 v[0:1], s[28:29], 0, v[132:133]
	v_lshl_add_u64 v[136:137], v[2:3], 0, v[130:131]
	v_lshl_add_u64 v[138:139], v[0:1], 0, v[130:131]
	global_load_dwordx4 v[62:65], v[136:137], off
	global_load_dwordx4 v[58:61], v[136:137], off offset:1024
	global_load_dwordx4 v[66:69], v[136:137], off offset:2048
	global_load_dwordx4 v[50:53], v[136:137], off offset:3072
	global_load_dwordx4 v[42:45], v[138:139], off
	global_load_dwordx4 v[46:49], v[138:139], off offset:1024
	global_load_dwordx4 v[38:41], v[138:139], off offset:2048
	global_load_dwordx4 v[34:37], v[138:139], off offset:3072
	v_add_u32_e32 v131, 0x9100, v4
	s_movk_i32 s28, 0x1000
	v_mov_b64_e32 v[144:145], v[138:139]
	v_mov_b64_e32 v[146:147], v[136:137]
	s_branch .LBB0_216
